# adds: first 3 LDS reads of the next load segment issued between the two tail MFMAs after the early barrier (MFMA-LDS interleave)
# speedup vs baseline: 1.0014x; 1.0013x over previous
; #define PG8_STAGE(bufoff, gbase, voff) do { _Pragma("unroll") for (int _i = 0; _i < 2; ++_i) \
;         __builtin_amdgcn_global_load_lds((const unsigned*)((const char*)(gbase) + (voff)[_i]), (LAS unsigned*)(lds + (bufoff) + ldsw + _i * 8192), 16, 0, 0); } while (0)
; #define PG8_LDA(dst, b, h) do { _Pragma("unroll") for (int m = 0; m < 4; ++m) _Pragma("unroll") for (int k = 0; k < 2; ++k) dst[m][k] = *(const LAS bf16x8*)(lds + PG8_SA(b, h) + aoff + m * 2048 + k * 1024); } while (0)
; #define PG8_LDB(dst, b, h) do { _Pragma("unroll") for (int n = 0; n < 2; ++n) _Pragma("unroll") for (int k = 0; k < 2; ++k) dst[n][k] = *(const LAS bf16x8*)(lds + PG8_SB(b, h) + boff + n * 2048 + k * 1024); } while (0)
; #define PG8_MMA(ai, bj, At, Bt) do { __builtin_amdgcn_s_setprio(1); _Pragma("unroll") for (int m = 0; m < 4; ++m) _Pragma("unroll") for (int n = 0; n < 2; ++n) _Pragma("unroll") for (int k = 0; k < 2; ++k) \
;         acc[ai][bj][m][n] = __builtin_amdgcn_mfma_f32_16x16x32_bf16(Bt[n][k], At[m][k], acc[ai][bj][m][n], 0, 0, 0); __builtin_amdgcn_s_setprio(0); } while (0)
; #define PG8_WAIT_V(n) asm volatile("s_waitcnt vmcnt(" #n ")" ::: "memory")
; #define PG8_WAIT_L(n) asm volatile("s_waitcnt lgkmcnt(" #n ")" ::: "memory")
; #define PG8_BAR __builtin_amdgcn_s_barrier()
; #define PG8_SCHED __builtin_amdgcn_sched_barrier(0)
; template <class Epi>
; __device__ __forceinline__ void gemm_phase(LAS unsigned char* lds, const Gemm g, const TileOrder& S, const Epi& E) {
;     ...
;         for (int t = 0; t < nt; t += 2) {
;             const bool last = (t == nt - 2);
;             const char* a1 = cA + (size_t)(t + 1) * kstepA;
;             const char* a2 = last ? nA : cA + (size_t)(t + 2) * kstepA; const char* b2 = last ? nB : cB + (size_t)(t + 2) * kstep;
;             const char* a3 = a2 + kstepA; const char* b3 = b2 + kstep;
;             PG8_LDB(B0, 0, 0); PG8_LDB(B1, 0, 1); PG8_SCHED; PG8_LDA(At, 0, 0); PG8_STAGE(PG8_SA(1, 1), a1 + hstepA, voffA);
;             PG8_WAIT_V(8); PG8_WAIT_L(0); PG8_BAR; PG8_MMA(0, 0, At, B0); PG8_MMA(0, 1, At, B1); PG8_BAR; PG8_SCHED;
;             PG8_LDA(At, 0, 1); PG8_STAGE(PG8_SB(0, 0), b2, voffB); PG8_STAGE(PG8_SB(0, 1), b2 + hstepB, voffB); PG8_STAGE(PG8_SA(0, 0), a2, voffA);
;             PG8_WAIT_V(8); PG8_WAIT_L(0); PG8_BAR; PG8_MMA(1, 0, At, B0); PG8_MMA(1, 1, At, B1); PG8_BAR; PG8_SCHED;
.LBB0_51:
	s_mov_b32 s6, 0x10000
	v_add_u32_e32 v0, s6, v186
	s_mov_b32 s12, 0x14000
	ds_read_b128 v[130:133], v0
	ds_read_b128 v[134:137], v0 offset:1024
	ds_read_b128 v[138:141], v0 offset:2048
	ds_read_b128 v[142:145], v0 offset:3072
	v_add_u32_e32 v0, s12, v186
	ds_read_b128 v[154:157], v0
	ds_read_b128 v[158:161], v0 offset:1024
	ds_read_b128 v[162:165], v0 offset:2048
	ds_read_b128 v[166:169], v0 offset:3072
	ds_read_b128 v[170:173], v187
	ds_read_b128 v[174:177], v187 offset:1024
	ds_read_b128 v[178:181], v187 offset:2048
	ds_read_b128 v[188:191], v187 offset:3072
	ds_read_b128 v[192:195], v187 offset:4096
	ds_read_b128 v[196:199], v187 offset:5120
	ds_read_b128 v[200:203], v187 offset:6144
	ds_read_b128 v[204:207], v187 offset:7168
	s_add_u32 s2, s28, 0xfff80080
	s_addc_u32 s3, s29, -1
	s_cmp_eq_u32 s72, 28
	s_cselect_b32 s31, s49, s3
	s_cselect_b32 s30, s68, s2
	s_cselect_b32 s3, s47, s71
	s_cselect_b32 s2, s69, s70
	s_waitcnt lgkmcnt(0)
	s_add_i32 m0, s56, 0xc000
	s_nop 0
	global_load_lds_dwordx4 v150, s[28:29]
	s_add_i32 m0, s56, 0xe000
	s_nop 0
	global_load_lds_dwordx4 v152, s[28:29]
	s_waitcnt vmcnt(8)
	s_waitcnt lgkmcnt(0)
	s_barrier
	s_setprio 1
	s_waitcnt lgkmcnt(0)
	v_mfma_f32_16x16x32_bf16 v[126:129], v[130:133], v[170:173], v[126:129]
	v_mfma_f32_16x16x32_bf16 v[118:121], v[138:141], v[170:173], v[118:121]
	v_mfma_f32_16x16x32_bf16 v[110:113], v[130:133], v[178:181], v[110:113]
	v_mfma_f32_16x16x32_bf16 v[102:105], v[138:141], v[178:181], v[102:105]
	v_mfma_f32_16x16x32_bf16 v[94:97], v[130:133], v[192:195], v[94:97]
	v_mfma_f32_16x16x32_bf16 v[86:89], v[138:141], v[192:195], v[86:89]
	v_mfma_f32_16x16x32_bf16 v[78:81], v[130:133], v[200:203], v[78:81]
	v_mfma_f32_16x16x32_bf16 v[70:73], v[138:141], v[200:203], v[70:73]
	v_mfma_f32_16x16x32_bf16 v[126:129], v[134:137], v[174:177], v[126:129]
	v_mfma_f32_16x16x32_bf16 v[118:121], v[142:145], v[174:177], v[118:121]
	v_mfma_f32_16x16x32_bf16 v[110:113], v[134:137], v[188:191], v[110:113]
	v_mfma_f32_16x16x32_bf16 v[102:105], v[142:145], v[188:191], v[102:105]
	v_mfma_f32_16x16x32_bf16 v[94:97], v[134:137], v[196:199], v[94:97]
	v_mfma_f32_16x16x32_bf16 v[86:89], v[142:145], v[196:199], v[86:89]
	v_mfma_f32_16x16x32_bf16 v[78:81], v[134:137], v[204:207], v[78:81]
	v_mfma_f32_16x16x32_bf16 v[70:73], v[142:145], v[204:207], v[70:73]
	s_setprio 0
	s_setprio 1
	v_mfma_f32_16x16x32_bf16 v[122:125], v[154:157], v[170:173], v[122:125]
	v_mfma_f32_16x16x32_bf16 v[114:117], v[162:165], v[170:173], v[114:117]
	v_mfma_f32_16x16x32_bf16 v[106:109], v[154:157], v[178:181], v[106:109]
	v_mfma_f32_16x16x32_bf16 v[98:101], v[162:165], v[178:181], v[98:101]
	v_mfma_f32_16x16x32_bf16 v[90:93], v[154:157], v[192:195], v[90:93]
	v_mfma_f32_16x16x32_bf16 v[82:85], v[162:165], v[192:195], v[82:85]
	v_mfma_f32_16x16x32_bf16 v[74:77], v[154:157], v[200:203], v[74:77]
	v_mfma_f32_16x16x32_bf16 v[66:69], v[162:165], v[200:203], v[66:69]
	v_mfma_f32_16x16x32_bf16 v[122:125], v[158:161], v[174:177], v[122:125]
	v_mfma_f32_16x16x32_bf16 v[114:117], v[166:169], v[174:177], v[114:117]
	v_mfma_f32_16x16x32_bf16 v[106:109], v[158:161], v[188:191], v[106:109]
	v_mfma_f32_16x16x32_bf16 v[98:101], v[166:169], v[188:191], v[98:101]
	v_mfma_f32_16x16x32_bf16 v[90:93], v[158:161], v[196:199], v[90:93]
	v_mfma_f32_16x16x32_bf16 v[82:85], v[166:169], v[196:199], v[82:85]
	s_setprio 2
	s_barrier
	v_mfma_f32_16x16x32_bf16 v[74:77], v[158:161], v[204:207], v[74:77]
	ds_read_b128 v[170:173], v187 offset:16384
	ds_read_b128 v[174:177], v187 offset:17408
	ds_read_b128 v[178:181], v187 offset:18432
	v_mfma_f32_16x16x32_bf16 v[66:69], v[166:169], v[204:207], v[66:69]
	s_setprio 0
	s_add_i32 s6, s6, s55
	v_lshl_add_u64 v[182:183], s[2:3], 0, v[148:149]
	s_mov_b32 m0, s6
	ds_read_b128 v[188:191], v187 offset:19456
	ds_read_b128 v[192:195], v187 offset:20480
	ds_read_b128 v[196:199], v187 offset:21504
	ds_read_b128 v[200:203], v187 offset:22528
	ds_read_b128 v[204:207], v187 offset:23552
	global_load_lds_dwordx4 v[182:183], off
	s_add_i32 m0, s6, 0x2000
	s_add_u32 s14, s2, 0x80000
	v_lshl_add_u64 v[208:209], s[2:3], 0, v[146:147]
	s_addc_u32 s15, s3, 0
	s_add_i32 s6, s12, s55
	global_load_lds_dwordx4 v[208:209], off
	s_mov_b32 m0, s6
	v_lshl_add_u64 v[212:213], s[30:31], 0, v[146:147]
	global_load_lds_dwordx4 v148, s[14:15]
	s_add_i32 m0, s6, 0x2000
	s_nop 0
	global_load_lds_dwordx4 v146, s[14:15]
	v_lshl_add_u64 v[210:211], s[30:31], 0, v[148:149]
	s_mov_b32 m0, s56
	s_nop 0
	global_load_lds_dwordx4 v[210:211], off
	s_mov_b32 m0, s57
	s_nop 0
	global_load_lds_dwordx4 v[212:213], off
	s_waitcnt vmcnt(8)
	s_waitcnt lgkmcnt(0)
	s_barrier
; #define PG8_STAGE(bufoff, gbase, voff) do { _Pragma("unroll") for (int _i = 0; _i < 2; ++_i) \
;         __builtin_amdgcn_global_load_lds((const unsigned*)((const char*)(gbase) + (voff)[_i]), (LAS unsigned*)(lds + (bufoff) + ldsw + _i * 8192), 16, 0, 0); } while (0)
; #define PG8_LDA(dst, b, h) do { _Pragma("unroll") for (int m = 0; m < 4; ++m) _Pragma("unroll") for (int k = 0; k < 2; ++k) dst[m][k] = *(const LAS bf16x8*)(lds + PG8_SA(b, h) + aoff + m * 2048 + k * 1024); } while (0)
; #define PG8_LDB(dst, b, h) do { _Pragma("unroll") for (int n = 0; n < 2; ++n) _Pragma("unroll") for (int k = 0; k < 2; ++k) dst[n][k] = *(const LAS bf16x8*)(lds + PG8_SB(b, h) + boff + n * 2048 + k * 1024); } while (0)
; #define PG8_MMA(ai, bj, At, Bt) do { __builtin_amdgcn_s_setprio(1); _Pragma("unroll") for (int m = 0; m < 4; ++m) _Pragma("unroll") for (int n = 0; n < 2; ++n) _Pragma("unroll") for (int k = 0; k < 2; ++k) \
;         acc[ai][bj][m][n] = __builtin_amdgcn_mfma_f32_16x16x32_bf16(Bt[n][k], At[m][k], acc[ai][bj][m][n], 0, 0, 0); __builtin_amdgcn_s_setprio(0); } while (0)
; #define PG8_WAIT_V(n) asm volatile("s_waitcnt vmcnt(" #n ")" ::: "memory")
; #define PG8_WAIT_L(n) asm volatile("s_waitcnt lgkmcnt(" #n ")" ::: "memory")
; #define PG8_BAR __builtin_amdgcn_s_barrier()
; #define PG8_SCHED __builtin_amdgcn_sched_barrier(0)
; template <class Epi>
; __device__ __forceinline__ void gemm_phase(LAS unsigned char* lds, const Gemm g, const TileOrder& S, const Epi& E) {
;     ...
;             PG8_WAIT_V(8); PG8_WAIT_L(0); PG8_BAR; PG8_MMA(1, 0, At, B0); PG8_MMA(1, 1, At, B1); PG8_BAR; PG8_SCHED;
;             PG8_LDB(B0, 1, 0); PG8_LDB(B1, 1, 1); PG8_SCHED; PG8_LDA(At, 1, 0); PG8_STAGE(PG8_SA(0, 1), a2 + hstepA, voffA);
;             PG8_WAIT_V(8); PG8_WAIT_L(0); PG8_BAR; PG8_MMA(0, 0, At, B0); PG8_MMA(0, 1, At, B1); PG8_BAR; PG8_SCHED;
	s_setprio 1
	s_waitcnt lgkmcnt(0)
	v_mfma_f32_16x16x32_bf16 v[62:65], v[130:133], v[170:173], v[62:65]
	v_mfma_f32_16x16x32_bf16 v[54:57], v[138:141], v[170:173], v[54:57]
	v_mfma_f32_16x16x32_bf16 v[46:49], v[130:133], v[178:181], v[46:49]
	v_mfma_f32_16x16x32_bf16 v[38:41], v[138:141], v[178:181], v[38:41]
	v_mfma_f32_16x16x32_bf16 v[30:33], v[130:133], v[192:195], v[30:33]
	v_mfma_f32_16x16x32_bf16 v[22:25], v[138:141], v[192:195], v[22:25]
	v_mfma_f32_16x16x32_bf16 v[14:17], v[130:133], v[200:203], v[14:17]
	v_mfma_f32_16x16x32_bf16 v[6:9], v[138:141], v[200:203], v[6:9]
	v_mfma_f32_16x16x32_bf16 v[62:65], v[134:137], v[174:177], v[62:65]
	v_mfma_f32_16x16x32_bf16 v[54:57], v[142:145], v[174:177], v[54:57]
	v_mfma_f32_16x16x32_bf16 v[46:49], v[134:137], v[188:191], v[46:49]
	v_mfma_f32_16x16x32_bf16 v[38:41], v[142:145], v[188:191], v[38:41]
	v_mfma_f32_16x16x32_bf16 v[30:33], v[134:137], v[196:199], v[30:33]
	v_mfma_f32_16x16x32_bf16 v[22:25], v[142:145], v[196:199], v[22:25]
	v_mfma_f32_16x16x32_bf16 v[14:17], v[134:137], v[204:207], v[14:17]
	v_mfma_f32_16x16x32_bf16 v[6:9], v[142:145], v[204:207], v[6:9]
	s_setprio 0
	s_setprio 1
	v_mfma_f32_16x16x32_bf16 v[58:61], v[154:157], v[170:173], v[58:61]
	v_mfma_f32_16x16x32_bf16 v[50:53], v[162:165], v[170:173], v[50:53]
	v_mfma_f32_16x16x32_bf16 v[42:45], v[154:157], v[178:181], v[42:45]
	v_mfma_f32_16x16x32_bf16 v[34:37], v[162:165], v[178:181], v[34:37]
	v_mfma_f32_16x16x32_bf16 v[26:29], v[154:157], v[192:195], v[26:29]
	v_mfma_f32_16x16x32_bf16 v[18:21], v[162:165], v[192:195], v[18:21]
	v_mfma_f32_16x16x32_bf16 v[10:13], v[154:157], v[200:203], v[10:13]
	v_mfma_f32_16x16x32_bf16 v[2:5], v[162:165], v[200:203], v[2:5]
	v_mfma_f32_16x16x32_bf16 v[58:61], v[158:161], v[174:177], v[58:61]
	v_mfma_f32_16x16x32_bf16 v[50:53], v[166:169], v[174:177], v[50:53]
	v_mfma_f32_16x16x32_bf16 v[42:45], v[158:161], v[188:191], v[42:45]
	v_mfma_f32_16x16x32_bf16 v[34:37], v[166:169], v[188:191], v[34:37]
	v_mfma_f32_16x16x32_bf16 v[26:29], v[158:161], v[196:199], v[26:29]
	v_mfma_f32_16x16x32_bf16 v[18:21], v[166:169], v[196:199], v[18:21]
	s_setprio 2
	s_barrier
	v_mfma_f32_16x16x32_bf16 v[10:13], v[158:161], v[204:207], v[10:13]
	s_mov_b32 s6, 0x18000
	v_add_u32_e32 v0, s6, v186
	s_mov_b32 s12, 0x1c000
	ds_read_b128 v[130:133], v0
	ds_read_b128 v[134:137], v0 offset:1024
	ds_read_b128 v[138:141], v0 offset:2048
	v_mfma_f32_16x16x32_bf16 v[2:5], v[166:169], v[204:207], v[2:5]
	s_setprio 0
	ds_read_b128 v[142:145], v0 offset:3072
	v_add_u32_e32 v0, s12, v186
	ds_read_b128 v[154:157], v0
	ds_read_b128 v[158:161], v0 offset:1024
	ds_read_b128 v[162:165], v0 offset:2048
	ds_read_b128 v[166:169], v0 offset:3072
	s_add_u32 s14, s30, 0x80000
	s_addc_u32 s15, s31, 0
	s_mov_b32 m0, s58
	ds_read_b128 v[170:173], v187 offset:32768
	ds_read_b128 v[174:177], v187 offset:33792
	ds_read_b128 v[178:181], v187 offset:34816
	ds_read_b128 v[188:191], v187 offset:35840
	ds_read_b128 v[192:195], v187 offset:36864
	ds_read_b128 v[196:199], v187 offset:37888
	ds_read_b128 v[200:203], v187 offset:38912
	ds_read_b128 v[204:207], v187 offset:39936
	global_load_lds_dwordx4 v148, s[14:15]
	s_mov_b32 m0, s59
	s_nop 0
	global_load_lds_dwordx4 v146, s[14:15]
	s_waitcnt vmcnt(8)
	s_waitcnt lgkmcnt(0)
	s_barrier
	s_setprio 1
	s_waitcnt lgkmcnt(0)
	v_mfma_f32_16x16x32_bf16 v[126:129], v[130:133], v[170:173], v[126:129]
	v_mfma_f32_16x16x32_bf16 v[118:121], v[138:141], v[170:173], v[118:121]
	v_mfma_f32_16x16x32_bf16 v[110:113], v[130:133], v[178:181], v[110:113]
	v_mfma_f32_16x16x32_bf16 v[102:105], v[138:141], v[178:181], v[102:105]
	v_mfma_f32_16x16x32_bf16 v[94:97], v[130:133], v[192:195], v[94:97]
	v_mfma_f32_16x16x32_bf16 v[86:89], v[138:141], v[192:195], v[86:89]
	v_mfma_f32_16x16x32_bf16 v[78:81], v[130:133], v[200:203], v[78:81]
	v_mfma_f32_16x16x32_bf16 v[70:73], v[138:141], v[200:203], v[70:73]
	v_mfma_f32_16x16x32_bf16 v[126:129], v[134:137], v[174:177], v[126:129]
	v_mfma_f32_16x16x32_bf16 v[118:121], v[142:145], v[174:177], v[118:121]
	v_mfma_f32_16x16x32_bf16 v[110:113], v[134:137], v[188:191], v[110:113]
	v_mfma_f32_16x16x32_bf16 v[102:105], v[142:145], v[188:191], v[102:105]
	v_mfma_f32_16x16x32_bf16 v[94:97], v[134:137], v[196:199], v[94:97]
	v_mfma_f32_16x16x32_bf16 v[86:89], v[142:145], v[196:199], v[86:89]
	v_mfma_f32_16x16x32_bf16 v[78:81], v[134:137], v[204:207], v[78:81]
	v_mfma_f32_16x16x32_bf16 v[70:73], v[142:145], v[204:207], v[70:73]
	s_setprio 0
	s_setprio 1
	v_mfma_f32_16x16x32_bf16 v[122:125], v[154:157], v[170:173], v[122:125]
	v_mfma_f32_16x16x32_bf16 v[114:117], v[162:165], v[170:173], v[114:117]
	v_mfma_f32_16x16x32_bf16 v[106:109], v[154:157], v[178:181], v[106:109]
	v_mfma_f32_16x16x32_bf16 v[98:101], v[162:165], v[178:181], v[98:101]
	v_mfma_f32_16x16x32_bf16 v[90:93], v[154:157], v[192:195], v[90:93]
	v_mfma_f32_16x16x32_bf16 v[82:85], v[162:165], v[192:195], v[82:85]
	v_mfma_f32_16x16x32_bf16 v[74:77], v[154:157], v[200:203], v[74:77]
	v_mfma_f32_16x16x32_bf16 v[66:69], v[162:165], v[200:203], v[66:69]
	v_mfma_f32_16x16x32_bf16 v[122:125], v[158:161], v[174:177], v[122:125]
	v_mfma_f32_16x16x32_bf16 v[114:117], v[166:169], v[174:177], v[114:117]
	v_mfma_f32_16x16x32_bf16 v[106:109], v[158:161], v[188:191], v[106:109]
	v_mfma_f32_16x16x32_bf16 v[98:101], v[166:169], v[188:191], v[98:101]
	v_mfma_f32_16x16x32_bf16 v[90:93], v[158:161], v[196:199], v[90:93]
	v_mfma_f32_16x16x32_bf16 v[82:85], v[166:169], v[196:199], v[82:85]
	s_setprio 2
	s_barrier
; #define PG8_STAGE(bufoff, gbase, voff) do { _Pragma("unroll") for (int _i = 0; _i < 2; ++_i) \
;         __builtin_amdgcn_global_load_lds((const unsigned*)((const char*)(gbase) + (voff)[_i]), (LAS unsigned*)(lds + (bufoff) + ldsw + _i * 8192), 16, 0, 0); } while (0)
; #define PG8_LDA(dst, b, h) do { _Pragma("unroll") for (int m = 0; m < 4; ++m) _Pragma("unroll") for (int k = 0; k < 2; ++k) dst[m][k] = *(const LAS bf16x8*)(lds + PG8_SA(b, h) + aoff + m * 2048 + k * 1024); } while (0)
; #define PG8_MMA(ai, bj, At, Bt) do { __builtin_amdgcn_s_setprio(1); _Pragma("unroll") for (int m = 0; m < 4; ++m) _Pragma("unroll") for (int n = 0; n < 2; ++n) _Pragma("unroll") for (int k = 0; k < 2; ++k) \
;         acc[ai][bj][m][n] = __builtin_amdgcn_mfma_f32_16x16x32_bf16(Bt[n][k], At[m][k], acc[ai][bj][m][n], 0, 0, 0); __builtin_amdgcn_s_setprio(0); } while (0)
; #define PG8_WAIT_V(n) asm volatile("s_waitcnt vmcnt(" #n ")" ::: "memory")
; #define PG8_WAIT_L(n) asm volatile("s_waitcnt lgkmcnt(" #n ")" ::: "memory")
; #define PG8_BAR __builtin_amdgcn_s_barrier()
; #define PG8_SCHED __builtin_amdgcn_sched_barrier(0)
; template <class Epi>
; __device__ __forceinline__ void gemm_phase(LAS unsigned char* lds, const Gemm g, const TileOrder& S, const Epi& E) {
;     ...
;             PG8_WAIT_V(8); PG8_WAIT_L(0); PG8_BAR; PG8_MMA(0, 0, At, B0); PG8_MMA(0, 1, At, B1); PG8_BAR; PG8_SCHED;
;             PG8_LDA(At, 1, 1); PG8_STAGE(PG8_SB(1, 0), b3, voffB); PG8_STAGE(PG8_SB(1, 1), b3 + hstepB, voffB); PG8_STAGE(PG8_SA(1, 0), a3, voffA);
;             PG8_WAIT_V(8); PG8_WAIT_L(0); PG8_BAR; PG8_MMA(1, 0, At, B0); PG8_MMA(1, 1, At, B1); PG8_BAR; PG8_SCHED;
;         }
;         if (wr == 0) PG8_BAR;
	v_mfma_f32_16x16x32_bf16 v[74:77], v[158:161], v[204:207], v[74:77]
	ds_read_b128 v[170:173], v187 offset:49152
	ds_read_b128 v[174:177], v187 offset:50176
	ds_read_b128 v[178:181], v187 offset:51200
	v_mfma_f32_16x16x32_bf16 v[66:69], v[166:169], v[204:207], v[66:69]
	s_setprio 0
	s_add_i32 s6, s6, s55
	v_lshl_add_u64 v[182:183], v[182:183], 0, s[34:35]
	s_mov_b32 m0, s6
	ds_read_b128 v[188:191], v187 offset:52224
	ds_read_b128 v[192:195], v187 offset:53248
	ds_read_b128 v[196:199], v187 offset:54272
	ds_read_b128 v[200:203], v187 offset:55296
	ds_read_b128 v[204:207], v187 offset:56320
	global_load_lds_dwordx4 v[182:183], off
	s_add_i32 m0, s6, 0x2000
	s_add_u32 s2, s2, 0x80080
	v_lshl_add_u64 v[182:183], v[208:209], 0, s[34:35]
	s_addc_u32 s3, s3, 0
	s_add_i32 s6, s12, s55
	global_load_lds_dwordx4 v[182:183], off
	s_mov_b32 m0, s6
	s_nop 0
	global_load_lds_dwordx4 v148, s[2:3]
	v_lshl_add_u64 v[182:183], s[2:3], 0, v[146:147]
	s_add_i32 m0, s6, 0x2000
	s_nop 0
	global_load_lds_dwordx4 v[182:183], off
	v_lshl_add_u64 v[182:183], v[210:211], 0, s[34:35]
	s_mov_b32 m0, s61
	s_nop 0
	global_load_lds_dwordx4 v[182:183], off
	v_lshl_add_u64 v[182:183], v[212:213], 0, s[34:35]
	s_mov_b32 m0, s62
	s_nop 0
	global_load_lds_dwordx4 v[182:183], off
	s_waitcnt vmcnt(8)
	s_waitcnt lgkmcnt(0)
	s_barrier
	s_setprio 1
	s_waitcnt lgkmcnt(0)
	v_mfma_f32_16x16x32_bf16 v[62:65], v[130:133], v[170:173], v[62:65]
	v_mfma_f32_16x16x32_bf16 v[54:57], v[138:141], v[170:173], v[54:57]
	v_mfma_f32_16x16x32_bf16 v[46:49], v[130:133], v[178:181], v[46:49]
	v_mfma_f32_16x16x32_bf16 v[38:41], v[138:141], v[178:181], v[38:41]
	v_mfma_f32_16x16x32_bf16 v[30:33], v[130:133], v[192:195], v[30:33]
	v_mfma_f32_16x16x32_bf16 v[22:25], v[138:141], v[192:195], v[22:25]
	v_mfma_f32_16x16x32_bf16 v[14:17], v[130:133], v[200:203], v[14:17]
	v_mfma_f32_16x16x32_bf16 v[6:9], v[138:141], v[200:203], v[6:9]
	v_mfma_f32_16x16x32_bf16 v[62:65], v[134:137], v[174:177], v[62:65]
	v_mfma_f32_16x16x32_bf16 v[54:57], v[142:145], v[174:177], v[54:57]
	v_mfma_f32_16x16x32_bf16 v[46:49], v[134:137], v[188:191], v[46:49]
	v_mfma_f32_16x16x32_bf16 v[38:41], v[142:145], v[188:191], v[38:41]
	v_mfma_f32_16x16x32_bf16 v[30:33], v[134:137], v[196:199], v[30:33]
	v_mfma_f32_16x16x32_bf16 v[22:25], v[142:145], v[196:199], v[22:25]
	v_mfma_f32_16x16x32_bf16 v[14:17], v[134:137], v[204:207], v[14:17]
	v_mfma_f32_16x16x32_bf16 v[6:9], v[142:145], v[204:207], v[6:9]
	s_setprio 0
	s_setprio 1
	v_mfma_f32_16x16x32_bf16 v[58:61], v[154:157], v[170:173], v[58:61]
	v_mfma_f32_16x16x32_bf16 v[50:53], v[162:165], v[170:173], v[50:53]
	v_mfma_f32_16x16x32_bf16 v[42:45], v[154:157], v[178:181], v[42:45]
	v_mfma_f32_16x16x32_bf16 v[34:37], v[162:165], v[178:181], v[34:37]
	v_mfma_f32_16x16x32_bf16 v[26:29], v[154:157], v[192:195], v[26:29]
	v_mfma_f32_16x16x32_bf16 v[18:21], v[162:165], v[192:195], v[18:21]
	v_mfma_f32_16x16x32_bf16 v[10:13], v[154:157], v[200:203], v[10:13]
	v_mfma_f32_16x16x32_bf16 v[2:5], v[162:165], v[200:203], v[2:5]
	v_mfma_f32_16x16x32_bf16 v[58:61], v[158:161], v[174:177], v[58:61]
	v_mfma_f32_16x16x32_bf16 v[50:53], v[166:169], v[174:177], v[50:53]
	v_mfma_f32_16x16x32_bf16 v[42:45], v[158:161], v[188:191], v[42:45]
	v_mfma_f32_16x16x32_bf16 v[34:37], v[166:169], v[188:191], v[34:37]
	v_mfma_f32_16x16x32_bf16 v[26:29], v[158:161], v[196:199], v[26:29]
	v_mfma_f32_16x16x32_bf16 v[18:21], v[166:169], v[196:199], v[18:21]
	s_setprio 2
	s_barrier
	v_mfma_f32_16x16x32_bf16 v[10:13], v[158:161], v[204:207], v[10:13]
	v_mfma_f32_16x16x32_bf16 v[2:5], v[166:169], v[204:207], v[2:5]
	s_setprio 0
	s_add_i32 s72, s72, 2
	s_add_u32 s28, s28, 0x100
	s_addc_u32 s29, s29, 0
	s_add_u32 s70, s70, 0x100
	s_addc_u32 s71, s71, 0
	s_cmp_gt_u32 s72, 29
	s_cbranch_scc0 .LBB0_51
	s_and_b64 vcc, exec, s[44:45]
	s_cbranch_vccz .LBB0_54
	s_barrier

; #define PG8_STAGE(bufoff, gbase, voff) do { _Pragma("unroll") for (int _i = 0; _i < 2; ++_i) \
;         __builtin_amdgcn_global_load_lds((const unsigned*)((const char*)(gbase) + (voff)[_i]), (LAS unsigned*)(lds + (bufoff) + ldsw + _i * 8192), 16, 0, 0); } while (0)
; #define PG8_LDA(dst, b, h) do { _Pragma("unroll") for (int m = 0; m < 4; ++m) _Pragma("unroll") for (int k = 0; k < 2; ++k) dst[m][k] = *(const LAS bf16x8*)(lds + PG8_SA(b, h) + aoff + m * 2048 + k * 1024); } while (0)
; #define PG8_LDB(dst, b, h) do { _Pragma("unroll") for (int n = 0; n < 2; ++n) _Pragma("unroll") for (int k = 0; k < 2; ++k) dst[n][k] = *(const LAS bf16x8*)(lds + PG8_SB(b, h) + boff + n * 2048 + k * 1024); } while (0)
; #define PG8_MMA(ai, bj, At, Bt) do { __builtin_amdgcn_s_setprio(1); _Pragma("unroll") for (int m = 0; m < 4; ++m) _Pragma("unroll") for (int n = 0; n < 2; ++n) _Pragma("unroll") for (int k = 0; k < 2; ++k) \
;         acc[ai][bj][m][n] = __builtin_amdgcn_mfma_f32_16x16x32_bf16(Bt[n][k], At[m][k], acc[ai][bj][m][n], 0, 0, 0); __builtin_amdgcn_s_setprio(0); } while (0)
; #define PG8_WAIT_V(n) asm volatile("s_waitcnt vmcnt(" #n ")" ::: "memory")
; #define PG8_WAIT_L(n) asm volatile("s_waitcnt lgkmcnt(" #n ")" ::: "memory")
; #define PG8_BAR __builtin_amdgcn_s_barrier()
; #define PG8_SCHED __builtin_amdgcn_sched_barrier(0)
; template <class Epi>
; __device__ __forceinline__ void gemm_phase(LAS unsigned char* lds, const Gemm g, const TileOrder& S, const Epi& E) {
;     ...
;         for (int t = 0; t < nt; t += 2) {
;             const bool last = (t == nt - 2);
;             const char* a1 = cA + (size_t)(t + 1) * kstepA;
;             const char* a2 = last ? nA : cA + (size_t)(t + 2) * kstepA; const char* b2 = last ? nB : cB + (size_t)(t + 2) * kstep;
;             const char* a3 = a2 + kstepA; const char* b3 = b2 + kstep;
;             PG8_LDB(B0, 0, 0); PG8_LDB(B1, 0, 1); PG8_SCHED; PG8_LDA(At, 0, 0); PG8_STAGE(PG8_SA(1, 1), a1 + hstepA, voffA);
;             PG8_WAIT_V(8); PG8_WAIT_L(0); PG8_BAR; PG8_MMA(0, 0, At, B0); PG8_MMA(0, 1, At, B1); PG8_BAR; PG8_SCHED;
;             PG8_LDA(At, 0, 1); PG8_STAGE(PG8_SB(0, 0), b2, voffB); PG8_STAGE(PG8_SB(0, 1), b2 + hstepB, voffB); PG8_STAGE(PG8_SA(0, 0), a2, voffA);
;             PG8_WAIT_V(8); PG8_WAIT_L(0); PG8_BAR; PG8_MMA(1, 0, At, B0); PG8_MMA(1, 1, At, B1); PG8_BAR; PG8_SCHED;
.LBB0_255:
	s_mov_b32 s6, 0x10000
	s_mov_b32 s14, 0x14000
	v_add_u32_e32 v134, s6, v238
	v_add_u32_e32 v158, s14, v238
	ds_read_b128 v[118:121], v134
	ds_read_b128 v[126:129], v134 offset:1024
	ds_read_b128 v[130:133], v134 offset:2048
	ds_read_b128 v[134:137], v134 offset:3072
	ds_read_b128 v[138:141], v158
	ds_read_b128 v[142:145], v158 offset:1024
	ds_read_b128 v[154:157], v158 offset:2048
	ds_read_b128 v[158:161], v158 offset:3072
	ds_read_b128 v[162:165], v239
	ds_read_b128 v[166:169], v239 offset:1024
	ds_read_b128 v[170:173], v239 offset:2048
	ds_read_b128 v[174:177], v239 offset:3072
	ds_read_b128 v[178:181], v239 offset:4096
	ds_read_b128 v[182:185], v239 offset:5120
	ds_read_b128 v[186:189], v239 offset:6144
	ds_read_b128 v[200:203], v239 offset:7168
	s_add_u32 s2, s28, 0x4000
	s_addc_u32 s3, s29, 0
	s_cmp_eq_u32 s68, 28
	s_cselect_b32 s48, s64, s2
	s_cselect_b32 s49, s43, s3
	s_cselect_b32 s30, s65, s66
	s_cselect_b32 s31, s39, s67
	s_add_u32 s2, s48, 0x8000
	s_addc_u32 s3, s49, 0
	s_add_i32 m0, s52, 0xc000
	s_nop 0
	global_load_lds_dwordx4 v196, s[28:29]
	s_add_i32 m0, s52, 0xe000
	s_nop 0
	global_load_lds_dwordx4 v198, s[28:29]
	s_waitcnt vmcnt(8)
	s_waitcnt lgkmcnt(0)
	s_barrier
	s_setprio 1
	s_waitcnt lgkmcnt(0)
	v_mfma_f32_16x16x32_bf16 v[150:153], v[118:121], v[162:165], v[150:153]
	v_mfma_f32_16x16x32_bf16 v[146:149], v[130:133], v[162:165], v[146:149]
	v_mfma_f32_16x16x32_bf16 v[110:113], v[118:121], v[170:173], v[110:113]
	v_mfma_f32_16x16x32_bf16 v[106:109], v[130:133], v[170:173], v[106:109]
	v_mfma_f32_16x16x32_bf16 v[94:97], v[118:121], v[178:181], v[94:97]
	v_mfma_f32_16x16x32_bf16 v[90:93], v[130:133], v[178:181], v[90:93]
	v_mfma_f32_16x16x32_bf16 v[78:81], v[118:121], v[186:189], v[78:81]
	v_mfma_f32_16x16x32_bf16 v[74:77], v[130:133], v[186:189], v[74:77]
	v_mfma_f32_16x16x32_bf16 v[150:153], v[126:129], v[166:169], v[150:153]
	v_mfma_f32_16x16x32_bf16 v[146:149], v[134:137], v[166:169], v[146:149]
	v_mfma_f32_16x16x32_bf16 v[110:113], v[126:129], v[174:177], v[110:113]
	v_mfma_f32_16x16x32_bf16 v[106:109], v[134:137], v[174:177], v[106:109]
	v_mfma_f32_16x16x32_bf16 v[94:97], v[126:129], v[182:185], v[94:97]
	v_mfma_f32_16x16x32_bf16 v[90:93], v[134:137], v[182:185], v[90:93]
	v_mfma_f32_16x16x32_bf16 v[78:81], v[126:129], v[200:203], v[78:81]
	v_mfma_f32_16x16x32_bf16 v[74:77], v[134:137], v[200:203], v[74:77]
	s_setprio 0
	s_setprio 1
	v_mfma_f32_16x16x32_bf16 v[122:125], v[138:141], v[162:165], v[122:125]
	v_mfma_f32_16x16x32_bf16 v[114:117], v[154:157], v[162:165], v[114:117]
	v_mfma_f32_16x16x32_bf16 v[102:105], v[138:141], v[170:173], v[102:105]
	v_mfma_f32_16x16x32_bf16 v[98:101], v[154:157], v[170:173], v[98:101]
	v_mfma_f32_16x16x32_bf16 v[86:89], v[138:141], v[178:181], v[86:89]
	v_mfma_f32_16x16x32_bf16 v[82:85], v[154:157], v[178:181], v[82:85]
	v_mfma_f32_16x16x32_bf16 v[70:73], v[138:141], v[186:189], v[70:73]
	v_mfma_f32_16x16x32_bf16 v[66:69], v[154:157], v[186:189], v[66:69]
	v_mfma_f32_16x16x32_bf16 v[122:125], v[142:145], v[166:169], v[122:125]
	v_mfma_f32_16x16x32_bf16 v[114:117], v[158:161], v[166:169], v[114:117]
	v_mfma_f32_16x16x32_bf16 v[102:105], v[142:145], v[174:177], v[102:105]
	v_mfma_f32_16x16x32_bf16 v[98:101], v[158:161], v[174:177], v[98:101]
	v_mfma_f32_16x16x32_bf16 v[86:89], v[142:145], v[182:185], v[86:89]
	v_mfma_f32_16x16x32_bf16 v[82:85], v[158:161], v[182:185], v[82:85]
	s_setprio 2
	s_barrier
	v_mfma_f32_16x16x32_bf16 v[70:73], v[142:145], v[200:203], v[70:73]
	ds_read_b128 v[162:165], v239 offset:16384
	ds_read_b128 v[166:169], v239 offset:17408
	ds_read_b128 v[170:173], v239 offset:18432
	v_mfma_f32_16x16x32_bf16 v[66:69], v[158:161], v[200:203], v[66:69]
	s_setprio 0
	s_add_i32 s6, s6, s51
	v_lshl_add_u64 v[204:205], s[30:31], 0, v[0:1]
	s_mov_b32 m0, s6
	ds_read_b128 v[174:177], v239 offset:19456
	ds_read_b128 v[178:181], v239 offset:20480
	ds_read_b128 v[182:185], v239 offset:21504
	ds_read_b128 v[186:189], v239 offset:22528
	ds_read_b128 v[200:203], v239 offset:23552
	global_load_lds_dwordx4 v[204:205], off
	s_add_i32 m0, s6, 0x2000
	s_add_u32 s12, s30, 0x80000
	v_lshl_add_u64 v[206:207], s[30:31], 0, v[190:191]
	s_addc_u32 s13, s31, 0
	s_add_i32 s6, s14, s51
	global_load_lds_dwordx4 v[206:207], off
	s_mov_b32 m0, s6
	s_nop 0
	global_load_lds_dwordx4 v0, s[12:13]
	s_add_i32 m0, s6, 0x2000
	s_nop 0
	global_load_lds_dwordx4 v190, s[12:13]
	s_mov_b32 m0, s52
	s_nop 0
	global_load_lds_dwordx4 v194, s[48:49]
	s_mov_b32 m0, s53
	s_nop 0
	global_load_lds_dwordx4 v192, s[48:49]
	s_waitcnt vmcnt(8)
	s_waitcnt lgkmcnt(0)
	s_barrier
; #define PG8_STAGE(bufoff, gbase, voff) do { _Pragma("unroll") for (int _i = 0; _i < 2; ++_i) \
;         __builtin_amdgcn_global_load_lds((const unsigned*)((const char*)(gbase) + (voff)[_i]), (LAS unsigned*)(lds + (bufoff) + ldsw + _i * 8192), 16, 0, 0); } while (0)
; #define PG8_LDA(dst, b, h) do { _Pragma("unroll") for (int m = 0; m < 4; ++m) _Pragma("unroll") for (int k = 0; k < 2; ++k) dst[m][k] = *(const LAS bf16x8*)(lds + PG8_SA(b, h) + aoff + m * 2048 + k * 1024); } while (0)
; #define PG8_LDB(dst, b, h) do { _Pragma("unroll") for (int n = 0; n < 2; ++n) _Pragma("unroll") for (int k = 0; k < 2; ++k) dst[n][k] = *(const LAS bf16x8*)(lds + PG8_SB(b, h) + boff + n * 2048 + k * 1024); } while (0)
; #define PG8_MMA(ai, bj, At, Bt) do { __builtin_amdgcn_s_setprio(1); _Pragma("unroll") for (int m = 0; m < 4; ++m) _Pragma("unroll") for (int n = 0; n < 2; ++n) _Pragma("unroll") for (int k = 0; k < 2; ++k) \
;         acc[ai][bj][m][n] = __builtin_amdgcn_mfma_f32_16x16x32_bf16(Bt[n][k], At[m][k], acc[ai][bj][m][n], 0, 0, 0); __builtin_amdgcn_s_setprio(0); } while (0)
; #define PG8_WAIT_V(n) asm volatile("s_waitcnt vmcnt(" #n ")" ::: "memory")
; #define PG8_WAIT_L(n) asm volatile("s_waitcnt lgkmcnt(" #n ")" ::: "memory")
; #define PG8_BAR __builtin_amdgcn_s_barrier()
; #define PG8_SCHED __builtin_amdgcn_sched_barrier(0)
; template <class Epi>
; __device__ __forceinline__ void gemm_phase(LAS unsigned char* lds, const Gemm g, const TileOrder& S, const Epi& E) {
;     ...
;             PG8_WAIT_V(8); PG8_WAIT_L(0); PG8_BAR; PG8_MMA(1, 0, At, B0); PG8_MMA(1, 1, At, B1); PG8_BAR; PG8_SCHED;
;             PG8_LDB(B0, 1, 0); PG8_LDB(B1, 1, 1); PG8_SCHED; PG8_LDA(At, 1, 0); PG8_STAGE(PG8_SA(0, 1), a2 + hstepA, voffA);
;             PG8_WAIT_V(8); PG8_WAIT_L(0); PG8_BAR; PG8_MMA(0, 0, At, B0); PG8_MMA(0, 1, At, B1); PG8_BAR; PG8_SCHED;
	s_setprio 1
	s_waitcnt lgkmcnt(0)
	v_mfma_f32_16x16x32_bf16 v[62:65], v[118:121], v[162:165], v[62:65]
	v_mfma_f32_16x16x32_bf16 v[58:61], v[130:133], v[162:165], v[58:61]
	v_mfma_f32_16x16x32_bf16 v[46:49], v[118:121], v[170:173], v[46:49]
	v_mfma_f32_16x16x32_bf16 v[42:45], v[130:133], v[170:173], v[42:45]
	v_mfma_f32_16x16x32_bf16 v[30:33], v[118:121], v[178:181], v[30:33]
	v_mfma_f32_16x16x32_bf16 v[26:29], v[130:133], v[178:181], v[26:29]
	v_mfma_f32_16x16x32_bf16 v[14:17], v[118:121], v[186:189], v[14:17]
	v_mfma_f32_16x16x32_bf16 v[10:13], v[130:133], v[186:189], v[10:13]
	v_mfma_f32_16x16x32_bf16 v[62:65], v[126:129], v[166:169], v[62:65]
	v_mfma_f32_16x16x32_bf16 v[58:61], v[134:137], v[166:169], v[58:61]
	v_mfma_f32_16x16x32_bf16 v[46:49], v[126:129], v[174:177], v[46:49]
	v_mfma_f32_16x16x32_bf16 v[42:45], v[134:137], v[174:177], v[42:45]
	v_mfma_f32_16x16x32_bf16 v[30:33], v[126:129], v[182:185], v[30:33]
	v_mfma_f32_16x16x32_bf16 v[26:29], v[134:137], v[182:185], v[26:29]
	v_mfma_f32_16x16x32_bf16 v[14:17], v[126:129], v[200:203], v[14:17]
	v_mfma_f32_16x16x32_bf16 v[10:13], v[134:137], v[200:203], v[10:13]
	s_setprio 0
	s_setprio 1
	v_mfma_f32_16x16x32_bf16 v[54:57], v[138:141], v[162:165], v[54:57]
	v_mfma_f32_16x16x32_bf16 v[50:53], v[154:157], v[162:165], v[50:53]
	v_mfma_f32_16x16x32_bf16 v[38:41], v[138:141], v[170:173], v[38:41]
	v_mfma_f32_16x16x32_bf16 v[34:37], v[154:157], v[170:173], v[34:37]
	v_mfma_f32_16x16x32_bf16 v[22:25], v[138:141], v[178:181], v[22:25]
	v_mfma_f32_16x16x32_bf16 v[18:21], v[154:157], v[178:181], v[18:21]
	v_mfma_f32_16x16x32_bf16 v[6:9], v[138:141], v[186:189], v[6:9]
	v_mfma_f32_16x16x32_bf16 v[2:5], v[154:157], v[186:189], v[2:5]
	v_mfma_f32_16x16x32_bf16 v[54:57], v[142:145], v[166:169], v[54:57]
	v_mfma_f32_16x16x32_bf16 v[50:53], v[158:161], v[166:169], v[50:53]
	v_mfma_f32_16x16x32_bf16 v[38:41], v[142:145], v[174:177], v[38:41]
	v_mfma_f32_16x16x32_bf16 v[34:37], v[158:161], v[174:177], v[34:37]
	v_mfma_f32_16x16x32_bf16 v[22:25], v[142:145], v[182:185], v[22:25]
	v_mfma_f32_16x16x32_bf16 v[18:21], v[158:161], v[182:185], v[18:21]
	s_setprio 2
	s_barrier
	v_mfma_f32_16x16x32_bf16 v[6:9], v[142:145], v[200:203], v[6:9]
	s_mov_b32 s6, 0x18000
	s_mov_b32 s14, 0x1c000
	v_add_u32_e32 v134, s6, v238
	ds_read_b128 v[118:121], v134
	ds_read_b128 v[126:129], v134 offset:1024
	ds_read_b128 v[130:133], v134 offset:2048
	v_mfma_f32_16x16x32_bf16 v[2:5], v[158:161], v[200:203], v[2:5]
	s_setprio 0
	v_add_u32_e32 v158, s14, v238
	ds_read_b128 v[134:137], v134 offset:3072
	ds_read_b128 v[138:141], v158
	ds_read_b128 v[142:145], v158 offset:1024
	ds_read_b128 v[154:157], v158 offset:2048
	ds_read_b128 v[158:161], v158 offset:3072
	s_add_u32 s12, s48, 0x4000
	s_addc_u32 s13, s49, 0
	s_mov_b32 m0, s54
	ds_read_b128 v[162:165], v239 offset:32768
	ds_read_b128 v[166:169], v239 offset:33792
	ds_read_b128 v[170:173], v239 offset:34816
	ds_read_b128 v[174:177], v239 offset:35840
	ds_read_b128 v[178:181], v239 offset:36864
	ds_read_b128 v[182:185], v239 offset:37888
	ds_read_b128 v[186:189], v239 offset:38912
	ds_read_b128 v[200:203], v239 offset:39936
	global_load_lds_dwordx4 v194, s[12:13]
	s_mov_b32 m0, s55
	s_nop 0
	global_load_lds_dwordx4 v192, s[12:13]
	s_waitcnt vmcnt(8)
	s_waitcnt lgkmcnt(0)
	s_barrier
	s_setprio 1
	s_waitcnt lgkmcnt(0)
	v_mfma_f32_16x16x32_bf16 v[150:153], v[118:121], v[162:165], v[150:153]
	v_mfma_f32_16x16x32_bf16 v[146:149], v[130:133], v[162:165], v[146:149]
	v_mfma_f32_16x16x32_bf16 v[110:113], v[118:121], v[170:173], v[110:113]
	v_mfma_f32_16x16x32_bf16 v[106:109], v[130:133], v[170:173], v[106:109]
	v_mfma_f32_16x16x32_bf16 v[94:97], v[118:121], v[178:181], v[94:97]
	v_mfma_f32_16x16x32_bf16 v[90:93], v[130:133], v[178:181], v[90:93]
	v_mfma_f32_16x16x32_bf16 v[78:81], v[118:121], v[186:189], v[78:81]
	v_mfma_f32_16x16x32_bf16 v[74:77], v[130:133], v[186:189], v[74:77]
	v_mfma_f32_16x16x32_bf16 v[150:153], v[126:129], v[166:169], v[150:153]
	v_mfma_f32_16x16x32_bf16 v[146:149], v[134:137], v[166:169], v[146:149]
	v_mfma_f32_16x16x32_bf16 v[110:113], v[126:129], v[174:177], v[110:113]
	v_mfma_f32_16x16x32_bf16 v[106:109], v[134:137], v[174:177], v[106:109]
	v_mfma_f32_16x16x32_bf16 v[94:97], v[126:129], v[182:185], v[94:97]
	v_mfma_f32_16x16x32_bf16 v[90:93], v[134:137], v[182:185], v[90:93]
	v_mfma_f32_16x16x32_bf16 v[78:81], v[126:129], v[200:203], v[78:81]
	v_mfma_f32_16x16x32_bf16 v[74:77], v[134:137], v[200:203], v[74:77]
	s_setprio 0
	s_setprio 1
	v_mfma_f32_16x16x32_bf16 v[122:125], v[138:141], v[162:165], v[122:125]
	v_mfma_f32_16x16x32_bf16 v[114:117], v[154:157], v[162:165], v[114:117]
	v_mfma_f32_16x16x32_bf16 v[102:105], v[138:141], v[170:173], v[102:105]
	v_mfma_f32_16x16x32_bf16 v[98:101], v[154:157], v[170:173], v[98:101]
	v_mfma_f32_16x16x32_bf16 v[86:89], v[138:141], v[178:181], v[86:89]
	v_mfma_f32_16x16x32_bf16 v[82:85], v[154:157], v[178:181], v[82:85]
	v_mfma_f32_16x16x32_bf16 v[70:73], v[138:141], v[186:189], v[70:73]
	v_mfma_f32_16x16x32_bf16 v[66:69], v[154:157], v[186:189], v[66:69]
	v_mfma_f32_16x16x32_bf16 v[122:125], v[142:145], v[166:169], v[122:125]
	v_mfma_f32_16x16x32_bf16 v[114:117], v[158:161], v[166:169], v[114:117]
	v_mfma_f32_16x16x32_bf16 v[102:105], v[142:145], v[174:177], v[102:105]
	v_mfma_f32_16x16x32_bf16 v[98:101], v[158:161], v[174:177], v[98:101]
	v_mfma_f32_16x16x32_bf16 v[86:89], v[142:145], v[182:185], v[86:89]
	v_mfma_f32_16x16x32_bf16 v[82:85], v[158:161], v[182:185], v[82:85]
	s_setprio 2
	s_barrier
; #define PG8_STAGE(bufoff, gbase, voff) do { _Pragma("unroll") for (int _i = 0; _i < 2; ++_i) \
;         __builtin_amdgcn_global_load_lds((const unsigned*)((const char*)(gbase) + (voff)[_i]), (LAS unsigned*)(lds + (bufoff) + ldsw + _i * 8192), 16, 0, 0); } while (0)
; #define PG8_LDA(dst, b, h) do { _Pragma("unroll") for (int m = 0; m < 4; ++m) _Pragma("unroll") for (int k = 0; k < 2; ++k) dst[m][k] = *(const LAS bf16x8*)(lds + PG8_SA(b, h) + aoff + m * 2048 + k * 1024); } while (0)
; #define PG8_MMA(ai, bj, At, Bt) do { __builtin_amdgcn_s_setprio(1); _Pragma("unroll") for (int m = 0; m < 4; ++m) _Pragma("unroll") for (int n = 0; n < 2; ++n) _Pragma("unroll") for (int k = 0; k < 2; ++k) \
;         acc[ai][bj][m][n] = __builtin_amdgcn_mfma_f32_16x16x32_bf16(Bt[n][k], At[m][k], acc[ai][bj][m][n], 0, 0, 0); __builtin_amdgcn_s_setprio(0); } while (0)
; #define PG8_WAIT_V(n) asm volatile("s_waitcnt vmcnt(" #n ")" ::: "memory")
; #define PG8_WAIT_L(n) asm volatile("s_waitcnt lgkmcnt(" #n ")" ::: "memory")
; #define PG8_BAR __builtin_amdgcn_s_barrier()
; #define PG8_SCHED __builtin_amdgcn_sched_barrier(0)
; template <class Epi>
; __device__ __forceinline__ void gemm_phase(LAS unsigned char* lds, const Gemm g, const TileOrder& S, const Epi& E) {
;     ...
;             PG8_WAIT_V(8); PG8_WAIT_L(0); PG8_BAR; PG8_MMA(0, 0, At, B0); PG8_MMA(0, 1, At, B1); PG8_BAR; PG8_SCHED;
;             PG8_LDA(At, 1, 1); PG8_STAGE(PG8_SB(1, 0), b3, voffB); PG8_STAGE(PG8_SB(1, 1), b3 + hstepB, voffB); PG8_STAGE(PG8_SA(1, 0), a3, voffA);
;             PG8_WAIT_V(8); PG8_WAIT_L(0); PG8_BAR; PG8_MMA(1, 0, At, B0); PG8_MMA(1, 1, At, B1); PG8_BAR; PG8_SCHED;
;         }
;         if (wr == 0) PG8_BAR;
	v_mfma_f32_16x16x32_bf16 v[70:73], v[142:145], v[200:203], v[70:73]
	ds_read_b128 v[162:165], v239 offset:49152
	ds_read_b128 v[166:169], v239 offset:50176
	ds_read_b128 v[170:173], v239 offset:51200
	v_mfma_f32_16x16x32_bf16 v[66:69], v[158:161], v[200:203], v[66:69]
	s_setprio 0
	s_add_i32 s6, s6, s51
	v_lshl_add_u64 v[204:205], v[204:205], 0, s[34:35]
	s_mov_b32 m0, s6
	ds_read_b128 v[174:177], v239 offset:52224
	ds_read_b128 v[178:181], v239 offset:53248
	ds_read_b128 v[182:185], v239 offset:54272
	ds_read_b128 v[186:189], v239 offset:55296
	ds_read_b128 v[200:203], v239 offset:56320
	global_load_lds_dwordx4 v[204:205], off
	s_add_i32 m0, s6, 0x2000
	s_add_u32 s12, s30, 0x80080
	v_lshl_add_u64 v[204:205], v[206:207], 0, s[34:35]
	s_addc_u32 s13, s31, 0
	s_add_i32 s6, s14, s51
	global_load_lds_dwordx4 v[204:205], off
	s_mov_b32 m0, s6
	s_nop 0
	global_load_lds_dwordx4 v0, s[12:13]
	s_add_i32 m0, s6, 0x2000
	s_nop 0
	global_load_lds_dwordx4 v190, s[12:13]
	s_mov_b32 m0, s60
	s_nop 0
	global_load_lds_dwordx4 v194, s[2:3]
	s_mov_b32 m0, s61
	s_nop 0
	global_load_lds_dwordx4 v192, s[2:3]
	s_waitcnt vmcnt(8)
	s_waitcnt lgkmcnt(0)
	s_barrier
	s_setprio 1
	s_waitcnt lgkmcnt(0)
	v_mfma_f32_16x16x32_bf16 v[62:65], v[118:121], v[162:165], v[62:65]
	v_mfma_f32_16x16x32_bf16 v[58:61], v[130:133], v[162:165], v[58:61]
	v_mfma_f32_16x16x32_bf16 v[46:49], v[118:121], v[170:173], v[46:49]
	v_mfma_f32_16x16x32_bf16 v[42:45], v[130:133], v[170:173], v[42:45]
	v_mfma_f32_16x16x32_bf16 v[30:33], v[118:121], v[178:181], v[30:33]
	v_mfma_f32_16x16x32_bf16 v[26:29], v[130:133], v[178:181], v[26:29]
	v_mfma_f32_16x16x32_bf16 v[14:17], v[118:121], v[186:189], v[14:17]
	v_mfma_f32_16x16x32_bf16 v[10:13], v[130:133], v[186:189], v[10:13]
	v_mfma_f32_16x16x32_bf16 v[62:65], v[126:129], v[166:169], v[62:65]
	v_mfma_f32_16x16x32_bf16 v[58:61], v[134:137], v[166:169], v[58:61]
	v_mfma_f32_16x16x32_bf16 v[46:49], v[126:129], v[174:177], v[46:49]
	v_mfma_f32_16x16x32_bf16 v[42:45], v[134:137], v[174:177], v[42:45]
	v_mfma_f32_16x16x32_bf16 v[30:33], v[126:129], v[182:185], v[30:33]
	v_mfma_f32_16x16x32_bf16 v[26:29], v[134:137], v[182:185], v[26:29]
	v_mfma_f32_16x16x32_bf16 v[14:17], v[126:129], v[200:203], v[14:17]
	v_mfma_f32_16x16x32_bf16 v[10:13], v[134:137], v[200:203], v[10:13]
	s_setprio 0
	s_setprio 1
	v_mfma_f32_16x16x32_bf16 v[54:57], v[138:141], v[162:165], v[54:57]
	v_mfma_f32_16x16x32_bf16 v[50:53], v[154:157], v[162:165], v[50:53]
	v_mfma_f32_16x16x32_bf16 v[38:41], v[138:141], v[170:173], v[38:41]
	v_mfma_f32_16x16x32_bf16 v[34:37], v[154:157], v[170:173], v[34:37]
	v_mfma_f32_16x16x32_bf16 v[22:25], v[138:141], v[178:181], v[22:25]
	v_mfma_f32_16x16x32_bf16 v[18:21], v[154:157], v[178:181], v[18:21]
	v_mfma_f32_16x16x32_bf16 v[6:9], v[138:141], v[186:189], v[6:9]
	v_mfma_f32_16x16x32_bf16 v[2:5], v[154:157], v[186:189], v[2:5]
	v_mfma_f32_16x16x32_bf16 v[54:57], v[142:145], v[166:169], v[54:57]
	v_mfma_f32_16x16x32_bf16 v[50:53], v[158:161], v[166:169], v[50:53]
	v_mfma_f32_16x16x32_bf16 v[38:41], v[142:145], v[174:177], v[38:41]
	v_mfma_f32_16x16x32_bf16 v[34:37], v[158:161], v[174:177], v[34:37]
	v_mfma_f32_16x16x32_bf16 v[22:25], v[142:145], v[182:185], v[22:25]
	v_mfma_f32_16x16x32_bf16 v[18:21], v[158:161], v[182:185], v[18:21]
	s_setprio 2
	s_barrier
	v_mfma_f32_16x16x32_bf16 v[6:9], v[142:145], v[200:203], v[6:9]
	v_mfma_f32_16x16x32_bf16 v[2:5], v[158:161], v[200:203], v[2:5]
	s_setprio 0
	s_add_i32 s68, s68, 2
	s_add_u32 s66, s66, 0x100
	s_addc_u32 s67, s67, 0
	s_add_u32 s28, s28, 0x10000
	s_addc_u32 s29, s29, 0
	s_cmp_gt_u32 s68, 29
	s_cbranch_scc0 .LBB0_255
	s_and_b64 vcc, exec, s[36:37]
	s_cbranch_vccz .LBB0_258
	s_barrier

; #define PG8_STAGE(bufoff, gbase, voff) do { _Pragma("unroll") for (int _i = 0; _i < 2; ++_i) \
;         __builtin_amdgcn_global_load_lds((const unsigned*)((const char*)(gbase) + (voff)[_i]), (LAS unsigned*)(lds + (bufoff) + ldsw + _i * 8192), 16, 0, 0); } while (0)
; #define PG8_LDA(dst, b, h) do { _Pragma("unroll") for (int m = 0; m < 4; ++m) _Pragma("unroll") for (int k = 0; k < 2; ++k) dst[m][k] = *(const LAS bf16x8*)(lds + PG8_SA(b, h) + aoff + m * 2048 + k * 1024); } while (0)
; #define PG8_LDB(dst, b, h) do { _Pragma("unroll") for (int n = 0; n < 2; ++n) _Pragma("unroll") for (int k = 0; k < 2; ++k) dst[n][k] = *(const LAS bf16x8*)(lds + PG8_SB(b, h) + boff + n * 2048 + k * 1024); } while (0)
; #define PG8_MMA(ai, bj, At, Bt) do { __builtin_amdgcn_s_setprio(1); _Pragma("unroll") for (int m = 0; m < 4; ++m) _Pragma("unroll") for (int n = 0; n < 2; ++n) _Pragma("unroll") for (int k = 0; k < 2; ++k) \
;         acc[ai][bj][m][n] = __builtin_amdgcn_mfma_f32_16x16x32_bf16(Bt[n][k], At[m][k], acc[ai][bj][m][n], 0, 0, 0); __builtin_amdgcn_s_setprio(0); } while (0)
; #define PG8_WAIT_V(n) asm volatile("s_waitcnt vmcnt(" #n ")" ::: "memory")
; #define PG8_WAIT_L(n) asm volatile("s_waitcnt lgkmcnt(" #n ")" ::: "memory")
; #define PG8_BAR __builtin_amdgcn_s_barrier()
; #define PG8_SCHED __builtin_amdgcn_sched_barrier(0)
; template <class Epi>
; __device__ __forceinline__ void gemm_phase(LAS unsigned char* lds, const Gemm g, const TileOrder& S, const Epi& E) {
;     ...
;         for (int t = 0; t < nt; t += 2) {
;             const bool last = (t == nt - 2);
;             const char* a1 = cA + (size_t)(t + 1) * kstepA;
;             const char* a2 = last ? nA : cA + (size_t)(t + 2) * kstepA; const char* b2 = last ? nB : cB + (size_t)(t + 2) * kstep;
;             const char* a3 = a2 + kstepA; const char* b3 = b2 + kstep;
;             PG8_LDB(B0, 0, 0); PG8_LDB(B1, 0, 1); PG8_SCHED; PG8_LDA(At, 0, 0); PG8_STAGE(PG8_SA(1, 1), a1 + hstepA, voffA);
;             PG8_WAIT_V(8); PG8_WAIT_L(0); PG8_BAR; PG8_MMA(0, 0, At, B0); PG8_MMA(0, 1, At, B1); PG8_BAR; PG8_SCHED;
;             PG8_LDA(At, 0, 1); PG8_STAGE(PG8_SB(0, 0), b2, voffB); PG8_STAGE(PG8_SB(0, 1), b2 + hstepB, voffB); PG8_STAGE(PG8_SA(0, 0), a2, voffA);
;             PG8_WAIT_V(8); PG8_WAIT_L(0); PG8_BAR; PG8_MMA(1, 0, At, B0); PG8_MMA(1, 1, At, B1); PG8_BAR; PG8_SCHED;
.LBB0_457:
	s_mov_b32 s6, 0x10000
	s_mov_b32 s12, 0x14000
	v_add_u32_e32 v156, s6, v142
	v_add_u32_e32 v172, s12, v142
	ds_read_b128 v[144:147], v156
	ds_read_b128 v[148:151], v156 offset:1024
	ds_read_b128 v[152:155], v156 offset:2048
	ds_read_b128 v[156:159], v156 offset:3072
	ds_read_b128 v[160:163], v172
	ds_read_b128 v[164:167], v172 offset:1024
	ds_read_b128 v[168:171], v172 offset:2048
	ds_read_b128 v[172:175], v172 offset:3072
	ds_read_b128 v[176:179], v143
	ds_read_b128 v[180:183], v143 offset:1024
	ds_read_b128 v[184:187], v143 offset:2048
	ds_read_b128 v[188:191], v143 offset:3072
	ds_read_b128 v[192:195], v143 offset:4096
	ds_read_b128 v[196:199], v143 offset:5120
	ds_read_b128 v[200:203], v143 offset:6144
	ds_read_b128 v[204:207], v143 offset:7168
	s_add_u32 s2, s44, 0x100
	s_addc_u32 s3, s45, 0
	s_cmp_eq_u32 s60, 4
	s_cselect_b32 s47, s39, s3
	s_cselect_b32 s46, s38, s2
	s_cselect_b32 s5, s29, s59
	s_cselect_b32 s4, s57, s58
	s_add_i32 m0, s26, 0xc000
	s_nop 0
	global_load_lds_dwordx4 v136, s[44:45]
	s_add_i32 m0, s26, 0xe000
	s_nop 0
	global_load_lds_dwordx4 v138, s[44:45]
	s_waitcnt vmcnt(8)
	s_waitcnt lgkmcnt(0)
	s_barrier
	s_setprio 1
	s_waitcnt lgkmcnt(0)
	v_mfma_f32_16x16x32_bf16 v[126:129], v[144:147], v[176:179], v[126:129]
	v_mfma_f32_16x16x32_bf16 v[122:125], v[152:155], v[176:179], v[122:125]
	v_mfma_f32_16x16x32_bf16 v[118:121], v[144:147], v[184:187], v[118:121]
	v_mfma_f32_16x16x32_bf16 v[114:117], v[152:155], v[184:187], v[114:117]
	v_mfma_f32_16x16x32_bf16 v[106:109], v[144:147], v[192:195], v[106:109]
	v_mfma_f32_16x16x32_bf16 v[98:101], v[152:155], v[192:195], v[98:101]
	v_mfma_f32_16x16x32_bf16 v[90:93], v[144:147], v[200:203], v[90:93]
	v_mfma_f32_16x16x32_bf16 v[82:85], v[152:155], v[200:203], v[82:85]
	v_mfma_f32_16x16x32_bf16 v[126:129], v[148:151], v[180:183], v[126:129]
	v_mfma_f32_16x16x32_bf16 v[122:125], v[156:159], v[180:183], v[122:125]
	v_mfma_f32_16x16x32_bf16 v[118:121], v[148:151], v[188:191], v[118:121]
	v_mfma_f32_16x16x32_bf16 v[114:117], v[156:159], v[188:191], v[114:117]
	v_mfma_f32_16x16x32_bf16 v[106:109], v[148:151], v[196:199], v[106:109]
	v_mfma_f32_16x16x32_bf16 v[98:101], v[156:159], v[196:199], v[98:101]
	v_mfma_f32_16x16x32_bf16 v[90:93], v[148:151], v[204:207], v[90:93]
	v_mfma_f32_16x16x32_bf16 v[82:85], v[156:159], v[204:207], v[82:85]
	s_setprio 0
	s_setprio 1
	v_mfma_f32_16x16x32_bf16 v[110:113], v[160:163], v[176:179], v[110:113]
	v_mfma_f32_16x16x32_bf16 v[102:105], v[168:171], v[176:179], v[102:105]
	v_mfma_f32_16x16x32_bf16 v[94:97], v[160:163], v[184:187], v[94:97]
	v_mfma_f32_16x16x32_bf16 v[86:89], v[168:171], v[184:187], v[86:89]
	v_mfma_f32_16x16x32_bf16 v[78:81], v[160:163], v[192:195], v[78:81]
	v_mfma_f32_16x16x32_bf16 v[74:77], v[168:171], v[192:195], v[74:77]
	v_mfma_f32_16x16x32_bf16 v[70:73], v[160:163], v[200:203], v[70:73]
	v_mfma_f32_16x16x32_bf16 v[66:69], v[168:171], v[200:203], v[66:69]
	v_mfma_f32_16x16x32_bf16 v[110:113], v[164:167], v[180:183], v[110:113]
	v_mfma_f32_16x16x32_bf16 v[102:105], v[172:175], v[180:183], v[102:105]
	v_mfma_f32_16x16x32_bf16 v[94:97], v[164:167], v[188:191], v[94:97]
	v_mfma_f32_16x16x32_bf16 v[86:89], v[172:175], v[188:191], v[86:89]
	v_mfma_f32_16x16x32_bf16 v[78:81], v[164:167], v[196:199], v[78:81]
	v_mfma_f32_16x16x32_bf16 v[74:77], v[172:175], v[196:199], v[74:77]
	s_setprio 2
	s_barrier
	v_mfma_f32_16x16x32_bf16 v[70:73], v[164:167], v[204:207], v[70:73]
	ds_read_b128 v[176:179], v143 offset:16384
	ds_read_b128 v[180:183], v143 offset:17408
	ds_read_b128 v[184:187], v143 offset:18432
	v_mfma_f32_16x16x32_bf16 v[66:69], v[172:175], v[204:207], v[66:69]
	s_setprio 0
	s_add_i32 s6, s6, s25
	v_lshl_add_u64 v[208:209], s[4:5], 0, v[0:1]
	s_mov_b32 m0, s6
	ds_read_b128 v[188:191], v143 offset:19456
	ds_read_b128 v[192:195], v143 offset:20480
	ds_read_b128 v[196:199], v143 offset:21504
	ds_read_b128 v[200:203], v143 offset:22528
	ds_read_b128 v[204:207], v143 offset:23552
	global_load_lds_dwordx4 v[208:209], off
	s_add_i32 m0, s6, 0x2000
	s_add_u32 s14, s4, 0x20000
	v_lshl_add_u64 v[210:211], s[4:5], 0, v[130:131]
	s_addc_u32 s15, s5, 0
	s_add_i32 s6, s12, s25
	global_load_lds_dwordx4 v[210:211], off
	s_mov_b32 m0, s6
	v_lshl_add_u64 v[214:215], s[46:47], 0, v[132:133]
	global_load_lds_dwordx4 v0, s[14:15]
	s_add_i32 m0, s6, 0x2000
	s_nop 0
	global_load_lds_dwordx4 v130, s[14:15]
	v_lshl_add_u64 v[212:213], s[46:47], 0, v[134:135]
	s_mov_b32 m0, s26
	s_nop 0
	global_load_lds_dwordx4 v[212:213], off
	s_mov_b32 m0, s48
	s_nop 0
	global_load_lds_dwordx4 v[214:215], off
	s_waitcnt vmcnt(8)
	s_waitcnt lgkmcnt(0)
	s_barrier
; #define PG8_STAGE(bufoff, gbase, voff) do { _Pragma("unroll") for (int _i = 0; _i < 2; ++_i) \
;         __builtin_amdgcn_global_load_lds((const unsigned*)((const char*)(gbase) + (voff)[_i]), (LAS unsigned*)(lds + (bufoff) + ldsw + _i * 8192), 16, 0, 0); } while (0)
; #define PG8_LDA(dst, b, h) do { _Pragma("unroll") for (int m = 0; m < 4; ++m) _Pragma("unroll") for (int k = 0; k < 2; ++k) dst[m][k] = *(const LAS bf16x8*)(lds + PG8_SA(b, h) + aoff + m * 2048 + k * 1024); } while (0)
; #define PG8_LDB(dst, b, h) do { _Pragma("unroll") for (int n = 0; n < 2; ++n) _Pragma("unroll") for (int k = 0; k < 2; ++k) dst[n][k] = *(const LAS bf16x8*)(lds + PG8_SB(b, h) + boff + n * 2048 + k * 1024); } while (0)
; #define PG8_MMA(ai, bj, At, Bt) do { __builtin_amdgcn_s_setprio(1); _Pragma("unroll") for (int m = 0; m < 4; ++m) _Pragma("unroll") for (int n = 0; n < 2; ++n) _Pragma("unroll") for (int k = 0; k < 2; ++k) \
;         acc[ai][bj][m][n] = __builtin_amdgcn_mfma_f32_16x16x32_bf16(Bt[n][k], At[m][k], acc[ai][bj][m][n], 0, 0, 0); __builtin_amdgcn_s_setprio(0); } while (0)
; #define PG8_WAIT_V(n) asm volatile("s_waitcnt vmcnt(" #n ")" ::: "memory")
; #define PG8_WAIT_L(n) asm volatile("s_waitcnt lgkmcnt(" #n ")" ::: "memory")
; #define PG8_BAR __builtin_amdgcn_s_barrier()
; #define PG8_SCHED __builtin_amdgcn_sched_barrier(0)
; template <class Epi>
; __device__ __forceinline__ void gemm_phase(LAS unsigned char* lds, const Gemm g, const TileOrder& S, const Epi& E) {
;     ...
;             PG8_WAIT_V(8); PG8_WAIT_L(0); PG8_BAR; PG8_MMA(1, 0, At, B0); PG8_MMA(1, 1, At, B1); PG8_BAR; PG8_SCHED;
;             PG8_LDB(B0, 1, 0); PG8_LDB(B1, 1, 1); PG8_SCHED; PG8_LDA(At, 1, 0); PG8_STAGE(PG8_SA(0, 1), a2 + hstepA, voffA);
;             PG8_WAIT_V(8); PG8_WAIT_L(0); PG8_BAR; PG8_MMA(0, 0, At, B0); PG8_MMA(0, 1, At, B1); PG8_BAR; PG8_SCHED;
	s_setprio 1
	s_waitcnt lgkmcnt(0)
	v_mfma_f32_16x16x32_bf16 v[62:65], v[144:147], v[176:179], v[62:65]
	v_mfma_f32_16x16x32_bf16 v[58:61], v[152:155], v[176:179], v[58:61]
	v_mfma_f32_16x16x32_bf16 v[54:57], v[144:147], v[184:187], v[54:57]
	v_mfma_f32_16x16x32_bf16 v[50:53], v[152:155], v[184:187], v[50:53]
	v_mfma_f32_16x16x32_bf16 v[38:41], v[144:147], v[192:195], v[38:41]
	v_mfma_f32_16x16x32_bf16 v[34:37], v[152:155], v[192:195], v[34:37]
	v_mfma_f32_16x16x32_bf16 v[22:25], v[144:147], v[200:203], v[22:25]
	v_mfma_f32_16x16x32_bf16 v[18:21], v[152:155], v[200:203], v[18:21]
	v_mfma_f32_16x16x32_bf16 v[62:65], v[148:151], v[180:183], v[62:65]
	v_mfma_f32_16x16x32_bf16 v[58:61], v[156:159], v[180:183], v[58:61]
	v_mfma_f32_16x16x32_bf16 v[54:57], v[148:151], v[188:191], v[54:57]
	v_mfma_f32_16x16x32_bf16 v[50:53], v[156:159], v[188:191], v[50:53]
	v_mfma_f32_16x16x32_bf16 v[38:41], v[148:151], v[196:199], v[38:41]
	v_mfma_f32_16x16x32_bf16 v[34:37], v[156:159], v[196:199], v[34:37]
	v_mfma_f32_16x16x32_bf16 v[22:25], v[148:151], v[204:207], v[22:25]
	v_mfma_f32_16x16x32_bf16 v[18:21], v[156:159], v[204:207], v[18:21]
	s_setprio 0
	s_setprio 1
	v_mfma_f32_16x16x32_bf16 v[46:49], v[160:163], v[176:179], v[46:49]
	v_mfma_f32_16x16x32_bf16 v[42:45], v[168:171], v[176:179], v[42:45]
	v_mfma_f32_16x16x32_bf16 v[30:33], v[160:163], v[184:187], v[30:33]
	v_mfma_f32_16x16x32_bf16 v[26:29], v[168:171], v[184:187], v[26:29]
	v_mfma_f32_16x16x32_bf16 v[14:17], v[160:163], v[192:195], v[14:17]
	v_mfma_f32_16x16x32_bf16 v[10:13], v[168:171], v[192:195], v[10:13]
	v_mfma_f32_16x16x32_bf16 v[6:9], v[160:163], v[200:203], v[6:9]
	v_mfma_f32_16x16x32_bf16 v[2:5], v[168:171], v[200:203], v[2:5]
	v_mfma_f32_16x16x32_bf16 v[46:49], v[164:167], v[180:183], v[46:49]
	v_mfma_f32_16x16x32_bf16 v[42:45], v[172:175], v[180:183], v[42:45]
	v_mfma_f32_16x16x32_bf16 v[30:33], v[164:167], v[188:191], v[30:33]
	v_mfma_f32_16x16x32_bf16 v[26:29], v[172:175], v[188:191], v[26:29]
	v_mfma_f32_16x16x32_bf16 v[14:17], v[164:167], v[196:199], v[14:17]
	v_mfma_f32_16x16x32_bf16 v[10:13], v[172:175], v[196:199], v[10:13]
	s_setprio 2
	s_barrier
	v_mfma_f32_16x16x32_bf16 v[6:9], v[164:167], v[204:207], v[6:9]
	s_mov_b32 s6, 0x18000
	s_mov_b32 s12, 0x1c000
	v_add_u32_e32 v156, s6, v142
	ds_read_b128 v[144:147], v156
	ds_read_b128 v[148:151], v156 offset:1024
	ds_read_b128 v[152:155], v156 offset:2048
	v_mfma_f32_16x16x32_bf16 v[2:5], v[172:175], v[204:207], v[2:5]
	s_setprio 0
	v_add_u32_e32 v172, s12, v142
	ds_read_b128 v[156:159], v156 offset:3072
	ds_read_b128 v[160:163], v172
	ds_read_b128 v[164:167], v172 offset:1024
	ds_read_b128 v[168:171], v172 offset:2048
	ds_read_b128 v[172:175], v172 offset:3072
	s_add_u32 s14, s46, 0x30000
	s_addc_u32 s15, s47, 0
	s_mov_b32 m0, s49
	ds_read_b128 v[176:179], v143 offset:32768
	ds_read_b128 v[180:183], v143 offset:33792
	ds_read_b128 v[184:187], v143 offset:34816
	ds_read_b128 v[188:191], v143 offset:35840
	ds_read_b128 v[192:195], v143 offset:36864
	ds_read_b128 v[196:199], v143 offset:37888
	ds_read_b128 v[200:203], v143 offset:38912
	ds_read_b128 v[204:207], v143 offset:39936
	global_load_lds_dwordx4 v134, s[14:15]
	s_mov_b32 m0, s50
	s_nop 0
	global_load_lds_dwordx4 v132, s[14:15]
	s_waitcnt vmcnt(8)
	s_waitcnt lgkmcnt(0)
	s_barrier
	s_setprio 1
	s_waitcnt lgkmcnt(0)
	v_mfma_f32_16x16x32_bf16 v[126:129], v[144:147], v[176:179], v[126:129]
	v_mfma_f32_16x16x32_bf16 v[122:125], v[152:155], v[176:179], v[122:125]
	v_mfma_f32_16x16x32_bf16 v[118:121], v[144:147], v[184:187], v[118:121]
	v_mfma_f32_16x16x32_bf16 v[114:117], v[152:155], v[184:187], v[114:117]
	v_mfma_f32_16x16x32_bf16 v[106:109], v[144:147], v[192:195], v[106:109]
	v_mfma_f32_16x16x32_bf16 v[98:101], v[152:155], v[192:195], v[98:101]
	v_mfma_f32_16x16x32_bf16 v[90:93], v[144:147], v[200:203], v[90:93]
	v_mfma_f32_16x16x32_bf16 v[82:85], v[152:155], v[200:203], v[82:85]
	v_mfma_f32_16x16x32_bf16 v[126:129], v[148:151], v[180:183], v[126:129]
	v_mfma_f32_16x16x32_bf16 v[122:125], v[156:159], v[180:183], v[122:125]
	v_mfma_f32_16x16x32_bf16 v[118:121], v[148:151], v[188:191], v[118:121]
	v_mfma_f32_16x16x32_bf16 v[114:117], v[156:159], v[188:191], v[114:117]
	v_mfma_f32_16x16x32_bf16 v[106:109], v[148:151], v[196:199], v[106:109]
	v_mfma_f32_16x16x32_bf16 v[98:101], v[156:159], v[196:199], v[98:101]
	v_mfma_f32_16x16x32_bf16 v[90:93], v[148:151], v[204:207], v[90:93]
	v_mfma_f32_16x16x32_bf16 v[82:85], v[156:159], v[204:207], v[82:85]
	s_setprio 0
	s_setprio 1
	v_mfma_f32_16x16x32_bf16 v[110:113], v[160:163], v[176:179], v[110:113]
	v_mfma_f32_16x16x32_bf16 v[102:105], v[168:171], v[176:179], v[102:105]
	v_mfma_f32_16x16x32_bf16 v[94:97], v[160:163], v[184:187], v[94:97]
	v_mfma_f32_16x16x32_bf16 v[86:89], v[168:171], v[184:187], v[86:89]
	v_mfma_f32_16x16x32_bf16 v[78:81], v[160:163], v[192:195], v[78:81]
	v_mfma_f32_16x16x32_bf16 v[74:77], v[168:171], v[192:195], v[74:77]
	v_mfma_f32_16x16x32_bf16 v[70:73], v[160:163], v[200:203], v[70:73]
	v_mfma_f32_16x16x32_bf16 v[66:69], v[168:171], v[200:203], v[66:69]
	v_mfma_f32_16x16x32_bf16 v[110:113], v[164:167], v[180:183], v[110:113]
	v_mfma_f32_16x16x32_bf16 v[102:105], v[172:175], v[180:183], v[102:105]
	v_mfma_f32_16x16x32_bf16 v[94:97], v[164:167], v[188:191], v[94:97]
	v_mfma_f32_16x16x32_bf16 v[86:89], v[172:175], v[188:191], v[86:89]
	v_mfma_f32_16x16x32_bf16 v[78:81], v[164:167], v[196:199], v[78:81]
	v_mfma_f32_16x16x32_bf16 v[74:77], v[172:175], v[196:199], v[74:77]
	s_setprio 2
	s_barrier
; #define PG8_STAGE(bufoff, gbase, voff) do { _Pragma("unroll") for (int _i = 0; _i < 2; ++_i) \
;         __builtin_amdgcn_global_load_lds((const unsigned*)((const char*)(gbase) + (voff)[_i]), (LAS unsigned*)(lds + (bufoff) + ldsw + _i * 8192), 16, 0, 0); } while (0)
; #define PG8_LDA(dst, b, h) do { _Pragma("unroll") for (int m = 0; m < 4; ++m) _Pragma("unroll") for (int k = 0; k < 2; ++k) dst[m][k] = *(const LAS bf16x8*)(lds + PG8_SA(b, h) + aoff + m * 2048 + k * 1024); } while (0)
; #define PG8_MMA(ai, bj, At, Bt) do { __builtin_amdgcn_s_setprio(1); _Pragma("unroll") for (int m = 0; m < 4; ++m) _Pragma("unroll") for (int n = 0; n < 2; ++n) _Pragma("unroll") for (int k = 0; k < 2; ++k) \
;         acc[ai][bj][m][n] = __builtin_amdgcn_mfma_f32_16x16x32_bf16(Bt[n][k], At[m][k], acc[ai][bj][m][n], 0, 0, 0); __builtin_amdgcn_s_setprio(0); } while (0)
; #define PG8_WAIT_V(n) asm volatile("s_waitcnt vmcnt(" #n ")" ::: "memory")
; #define PG8_WAIT_L(n) asm volatile("s_waitcnt lgkmcnt(" #n ")" ::: "memory")
; #define PG8_BAR __builtin_amdgcn_s_barrier()
; #define PG8_SCHED __builtin_amdgcn_sched_barrier(0)
; template <class Epi>
; __device__ __forceinline__ void gemm_phase(LAS unsigned char* lds, const Gemm g, const TileOrder& S, const Epi& E) {
;     ...
;             PG8_WAIT_V(8); PG8_WAIT_L(0); PG8_BAR; PG8_MMA(0, 0, At, B0); PG8_MMA(0, 1, At, B1); PG8_BAR; PG8_SCHED;
;             PG8_LDA(At, 1, 1); PG8_STAGE(PG8_SB(1, 0), b3, voffB); PG8_STAGE(PG8_SB(1, 1), b3 + hstepB, voffB); PG8_STAGE(PG8_SA(1, 0), a3, voffA);
;             PG8_WAIT_V(8); PG8_WAIT_L(0); PG8_BAR; PG8_MMA(1, 0, At, B0); PG8_MMA(1, 1, At, B1); PG8_BAR; PG8_SCHED;
;         }
;         if (wr == 0) PG8_BAR;
	v_mfma_f32_16x16x32_bf16 v[70:73], v[164:167], v[204:207], v[70:73]
	ds_read_b128 v[176:179], v143 offset:49152
	ds_read_b128 v[180:183], v143 offset:50176
	ds_read_b128 v[184:187], v143 offset:51200
	v_mfma_f32_16x16x32_bf16 v[66:69], v[172:175], v[204:207], v[66:69]
	s_setprio 0
	s_add_i32 s6, s6, s25
	v_lshl_add_u64 v[208:209], v[208:209], 0, s[34:35]
	s_mov_b32 m0, s6
	ds_read_b128 v[188:191], v143 offset:52224
	ds_read_b128 v[192:195], v143 offset:53248
	ds_read_b128 v[196:199], v143 offset:54272
	ds_read_b128 v[200:203], v143 offset:55296
	ds_read_b128 v[204:207], v143 offset:56320
	global_load_lds_dwordx4 v[208:209], off
	s_add_i32 m0, s6, 0x2000
	s_add_u32 s4, s4, 0x20080
	v_lshl_add_u64 v[208:209], v[210:211], 0, s[34:35]
	s_addc_u32 s5, s5, 0
	s_add_i32 s6, s12, s25
	global_load_lds_dwordx4 v[208:209], off
	s_mov_b32 m0, s6
	s_nop 0
	global_load_lds_dwordx4 v0, s[4:5]
	v_lshl_add_u64 v[208:209], s[4:5], 0, v[130:131]
	s_add_i32 m0, s6, 0x2000
	s_nop 0
	global_load_lds_dwordx4 v[208:209], off
	v_lshl_add_u64 v[208:209], v[212:213], 0, s[34:35]
	s_mov_b32 m0, s51
	s_nop 0
	global_load_lds_dwordx4 v[208:209], off
	v_lshl_add_u64 v[208:209], v[214:215], 0, s[34:35]
	s_mov_b32 m0, s52
	s_nop 0
	global_load_lds_dwordx4 v[208:209], off
	s_waitcnt vmcnt(8)
	s_waitcnt lgkmcnt(0)
	s_barrier
	s_setprio 1
	s_waitcnt lgkmcnt(0)
	v_mfma_f32_16x16x32_bf16 v[62:65], v[144:147], v[176:179], v[62:65]
	v_mfma_f32_16x16x32_bf16 v[58:61], v[152:155], v[176:179], v[58:61]
	v_mfma_f32_16x16x32_bf16 v[54:57], v[144:147], v[184:187], v[54:57]
	v_mfma_f32_16x16x32_bf16 v[50:53], v[152:155], v[184:187], v[50:53]
	v_mfma_f32_16x16x32_bf16 v[38:41], v[144:147], v[192:195], v[38:41]
	v_mfma_f32_16x16x32_bf16 v[34:37], v[152:155], v[192:195], v[34:37]
	v_mfma_f32_16x16x32_bf16 v[22:25], v[144:147], v[200:203], v[22:25]
	v_mfma_f32_16x16x32_bf16 v[18:21], v[152:155], v[200:203], v[18:21]
	v_mfma_f32_16x16x32_bf16 v[62:65], v[148:151], v[180:183], v[62:65]
	v_mfma_f32_16x16x32_bf16 v[58:61], v[156:159], v[180:183], v[58:61]
	v_mfma_f32_16x16x32_bf16 v[54:57], v[148:151], v[188:191], v[54:57]
	v_mfma_f32_16x16x32_bf16 v[50:53], v[156:159], v[188:191], v[50:53]
	v_mfma_f32_16x16x32_bf16 v[38:41], v[148:151], v[196:199], v[38:41]
	v_mfma_f32_16x16x32_bf16 v[34:37], v[156:159], v[196:199], v[34:37]
	v_mfma_f32_16x16x32_bf16 v[22:25], v[148:151], v[204:207], v[22:25]
	v_mfma_f32_16x16x32_bf16 v[18:21], v[156:159], v[204:207], v[18:21]
	s_setprio 0
	s_setprio 1
	v_mfma_f32_16x16x32_bf16 v[46:49], v[160:163], v[176:179], v[46:49]
	v_mfma_f32_16x16x32_bf16 v[42:45], v[168:171], v[176:179], v[42:45]
	v_mfma_f32_16x16x32_bf16 v[30:33], v[160:163], v[184:187], v[30:33]
	v_mfma_f32_16x16x32_bf16 v[26:29], v[168:171], v[184:187], v[26:29]
	v_mfma_f32_16x16x32_bf16 v[14:17], v[160:163], v[192:195], v[14:17]
	v_mfma_f32_16x16x32_bf16 v[10:13], v[168:171], v[192:195], v[10:13]
	v_mfma_f32_16x16x32_bf16 v[6:9], v[160:163], v[200:203], v[6:9]
	v_mfma_f32_16x16x32_bf16 v[2:5], v[168:171], v[200:203], v[2:5]
	v_mfma_f32_16x16x32_bf16 v[46:49], v[164:167], v[180:183], v[46:49]
	v_mfma_f32_16x16x32_bf16 v[42:45], v[172:175], v[180:183], v[42:45]
	v_mfma_f32_16x16x32_bf16 v[30:33], v[164:167], v[188:191], v[30:33]
	v_mfma_f32_16x16x32_bf16 v[26:29], v[172:175], v[188:191], v[26:29]
	v_mfma_f32_16x16x32_bf16 v[14:17], v[164:167], v[196:199], v[14:17]
	v_mfma_f32_16x16x32_bf16 v[10:13], v[172:175], v[196:199], v[10:13]
	s_setprio 2
	s_barrier
	v_mfma_f32_16x16x32_bf16 v[6:9], v[164:167], v[204:207], v[6:9]
	v_mfma_f32_16x16x32_bf16 v[2:5], v[172:175], v[204:207], v[2:5]
	s_setprio 0
	s_add_i32 s60, s60, 2
	s_add_u32 s58, s58, 0x100
	s_addc_u32 s59, s59, 0
	s_cmp_gt_u32 s60, 5
	s_mov_b64 s[44:45], s[2:3]
	s_cbranch_scc0 .LBB0_457
	s_and_b64 vcc, exec, s[36:37]
	s_cbranch_vccz .LBB0_460
	s_barrier

; #define PG8_STAGE(bufoff, gbase, voff) do { _Pragma("unroll") for (int _i = 0; _i < 2; ++_i) \
;         __builtin_amdgcn_global_load_lds((const unsigned*)((const char*)(gbase) + (voff)[_i]), (LAS unsigned*)(lds + (bufoff) + ldsw + _i * 8192), 16, 0, 0); } while (0)
; #define PG8_LDA(dst, b, h) do { _Pragma("unroll") for (int m = 0; m < 4; ++m) _Pragma("unroll") for (int k = 0; k < 2; ++k) dst[m][k] = *(const LAS bf16x8*)(lds + PG8_SA(b, h) + aoff + m * 2048 + k * 1024); } while (0)
; #define PG8_LDB(dst, b, h) do { _Pragma("unroll") for (int n = 0; n < 2; ++n) _Pragma("unroll") for (int k = 0; k < 2; ++k) dst[n][k] = *(const LAS bf16x8*)(lds + PG8_SB(b, h) + boff + n * 2048 + k * 1024); } while (0)
; #define PG8_MMA(ai, bj, At, Bt) do { __builtin_amdgcn_s_setprio(1); _Pragma("unroll") for (int m = 0; m < 4; ++m) _Pragma("unroll") for (int n = 0; n < 2; ++n) _Pragma("unroll") for (int k = 0; k < 2; ++k) \
;         acc[ai][bj][m][n] = __builtin_amdgcn_mfma_f32_16x16x32_bf16(Bt[n][k], At[m][k], acc[ai][bj][m][n], 0, 0, 0); __builtin_amdgcn_s_setprio(0); } while (0)
; #define PG8_WAIT_V(n) asm volatile("s_waitcnt vmcnt(" #n ")" ::: "memory")
; #define PG8_WAIT_L(n) asm volatile("s_waitcnt lgkmcnt(" #n ")" ::: "memory")
; #define PG8_BAR __builtin_amdgcn_s_barrier()
; #define PG8_SCHED __builtin_amdgcn_sched_barrier(0)
; template <class Epi>
; __device__ __forceinline__ void gemm_phase(LAS unsigned char* lds, const Gemm g, const TileOrder& S, const Epi& E) {
;     ...
;         for (int t = 0; t < nt; t += 2) {
;             const bool last = (t == nt - 2);
;             const char* a1 = cA + (size_t)(t + 1) * kstepA;
;             const char* a2 = last ? nA : cA + (size_t)(t + 2) * kstepA; const char* b2 = last ? nB : cB + (size_t)(t + 2) * kstep;
;             const char* a3 = a2 + kstepA; const char* b3 = b2 + kstep;
;             PG8_LDB(B0, 0, 0); PG8_LDB(B1, 0, 1); PG8_SCHED; PG8_LDA(At, 0, 0); PG8_STAGE(PG8_SA(1, 1), a1 + hstepA, voffA);
;             PG8_WAIT_V(8); PG8_WAIT_L(0); PG8_BAR; PG8_MMA(0, 0, At, B0); PG8_MMA(0, 1, At, B1); PG8_BAR; PG8_SCHED;
;             PG8_LDA(At, 0, 1); PG8_STAGE(PG8_SB(0, 0), b2, voffB); PG8_STAGE(PG8_SB(0, 1), b2 + hstepB, voffB); PG8_STAGE(PG8_SA(0, 0), a2, voffA);
;             PG8_WAIT_V(8); PG8_WAIT_L(0); PG8_BAR; PG8_MMA(1, 0, At, B0); PG8_MMA(1, 1, At, B1); PG8_BAR; PG8_SCHED;
.LBB0_596:
	s_mov_b32 s6, 0x10000
	s_mov_b32 s12, 0x14000
	v_add_u32_e32 v58, s6, v224
	v_add_u32_e32 v102, s12, v224
	ds_read_b128 v[42:45], v58
	ds_read_b128 v[46:49], v58 offset:1024
	ds_read_b128 v[50:53], v58 offset:2048
	ds_read_b128 v[58:61], v58 offset:3072
	ds_read_b128 v[74:77], v102
	ds_read_b128 v[82:85], v102 offset:1024
	ds_read_b128 v[94:97], v102 offset:2048
	ds_read_b128 v[102:105], v102 offset:3072
	ds_read_b128 v[114:117], v225
	ds_read_b128 v[126:129], v225 offset:1024
	ds_read_b128 v[138:141], v225 offset:2048
	ds_read_b128 v[150:153], v225 offset:3072
	ds_read_b128 v[162:165], v225 offset:4096
	ds_read_b128 v[174:177], v225 offset:5120
	ds_read_b128 v[186:189], v225 offset:6144
	ds_read_b128 v[190:193], v225 offset:7168
	s_add_u32 s2, s28, 0x100
	s_addc_u32 s3, s29, 0
	s_cmp_eq_u32 s62, 8
	s_cselect_b32 s47, s1, s3
	s_cselect_b32 s46, s0, s2
	s_cselect_b32 s31, s45, s61
	s_cselect_b32 s30, s44, s60
	s_add_i32 m0, s26, 0xc000
	s_nop 0
	global_load_lds_dwordx4 v214, s[28:29]
	s_add_i32 m0, s26, 0xe000
	s_nop 0
	global_load_lds_dwordx4 v216, s[28:29]
	s_waitcnt vmcnt(8)
	s_waitcnt lgkmcnt(0)
	s_barrier
	s_setprio 1
	s_waitcnt lgkmcnt(0)
	v_mfma_f32_16x16x32_bf16 v[182:185], v[42:45], v[114:117], v[182:185]
	v_mfma_f32_16x16x32_bf16 v[178:181], v[50:53], v[114:117], v[178:181]
	v_mfma_f32_16x16x32_bf16 v[158:161], v[42:45], v[138:141], v[158:161]
	v_mfma_f32_16x16x32_bf16 v[154:157], v[50:53], v[138:141], v[154:157]
	v_mfma_f32_16x16x32_bf16 v[134:137], v[42:45], v[162:165], v[134:137]
	v_mfma_f32_16x16x32_bf16 v[130:133], v[50:53], v[162:165], v[130:133]
	v_mfma_f32_16x16x32_bf16 v[110:113], v[42:45], v[186:189], v[110:113]
	v_mfma_f32_16x16x32_bf16 v[106:109], v[50:53], v[186:189], v[106:109]
	v_mfma_f32_16x16x32_bf16 v[182:185], v[46:49], v[126:129], v[182:185]
	v_mfma_f32_16x16x32_bf16 v[178:181], v[58:61], v[126:129], v[178:181]
	v_mfma_f32_16x16x32_bf16 v[158:161], v[46:49], v[150:153], v[158:161]
	v_mfma_f32_16x16x32_bf16 v[154:157], v[58:61], v[150:153], v[154:157]
	v_mfma_f32_16x16x32_bf16 v[134:137], v[46:49], v[174:177], v[134:137]
	v_mfma_f32_16x16x32_bf16 v[130:133], v[58:61], v[174:177], v[130:133]
	v_mfma_f32_16x16x32_bf16 v[110:113], v[46:49], v[190:193], v[110:113]
	v_mfma_f32_16x16x32_bf16 v[106:109], v[58:61], v[190:193], v[106:109]
	s_setprio 0
	s_setprio 1
	v_mfma_f32_16x16x32_bf16 v[170:173], v[74:77], v[114:117], v[170:173]
	v_mfma_f32_16x16x32_bf16 v[114:117], v[94:97], v[114:117], v[166:169]
	v_mfma_f32_16x16x32_bf16 v[122:125], v[74:77], v[162:165], v[122:125]
	v_mfma_f32_16x16x32_bf16 v[118:121], v[94:97], v[162:165], v[118:121]
	v_mfma_f32_16x16x32_bf16 v[98:101], v[74:77], v[186:189], v[98:101]
	v_mfma_f32_16x16x32_bf16 v[90:93], v[94:97], v[186:189], v[90:93]
	v_mfma_f32_16x16x32_bf16 v[170:173], v[82:85], v[126:129], v[170:173]
	v_mfma_f32_16x16x32_bf16 v[114:117], v[102:105], v[126:129], v[114:117]
	v_mfma_f32_16x16x32_bf16 v[126:129], v[74:77], v[138:141], v[146:149]
	v_mfma_f32_16x16x32_bf16 v[138:141], v[94:97], v[138:141], v[142:145]
	v_mfma_f32_16x16x32_bf16 v[122:125], v[82:85], v[174:177], v[122:125]
	v_mfma_f32_16x16x32_bf16 v[118:121], v[102:105], v[174:177], v[118:121]
	v_mfma_f32_16x16x32_bf16 v[98:101], v[82:85], v[190:193], v[98:101]
	v_mfma_f32_16x16x32_bf16 v[90:93], v[102:105], v[190:193], v[90:93]
	s_setprio 2
	s_barrier
	v_mfma_f32_16x16x32_bf16 v[126:129], v[82:85], v[150:153], v[126:129]
	ds_read_b128 v[142:145], v225 offset:16384
	ds_read_b128 v[146:149], v225 offset:17408
	v_mfma_f32_16x16x32_bf16 v[138:141], v[102:105], v[150:153], v[138:141]
	s_setprio 0
	s_add_i32 s6, s6, s25
	v_lshl_add_u64 v[198:199], s[30:31], 0, v[0:1]
	s_mov_b32 m0, s6
	ds_read_b128 v[150:153], v225 offset:18432
	ds_read_b128 v[162:165], v225 offset:19456
	ds_read_b128 v[166:169], v225 offset:20480
	ds_read_b128 v[174:177], v225 offset:21504
	ds_read_b128 v[186:189], v225 offset:22528
	ds_read_b128 v[190:193], v225 offset:23552
	global_load_lds_dwordx4 v[198:199], off
	s_add_i32 m0, s6, 0x2000
	s_add_u32 s14, s30, 0x30000
	v_lshl_add_u64 v[200:201], s[30:31], 0, v[208:209]
	s_addc_u32 s15, s31, 0
	s_add_i32 s6, s12, s25
	global_load_lds_dwordx4 v[200:201], off
	s_mov_b32 m0, s6
	v_lshl_add_u64 v[202:203], s[46:47], 0, v[212:213]
	global_load_lds_dwordx4 v0, s[14:15]
	v_lshl_add_u64 v[194:195], s[14:15], 0, v[208:209]
	s_add_i32 m0, s6, 0x2000
	v_lshl_add_u64 v[204:205], s[46:47], 0, v[210:211]
	global_load_lds_dwordx4 v[194:195], off
	s_mov_b32 m0, s26
	s_nop 0
	global_load_lds_dwordx4 v[202:203], off
	s_mov_b32 m0, s48
	s_nop 0
	global_load_lds_dwordx4 v[204:205], off
	s_waitcnt vmcnt(8)
	s_waitcnt lgkmcnt(0)
	s_barrier
; #define PG8_STAGE(bufoff, gbase, voff) do { _Pragma("unroll") for (int _i = 0; _i < 2; ++_i) \
;         __builtin_amdgcn_global_load_lds((const unsigned*)((const char*)(gbase) + (voff)[_i]), (LAS unsigned*)(lds + (bufoff) + ldsw + _i * 8192), 16, 0, 0); } while (0)
; #define PG8_LDA(dst, b, h) do { _Pragma("unroll") for (int m = 0; m < 4; ++m) _Pragma("unroll") for (int k = 0; k < 2; ++k) dst[m][k] = *(const LAS bf16x8*)(lds + PG8_SA(b, h) + aoff + m * 2048 + k * 1024); } while (0)
; #define PG8_LDB(dst, b, h) do { _Pragma("unroll") for (int n = 0; n < 2; ++n) _Pragma("unroll") for (int k = 0; k < 2; ++k) dst[n][k] = *(const LAS bf16x8*)(lds + PG8_SB(b, h) + boff + n * 2048 + k * 1024); } while (0)
; #define PG8_MMA(ai, bj, At, Bt) do { __builtin_amdgcn_s_setprio(1); _Pragma("unroll") for (int m = 0; m < 4; ++m) _Pragma("unroll") for (int n = 0; n < 2; ++n) _Pragma("unroll") for (int k = 0; k < 2; ++k) \
;         acc[ai][bj][m][n] = __builtin_amdgcn_mfma_f32_16x16x32_bf16(Bt[n][k], At[m][k], acc[ai][bj][m][n], 0, 0, 0); __builtin_amdgcn_s_setprio(0); } while (0)
; #define PG8_WAIT_V(n) asm volatile("s_waitcnt vmcnt(" #n ")" ::: "memory")
; #define PG8_WAIT_L(n) asm volatile("s_waitcnt lgkmcnt(" #n ")" ::: "memory")
; #define PG8_BAR __builtin_amdgcn_s_barrier()
; #define PG8_SCHED __builtin_amdgcn_sched_barrier(0)
; template <class Epi>
; __device__ __forceinline__ void gemm_phase(LAS unsigned char* lds, const Gemm g, const TileOrder& S, const Epi& E) {
;     ...
;             PG8_WAIT_V(8); PG8_WAIT_L(0); PG8_BAR; PG8_MMA(1, 0, At, B0); PG8_MMA(1, 1, At, B1); PG8_BAR; PG8_SCHED;
;             PG8_LDB(B0, 1, 0); PG8_LDB(B1, 1, 1); PG8_SCHED; PG8_LDA(At, 1, 0); PG8_STAGE(PG8_SA(0, 1), a2 + hstepA, voffA);
;             PG8_WAIT_V(8); PG8_WAIT_L(0); PG8_BAR; PG8_MMA(0, 0, At, B0); PG8_MMA(0, 1, At, B1); PG8_BAR; PG8_SCHED;
	s_setprio 1
	s_waitcnt lgkmcnt(0)
	v_mfma_f32_16x16x32_bf16 v[86:89], v[42:45], v[142:145], v[86:89]
	v_mfma_f32_16x16x32_bf16 v[78:81], v[50:53], v[142:145], v[78:81]
	v_mfma_f32_16x16x32_bf16 v[62:65], v[42:45], v[150:153], v[62:65]
	v_mfma_f32_16x16x32_bf16 v[54:57], v[50:53], v[150:153], v[54:57]
	v_mfma_f32_16x16x32_bf16 v[30:33], v[42:45], v[166:169], v[30:33]
	v_mfma_f32_16x16x32_bf16 v[26:29], v[50:53], v[166:169], v[26:29]
	v_mfma_f32_16x16x32_bf16 v[14:17], v[42:45], v[186:189], v[14:17]
	v_mfma_f32_16x16x32_bf16 v[10:13], v[50:53], v[186:189], v[10:13]
	v_mfma_f32_16x16x32_bf16 v[86:89], v[46:49], v[146:149], v[86:89]
	v_mfma_f32_16x16x32_bf16 v[78:81], v[58:61], v[146:149], v[78:81]
	v_mfma_f32_16x16x32_bf16 v[62:65], v[46:49], v[162:165], v[62:65]
	v_mfma_f32_16x16x32_bf16 v[54:57], v[58:61], v[162:165], v[54:57]
	v_mfma_f32_16x16x32_bf16 v[30:33], v[46:49], v[174:177], v[30:33]
	v_mfma_f32_16x16x32_bf16 v[26:29], v[58:61], v[174:177], v[26:29]
	v_mfma_f32_16x16x32_bf16 v[14:17], v[46:49], v[190:193], v[14:17]
	v_mfma_f32_16x16x32_bf16 v[10:13], v[58:61], v[190:193], v[10:13]
	s_setprio 0
	s_setprio 1
	v_mfma_f32_16x16x32_bf16 v[38:41], v[74:77], v[150:153], v[38:41]
	v_mfma_f32_16x16x32_bf16 v[34:37], v[94:97], v[150:153], v[34:37]
	v_mfma_f32_16x16x32_bf16 v[22:25], v[74:77], v[166:169], v[22:25]
	v_mfma_f32_16x16x32_bf16 v[18:21], v[94:97], v[166:169], v[18:21]
	v_mfma_f32_16x16x32_bf16 v[6:9], v[74:77], v[186:189], v[6:9]
	v_mfma_f32_16x16x32_bf16 v[2:5], v[94:97], v[186:189], v[2:5]
	v_mfma_f32_16x16x32_bf16 v[42:45], v[74:77], v[142:145], v[70:73]
	v_mfma_f32_16x16x32_bf16 v[46:49], v[94:97], v[142:145], v[66:69]
	v_mfma_f32_16x16x32_bf16 v[38:41], v[82:85], v[162:165], v[38:41]
	v_mfma_f32_16x16x32_bf16 v[34:37], v[102:105], v[162:165], v[34:37]
	v_mfma_f32_16x16x32_bf16 v[22:25], v[82:85], v[174:177], v[22:25]
	v_mfma_f32_16x16x32_bf16 v[18:21], v[102:105], v[174:177], v[18:21]
	v_mfma_f32_16x16x32_bf16 v[6:9], v[82:85], v[190:193], v[6:9]
	v_mfma_f32_16x16x32_bf16 v[2:5], v[102:105], v[190:193], v[2:5]
	s_setprio 2
	s_barrier
	v_mfma_f32_16x16x32_bf16 v[42:45], v[82:85], v[146:149], v[42:45]
	s_mov_b32 s6, 0x18000
	s_mov_b32 s12, 0x1c000
	v_add_u32_e32 v70, s6, v224
	ds_read_b128 v[50:53], v70
	ds_read_b128 v[58:61], v70 offset:1024
	ds_read_b128 v[66:69], v70 offset:2048
	v_mfma_f32_16x16x32_bf16 v[46:49], v[102:105], v[146:149], v[46:49]
	s_setprio 0
	v_add_u32_e32 v102, s12, v224
	ds_read_b128 v[70:73], v70 offset:3072
	ds_read_b128 v[74:77], v102
	ds_read_b128 v[82:85], v102 offset:1024
	ds_read_b128 v[94:97], v102 offset:2048
	ds_read_b128 v[102:105], v102 offset:3072
	s_add_u32 s14, s46, 0x30000
	s_addc_u32 s15, s47, 0
	s_mov_b32 m0, s49
	ds_read_b128 v[142:145], v225 offset:32768
	ds_read_b128 v[146:149], v225 offset:33792
	ds_read_b128 v[150:153], v225 offset:34816
	ds_read_b128 v[162:165], v225 offset:35840
	ds_read_b128 v[174:177], v225 offset:36864
	ds_read_b128 v[186:189], v225 offset:37888
	ds_read_b128 v[190:193], v225 offset:38912
	ds_read_b128 v[194:197], v225 offset:39936
	global_load_lds_dwordx4 v212, s[14:15]
	s_mov_b32 m0, s50
	s_nop 0
	global_load_lds_dwordx4 v210, s[14:15]
	s_waitcnt vmcnt(8)
	s_waitcnt lgkmcnt(0)
	s_barrier
	s_setprio 1
	s_waitcnt lgkmcnt(0)
	v_mfma_f32_16x16x32_bf16 v[166:169], v[50:53], v[142:145], v[182:185]
	v_mfma_f32_16x16x32_bf16 v[182:185], v[58:61], v[146:149], v[166:169]
	v_mfma_f32_16x16x32_bf16 v[166:169], v[66:69], v[142:145], v[178:181]
	v_mfma_f32_16x16x32_bf16 v[158:161], v[50:53], v[150:153], v[158:161]
	v_mfma_f32_16x16x32_bf16 v[154:157], v[66:69], v[150:153], v[154:157]
	v_mfma_f32_16x16x32_bf16 v[134:137], v[50:53], v[174:177], v[134:137]
	v_mfma_f32_16x16x32_bf16 v[130:133], v[66:69], v[174:177], v[130:133]
	v_mfma_f32_16x16x32_bf16 v[110:113], v[50:53], v[190:193], v[110:113]
	v_mfma_f32_16x16x32_bf16 v[106:109], v[66:69], v[190:193], v[106:109]
	v_mfma_f32_16x16x32_bf16 v[178:181], v[70:73], v[146:149], v[166:169]
	v_mfma_f32_16x16x32_bf16 v[158:161], v[58:61], v[162:165], v[158:161]
	v_mfma_f32_16x16x32_bf16 v[154:157], v[70:73], v[162:165], v[154:157]
	v_mfma_f32_16x16x32_bf16 v[134:137], v[58:61], v[186:189], v[134:137]
	v_mfma_f32_16x16x32_bf16 v[130:133], v[70:73], v[186:189], v[130:133]
	v_mfma_f32_16x16x32_bf16 v[110:113], v[58:61], v[194:197], v[110:113]
	v_mfma_f32_16x16x32_bf16 v[106:109], v[70:73], v[194:197], v[106:109]
	s_setprio 0
	s_setprio 1
	v_mfma_f32_16x16x32_bf16 v[166:169], v[74:77], v[142:145], v[170:173]
	v_mfma_f32_16x16x32_bf16 v[114:117], v[94:97], v[142:145], v[114:117]
	v_mfma_f32_16x16x32_bf16 v[170:173], v[82:85], v[146:149], v[166:169]
	v_mfma_f32_16x16x32_bf16 v[166:169], v[102:105], v[146:149], v[114:117]
	v_mfma_f32_16x16x32_bf16 v[114:117], v[74:77], v[150:153], v[126:129]
	v_mfma_f32_16x16x32_bf16 v[146:149], v[82:85], v[162:165], v[114:117]
	v_mfma_f32_16x16x32_bf16 v[114:117], v[94:97], v[150:153], v[138:141]
	v_mfma_f32_16x16x32_bf16 v[142:145], v[102:105], v[162:165], v[114:117]
	v_mfma_f32_16x16x32_bf16 v[114:117], v[74:77], v[174:177], v[122:125]
	v_mfma_f32_16x16x32_bf16 v[122:125], v[82:85], v[186:189], v[114:117]
	v_mfma_f32_16x16x32_bf16 v[114:117], v[94:97], v[174:177], v[118:121]
	v_mfma_f32_16x16x32_bf16 v[98:101], v[74:77], v[190:193], v[98:101]
	v_mfma_f32_16x16x32_bf16 v[90:93], v[94:97], v[190:193], v[90:93]
	v_mfma_f32_16x16x32_bf16 v[118:121], v[102:105], v[186:189], v[114:117]
	s_setprio 2
	s_barrier
; #define PG8_STAGE(bufoff, gbase, voff) do { _Pragma("unroll") for (int _i = 0; _i < 2; ++_i) \
;         __builtin_amdgcn_global_load_lds((const unsigned*)((const char*)(gbase) + (voff)[_i]), (LAS unsigned*)(lds + (bufoff) + ldsw + _i * 8192), 16, 0, 0); } while (0)
; #define PG8_LDA(dst, b, h) do { _Pragma("unroll") for (int m = 0; m < 4; ++m) _Pragma("unroll") for (int k = 0; k < 2; ++k) dst[m][k] = *(const LAS bf16x8*)(lds + PG8_SA(b, h) + aoff + m * 2048 + k * 1024); } while (0)
; #define PG8_MMA(ai, bj, At, Bt) do { __builtin_amdgcn_s_setprio(1); _Pragma("unroll") for (int m = 0; m < 4; ++m) _Pragma("unroll") for (int n = 0; n < 2; ++n) _Pragma("unroll") for (int k = 0; k < 2; ++k) \
;         acc[ai][bj][m][n] = __builtin_amdgcn_mfma_f32_16x16x32_bf16(Bt[n][k], At[m][k], acc[ai][bj][m][n], 0, 0, 0); __builtin_amdgcn_s_setprio(0); } while (0)
; #define PG8_WAIT_V(n) asm volatile("s_waitcnt vmcnt(" #n ")" ::: "memory")
; #define PG8_WAIT_L(n) asm volatile("s_waitcnt lgkmcnt(" #n ")" ::: "memory")
; #define PG8_BAR __builtin_amdgcn_s_barrier()
; #define PG8_SCHED __builtin_amdgcn_sched_barrier(0)
; template <class Epi>
; __device__ __forceinline__ void gemm_phase(LAS unsigned char* lds, const Gemm g, const TileOrder& S, const Epi& E) {
;     ...
;             PG8_WAIT_V(8); PG8_WAIT_L(0); PG8_BAR; PG8_MMA(0, 0, At, B0); PG8_MMA(0, 1, At, B1); PG8_BAR; PG8_SCHED;
;             PG8_LDA(At, 1, 1); PG8_STAGE(PG8_SB(1, 0), b3, voffB); PG8_STAGE(PG8_SB(1, 1), b3 + hstepB, voffB); PG8_STAGE(PG8_SA(1, 0), a3, voffA);
;             PG8_WAIT_V(8); PG8_WAIT_L(0); PG8_BAR; PG8_MMA(1, 0, At, B0); PG8_MMA(1, 1, At, B1); PG8_BAR; PG8_SCHED;
;         }
;         if (wr == 0) PG8_BAR;
	v_mfma_f32_16x16x32_bf16 v[98:101], v[82:85], v[194:197], v[98:101]
	ds_read_b128 v[114:117], v225 offset:49152
	ds_read_b128 v[126:129], v225 offset:50176
	ds_read_b128 v[138:141], v225 offset:51200
	v_mfma_f32_16x16x32_bf16 v[90:93], v[102:105], v[194:197], v[90:93]
	s_setprio 0
	s_add_i32 s6, s6, s25
	v_lshl_add_u64 v[194:195], v[198:199], 0, s[34:35]
	s_mov_b32 m0, s6
	ds_read_b128 v[150:153], v225 offset:52224
	ds_read_b128 v[162:165], v225 offset:53248
	ds_read_b128 v[174:177], v225 offset:54272
	ds_read_b128 v[186:189], v225 offset:55296
	ds_read_b128 v[190:193], v225 offset:56320
	global_load_lds_dwordx4 v[194:195], off
	s_add_i32 m0, s6, 0x2000
	s_add_u32 s14, s30, 0x30080
	v_lshl_add_u64 v[194:195], v[200:201], 0, s[34:35]
	s_addc_u32 s15, s31, 0
	s_add_i32 s6, s12, s25
	global_load_lds_dwordx4 v[194:195], off
	s_mov_b32 m0, s6
	s_nop 0
	global_load_lds_dwordx4 v0, s[14:15]
	v_lshl_add_u64 v[194:195], s[14:15], 0, v[208:209]
	s_add_i32 m0, s6, 0x2000
	s_nop 0
	global_load_lds_dwordx4 v[194:195], off
	v_lshl_add_u64 v[194:195], v[202:203], 0, s[34:35]
	s_mov_b32 m0, s51
	s_nop 0
	global_load_lds_dwordx4 v[194:195], off
	v_lshl_add_u64 v[194:195], v[204:205], 0, s[34:35]
	s_mov_b32 m0, s52
	s_nop 0
	global_load_lds_dwordx4 v[194:195], off
	s_waitcnt vmcnt(8)
	s_waitcnt lgkmcnt(0)
	s_barrier
	s_setprio 1
	s_waitcnt lgkmcnt(0)
	v_mfma_f32_16x16x32_bf16 v[86:89], v[50:53], v[114:117], v[86:89]
	v_mfma_f32_16x16x32_bf16 v[78:81], v[66:69], v[114:117], v[78:81]
	v_mfma_f32_16x16x32_bf16 v[62:65], v[50:53], v[138:141], v[62:65]
	v_mfma_f32_16x16x32_bf16 v[54:57], v[66:69], v[138:141], v[54:57]
	v_mfma_f32_16x16x32_bf16 v[30:33], v[50:53], v[162:165], v[30:33]
	v_mfma_f32_16x16x32_bf16 v[26:29], v[66:69], v[162:165], v[26:29]
	v_mfma_f32_16x16x32_bf16 v[14:17], v[50:53], v[186:189], v[14:17]
	v_mfma_f32_16x16x32_bf16 v[10:13], v[66:69], v[186:189], v[10:13]
	v_mfma_f32_16x16x32_bf16 v[86:89], v[58:61], v[126:129], v[86:89]
	v_mfma_f32_16x16x32_bf16 v[78:81], v[70:73], v[126:129], v[78:81]
	v_mfma_f32_16x16x32_bf16 v[62:65], v[58:61], v[150:153], v[62:65]
	v_mfma_f32_16x16x32_bf16 v[54:57], v[70:73], v[150:153], v[54:57]
	v_mfma_f32_16x16x32_bf16 v[30:33], v[58:61], v[174:177], v[30:33]
	v_mfma_f32_16x16x32_bf16 v[26:29], v[70:73], v[174:177], v[26:29]
	v_mfma_f32_16x16x32_bf16 v[14:17], v[58:61], v[190:193], v[14:17]
	v_mfma_f32_16x16x32_bf16 v[10:13], v[70:73], v[190:193], v[10:13]
	s_setprio 0
	s_setprio 1
	v_mfma_f32_16x16x32_bf16 v[42:45], v[74:77], v[114:117], v[42:45]
	v_mfma_f32_16x16x32_bf16 v[70:73], v[82:85], v[126:129], v[42:45]
	v_mfma_f32_16x16x32_bf16 v[42:45], v[94:97], v[114:117], v[46:49]
	v_mfma_f32_16x16x32_bf16 v[38:41], v[74:77], v[138:141], v[38:41]
	v_mfma_f32_16x16x32_bf16 v[34:37], v[94:97], v[138:141], v[34:37]
	v_mfma_f32_16x16x32_bf16 v[22:25], v[74:77], v[162:165], v[22:25]
	v_mfma_f32_16x16x32_bf16 v[18:21], v[94:97], v[162:165], v[18:21]
	v_mfma_f32_16x16x32_bf16 v[6:9], v[74:77], v[186:189], v[6:9]
	v_mfma_f32_16x16x32_bf16 v[2:5], v[94:97], v[186:189], v[2:5]
	v_mfma_f32_16x16x32_bf16 v[66:69], v[102:105], v[126:129], v[42:45]
	v_mfma_f32_16x16x32_bf16 v[38:41], v[82:85], v[150:153], v[38:41]
	v_mfma_f32_16x16x32_bf16 v[34:37], v[102:105], v[150:153], v[34:37]
	v_mfma_f32_16x16x32_bf16 v[22:25], v[82:85], v[174:177], v[22:25]
	v_mfma_f32_16x16x32_bf16 v[18:21], v[102:105], v[174:177], v[18:21]
	s_setprio 2
	s_barrier
	v_mfma_f32_16x16x32_bf16 v[6:9], v[82:85], v[190:193], v[6:9]
	v_mfma_f32_16x16x32_bf16 v[2:5], v[102:105], v[190:193], v[2:5]
	s_setprio 0
	s_add_i32 s62, s62, 2
	s_add_u32 s60, s60, 0x100
	s_addc_u32 s61, s61, 0
	s_cmp_gt_u32 s62, 9
	s_mov_b64 s[28:29], s[2:3]
	s_cbranch_scc0 .LBB0_596
	s_and_b64 vcc, exec, s[42:43]
	s_cbranch_vccz .LBB0_599
	s_barrier

; #define PG8_STAGE(bufoff, gbase, voff) do { _Pragma("unroll") for (int _i = 0; _i < 2; ++_i) \
;         __builtin_amdgcn_global_load_lds((const unsigned*)((const char*)(gbase) + (voff)[_i]), (LAS unsigned*)(lds + (bufoff) + ldsw + _i * 8192), 16, 0, 0); } while (0)
; #define PG8_LDA(dst, b, h) do { _Pragma("unroll") for (int m = 0; m < 4; ++m) _Pragma("unroll") for (int k = 0; k < 2; ++k) dst[m][k] = *(const LAS bf16x8*)(lds + PG8_SA(b, h) + aoff + m * 2048 + k * 1024); } while (0)
; #define PG8_LDB(dst, b, h) do { _Pragma("unroll") for (int n = 0; n < 2; ++n) _Pragma("unroll") for (int k = 0; k < 2; ++k) dst[n][k] = *(const LAS bf16x8*)(lds + PG8_SB(b, h) + boff + n * 2048 + k * 1024); } while (0)
; #define PG8_MMA(ai, bj, At, Bt) do { __builtin_amdgcn_s_setprio(1); _Pragma("unroll") for (int m = 0; m < 4; ++m) _Pragma("unroll") for (int n = 0; n < 2; ++n) _Pragma("unroll") for (int k = 0; k < 2; ++k) \
;         acc[ai][bj][m][n] = __builtin_amdgcn_mfma_f32_16x16x32_bf16(Bt[n][k], At[m][k], acc[ai][bj][m][n], 0, 0, 0); __builtin_amdgcn_s_setprio(0); } while (0)
; #define PG8_WAIT_V(n) asm volatile("s_waitcnt vmcnt(" #n ")" ::: "memory")
; #define PG8_WAIT_L(n) asm volatile("s_waitcnt lgkmcnt(" #n ")" ::: "memory")
; template <class Epi>
; __device__ __forceinline__ void gemm_phase(LAS unsigned char* lds, const Gemm g, const TileOrder& S, const Epi& E) {
;     ...
;         const bool has_next = S.next(ui + 1, nxt);
;         const char* nA = has_next ? (const char*)g.A + (size_t)nxt.pm * tstepA : cA; const char* nB = has_next ? (const char*)g.Bt + (size_t)nxt.pb * tstepB : cB;
;         for (int t = 0; t < nt; t += 2) {
;             const bool last = (t == nt - 2);
;             const char* a1 = cA + (size_t)(t + 1) * kstepA;
;             const char* a2 = last ? nA : cA + (size_t)(t + 2) * kstepA; const char* b2 = last ? nB : cB + (size_t)(t + 2) * kstep;
;             const char* a3 = a2 + kstepA; const char* b3 = b2 + kstep;
;             PG8_LDB(B0, 0, 0); PG8_LDB(B1, 0, 1); PG8_SCHED; PG8_LDA(At, 0, 0); PG8_STAGE(PG8_SA(1, 1), a1 + hstepA, voffA);
;             PG8_WAIT_V(8); PG8_WAIT_L(0); PG8_BAR; PG8_MMA(0, 0, At, B0); PG8_MMA(0, 1, At, B1); PG8_BAR; PG8_SCHED;
;             PG8_LDA(At, 0, 1); PG8_STAGE(PG8_SB(0, 0), b2, voffB); PG8_STAGE(PG8_SB(0, 1), b2 + hstepB, voffB); PG8_STAGE(PG8_SA(0, 0), a2, voffA);
.LBB0_668:
	s_mov_b32 s6, 0x10000
	s_mov_b32 s12, 0x14000
	v_add_u32_e32 v142, s6, v184
	v_add_u32_e32 v168, s12, v184
	ds_read_b128 v[130:133], v142
	ds_read_b128 v[134:137], v142 offset:1024
	ds_read_b128 v[138:141], v142 offset:2048
	ds_read_b128 v[142:145], v142 offset:3072
	ds_read_b128 v[146:149], v168
	ds_read_b128 v[150:153], v168 offset:1024
	ds_read_b128 v[164:167], v168 offset:2048
	ds_read_b128 v[168:171], v168 offset:3072
	ds_read_b128 v[172:175], v185
	ds_read_b128 v[176:179], v185 offset:1024
	ds_read_b128 v[186:189], v185 offset:2048
	ds_read_b128 v[190:193], v185 offset:3072
	ds_read_b128 v[194:197], v185 offset:4096
	ds_read_b128 v[198:201], v185 offset:5120
	ds_read_b128 v[202:205], v185 offset:6144
	ds_read_b128 v[206:209], v185 offset:7168
	s_add_u32 s2, s4, 0xfff80080
	s_addc_u32 s3, s5, -1
	s_cmp_eq_u32 s66, 28
	s_cselect_b32 s29, s45, s3
	s_cselect_b32 s28, s62, s2
	s_cselect_b32 s3, s43, s65
	s_cselect_b32 s2, s63, s64
	s_add_i32 m0, s50, 0xc000
	s_nop 0
	global_load_lds_dwordx4 v160, s[4:5]
	s_add_i32 m0, s50, 0xe000
	s_nop 0
	global_load_lds_dwordx4 v162, s[4:5]
	s_waitcnt vmcnt(8)
	s_waitcnt lgkmcnt(0)
	s_barrier
	s_setprio 1
	s_waitcnt lgkmcnt(0)
	v_mfma_f32_16x16x32_bf16 v[122:125], v[130:133], v[172:175], v[122:125]
	v_mfma_f32_16x16x32_bf16 v[118:121], v[138:141], v[172:175], v[118:121]
	v_mfma_f32_16x16x32_bf16 v[110:113], v[130:133], v[186:189], v[110:113]
	v_mfma_f32_16x16x32_bf16 v[102:105], v[138:141], v[186:189], v[102:105]
	v_mfma_f32_16x16x32_bf16 v[94:97], v[130:133], v[194:197], v[94:97]
	v_mfma_f32_16x16x32_bf16 v[86:89], v[138:141], v[194:197], v[86:89]
	v_mfma_f32_16x16x32_bf16 v[78:81], v[130:133], v[202:205], v[78:81]
	v_mfma_f32_16x16x32_bf16 v[70:73], v[138:141], v[202:205], v[70:73]
	v_mfma_f32_16x16x32_bf16 v[122:125], v[134:137], v[176:179], v[122:125]
	v_mfma_f32_16x16x32_bf16 v[118:121], v[142:145], v[176:179], v[118:121]
	v_mfma_f32_16x16x32_bf16 v[110:113], v[134:137], v[190:193], v[110:113]
	v_mfma_f32_16x16x32_bf16 v[102:105], v[142:145], v[190:193], v[102:105]
	v_mfma_f32_16x16x32_bf16 v[94:97], v[134:137], v[198:201], v[94:97]
	v_mfma_f32_16x16x32_bf16 v[86:89], v[142:145], v[198:201], v[86:89]
	v_mfma_f32_16x16x32_bf16 v[78:81], v[134:137], v[206:209], v[78:81]
	v_mfma_f32_16x16x32_bf16 v[70:73], v[142:145], v[206:209], v[70:73]
	s_setprio 0
	s_setprio 1
	v_mfma_f32_16x16x32_bf16 v[114:117], v[146:149], v[172:175], v[114:117]
	v_mfma_f32_16x16x32_bf16 v[126:129], v[164:167], v[172:175], v[126:129]
	v_mfma_f32_16x16x32_bf16 v[106:109], v[146:149], v[186:189], v[106:109]
	v_mfma_f32_16x16x32_bf16 v[98:101], v[164:167], v[186:189], v[98:101]
	v_mfma_f32_16x16x32_bf16 v[90:93], v[146:149], v[194:197], v[90:93]
	v_mfma_f32_16x16x32_bf16 v[82:85], v[164:167], v[194:197], v[82:85]
	v_mfma_f32_16x16x32_bf16 v[74:77], v[146:149], v[202:205], v[74:77]
	v_mfma_f32_16x16x32_bf16 v[66:69], v[164:167], v[202:205], v[66:69]
	v_mfma_f32_16x16x32_bf16 v[114:117], v[150:153], v[176:179], v[114:117]
	v_mfma_f32_16x16x32_bf16 v[126:129], v[168:171], v[176:179], v[126:129]
	v_mfma_f32_16x16x32_bf16 v[106:109], v[150:153], v[190:193], v[106:109]
	v_mfma_f32_16x16x32_bf16 v[98:101], v[168:171], v[190:193], v[98:101]
	v_mfma_f32_16x16x32_bf16 v[90:93], v[150:153], v[198:201], v[90:93]
	v_mfma_f32_16x16x32_bf16 v[82:85], v[168:171], v[198:201], v[82:85]
	s_setprio 2
	s_barrier
	v_mfma_f32_16x16x32_bf16 v[74:77], v[150:153], v[206:209], v[74:77]
	ds_read_b128 v[172:175], v185 offset:16384
	ds_read_b128 v[176:179], v185 offset:17408
	ds_read_b128 v[186:189], v185 offset:18432
	v_mfma_f32_16x16x32_bf16 v[66:69], v[168:171], v[206:209], v[66:69]
	s_setprio 0
	s_add_i32 s6, s6, s31
	v_lshl_add_u64 v[180:181], s[2:3], 0, v[0:1]
	s_mov_b32 m0, s6
	ds_read_b128 v[190:193], v185 offset:19456
	ds_read_b128 v[194:197], v185 offset:20480
	ds_read_b128 v[198:201], v185 offset:21504
	ds_read_b128 v[202:205], v185 offset:22528
	ds_read_b128 v[206:209], v185 offset:23552
	global_load_lds_dwordx4 v[180:181], off
	s_add_i32 m0, s6, 0x2000
	s_add_u32 s14, s2, 0x80000
	v_lshl_add_u64 v[210:211], s[2:3], 0, v[154:155]
	s_addc_u32 s15, s3, 0
	s_add_i32 s6, s12, s31
	global_load_lds_dwordx4 v[210:211], off
	s_mov_b32 m0, s6
	v_lshl_add_u64 v[214:215], s[28:29], 0, v[156:157]
	global_load_lds_dwordx4 v0, s[14:15]
	s_add_i32 m0, s6, 0x2000
	s_nop 0
	global_load_lds_dwordx4 v154, s[14:15]
	v_lshl_add_u64 v[212:213], s[28:29], 0, v[158:159]
	s_mov_b32 m0, s50
	s_nop 0
	global_load_lds_dwordx4 v[212:213], off
	s_mov_b32 m0, s51
	s_nop 0
	global_load_lds_dwordx4 v[214:215], off
	s_waitcnt vmcnt(8)
	s_waitcnt lgkmcnt(0)
	s_barrier
; #define PG8_STAGE(bufoff, gbase, voff) do { _Pragma("unroll") for (int _i = 0; _i < 2; ++_i) \
;         __builtin_amdgcn_global_load_lds((const unsigned*)((const char*)(gbase) + (voff)[_i]), (LAS unsigned*)(lds + (bufoff) + ldsw + _i * 8192), 16, 0, 0); } while (0)
; #define PG8_LDA(dst, b, h) do { _Pragma("unroll") for (int m = 0; m < 4; ++m) _Pragma("unroll") for (int k = 0; k < 2; ++k) dst[m][k] = *(const LAS bf16x8*)(lds + PG8_SA(b, h) + aoff + m * 2048 + k * 1024); } while (0)
; #define PG8_LDB(dst, b, h) do { _Pragma("unroll") for (int n = 0; n < 2; ++n) _Pragma("unroll") for (int k = 0; k < 2; ++k) dst[n][k] = *(const LAS bf16x8*)(lds + PG8_SB(b, h) + boff + n * 2048 + k * 1024); } while (0)
; #define PG8_MMA(ai, bj, At, Bt) do { __builtin_amdgcn_s_setprio(1); _Pragma("unroll") for (int m = 0; m < 4; ++m) _Pragma("unroll") for (int n = 0; n < 2; ++n) _Pragma("unroll") for (int k = 0; k < 2; ++k) \
;         acc[ai][bj][m][n] = __builtin_amdgcn_mfma_f32_16x16x32_bf16(Bt[n][k], At[m][k], acc[ai][bj][m][n], 0, 0, 0); __builtin_amdgcn_s_setprio(0); } while (0)
; #define PG8_WAIT_V(n) asm volatile("s_waitcnt vmcnt(" #n ")" ::: "memory")
; #define PG8_WAIT_L(n) asm volatile("s_waitcnt lgkmcnt(" #n ")" ::: "memory")
; #define PG8_BAR __builtin_amdgcn_s_barrier()
; #define PG8_SCHED __builtin_amdgcn_sched_barrier(0)
; template <class Epi>
; __device__ __forceinline__ void gemm_phase(LAS unsigned char* lds, const Gemm g, const TileOrder& S, const Epi& E) {
;     ...
;             PG8_WAIT_V(8); PG8_WAIT_L(0); PG8_BAR; PG8_MMA(1, 0, At, B0); PG8_MMA(1, 1, At, B1); PG8_BAR; PG8_SCHED;
;             PG8_LDB(B0, 1, 0); PG8_LDB(B1, 1, 1); PG8_SCHED; PG8_LDA(At, 1, 0); PG8_STAGE(PG8_SA(0, 1), a2 + hstepA, voffA);
;             PG8_WAIT_V(8); PG8_WAIT_L(0); PG8_BAR; PG8_MMA(0, 0, At, B0); PG8_MMA(0, 1, At, B1); PG8_BAR; PG8_SCHED;
	s_setprio 1
	s_waitcnt lgkmcnt(0)
	v_mfma_f32_16x16x32_bf16 v[62:65], v[130:133], v[172:175], v[62:65]
	v_mfma_f32_16x16x32_bf16 v[54:57], v[138:141], v[172:175], v[54:57]
	v_mfma_f32_16x16x32_bf16 v[46:49], v[130:133], v[186:189], v[46:49]
	v_mfma_f32_16x16x32_bf16 v[38:41], v[138:141], v[186:189], v[38:41]
	v_mfma_f32_16x16x32_bf16 v[30:33], v[130:133], v[194:197], v[30:33]
	v_mfma_f32_16x16x32_bf16 v[22:25], v[138:141], v[194:197], v[22:25]
	v_mfma_f32_16x16x32_bf16 v[14:17], v[130:133], v[202:205], v[14:17]
	v_mfma_f32_16x16x32_bf16 v[6:9], v[138:141], v[202:205], v[6:9]
	v_mfma_f32_16x16x32_bf16 v[62:65], v[134:137], v[176:179], v[62:65]
	v_mfma_f32_16x16x32_bf16 v[54:57], v[142:145], v[176:179], v[54:57]
	v_mfma_f32_16x16x32_bf16 v[46:49], v[134:137], v[190:193], v[46:49]
	v_mfma_f32_16x16x32_bf16 v[38:41], v[142:145], v[190:193], v[38:41]
	v_mfma_f32_16x16x32_bf16 v[30:33], v[134:137], v[198:201], v[30:33]
	v_mfma_f32_16x16x32_bf16 v[22:25], v[142:145], v[198:201], v[22:25]
	v_mfma_f32_16x16x32_bf16 v[14:17], v[134:137], v[206:209], v[14:17]
	v_mfma_f32_16x16x32_bf16 v[6:9], v[142:145], v[206:209], v[6:9]
	s_setprio 0
	s_setprio 1
	v_mfma_f32_16x16x32_bf16 v[58:61], v[146:149], v[172:175], v[58:61]
	v_mfma_f32_16x16x32_bf16 v[50:53], v[164:167], v[172:175], v[50:53]
	v_mfma_f32_16x16x32_bf16 v[42:45], v[146:149], v[186:189], v[42:45]
	v_mfma_f32_16x16x32_bf16 v[34:37], v[164:167], v[186:189], v[34:37]
	v_mfma_f32_16x16x32_bf16 v[26:29], v[146:149], v[194:197], v[26:29]
	v_mfma_f32_16x16x32_bf16 v[18:21], v[164:167], v[194:197], v[18:21]
	v_mfma_f32_16x16x32_bf16 v[10:13], v[146:149], v[202:205], v[10:13]
	v_mfma_f32_16x16x32_bf16 v[2:5], v[164:167], v[202:205], v[2:5]
	v_mfma_f32_16x16x32_bf16 v[58:61], v[150:153], v[176:179], v[58:61]
	v_mfma_f32_16x16x32_bf16 v[50:53], v[168:171], v[176:179], v[50:53]
	v_mfma_f32_16x16x32_bf16 v[42:45], v[150:153], v[190:193], v[42:45]
	v_mfma_f32_16x16x32_bf16 v[34:37], v[168:171], v[190:193], v[34:37]
	v_mfma_f32_16x16x32_bf16 v[26:29], v[150:153], v[198:201], v[26:29]
	v_mfma_f32_16x16x32_bf16 v[18:21], v[168:171], v[198:201], v[18:21]
	s_setprio 2
	s_barrier
	v_mfma_f32_16x16x32_bf16 v[10:13], v[150:153], v[206:209], v[10:13]
	s_mov_b32 s6, 0x18000
	s_mov_b32 s12, 0x1c000
	v_add_u32_e32 v142, s6, v184
	ds_read_b128 v[130:133], v142
	ds_read_b128 v[134:137], v142 offset:1024
	ds_read_b128 v[138:141], v142 offset:2048
	v_mfma_f32_16x16x32_bf16 v[2:5], v[168:171], v[206:209], v[2:5]
	s_setprio 0
	v_add_u32_e32 v168, s12, v184
	ds_read_b128 v[142:145], v142 offset:3072
	ds_read_b128 v[146:149], v168
	ds_read_b128 v[150:153], v168 offset:1024
	ds_read_b128 v[164:167], v168 offset:2048
	ds_read_b128 v[168:171], v168 offset:3072
	s_add_u32 s14, s28, 0x80000
	s_addc_u32 s15, s29, 0
	s_mov_b32 m0, s52
	ds_read_b128 v[172:175], v185 offset:32768
	ds_read_b128 v[176:179], v185 offset:33792
	ds_read_b128 v[186:189], v185 offset:34816
	ds_read_b128 v[190:193], v185 offset:35840
	ds_read_b128 v[194:197], v185 offset:36864
	ds_read_b128 v[198:201], v185 offset:37888
	ds_read_b128 v[202:205], v185 offset:38912
	ds_read_b128 v[206:209], v185 offset:39936
	global_load_lds_dwordx4 v158, s[14:15]
	s_mov_b32 m0, s53
	s_nop 0
	global_load_lds_dwordx4 v156, s[14:15]
	s_waitcnt vmcnt(8)
	s_waitcnt lgkmcnt(0)
	s_barrier
	s_setprio 1
	s_waitcnt lgkmcnt(0)
	v_mfma_f32_16x16x32_bf16 v[122:125], v[130:133], v[172:175], v[122:125]
	v_mfma_f32_16x16x32_bf16 v[118:121], v[138:141], v[172:175], v[118:121]
	v_mfma_f32_16x16x32_bf16 v[110:113], v[130:133], v[186:189], v[110:113]
	v_mfma_f32_16x16x32_bf16 v[102:105], v[138:141], v[186:189], v[102:105]
	v_mfma_f32_16x16x32_bf16 v[94:97], v[130:133], v[194:197], v[94:97]
	v_mfma_f32_16x16x32_bf16 v[86:89], v[138:141], v[194:197], v[86:89]
	v_mfma_f32_16x16x32_bf16 v[78:81], v[130:133], v[202:205], v[78:81]
	v_mfma_f32_16x16x32_bf16 v[70:73], v[138:141], v[202:205], v[70:73]
	v_mfma_f32_16x16x32_bf16 v[122:125], v[134:137], v[176:179], v[122:125]
	v_mfma_f32_16x16x32_bf16 v[118:121], v[142:145], v[176:179], v[118:121]
	v_mfma_f32_16x16x32_bf16 v[110:113], v[134:137], v[190:193], v[110:113]
	v_mfma_f32_16x16x32_bf16 v[102:105], v[142:145], v[190:193], v[102:105]
	v_mfma_f32_16x16x32_bf16 v[94:97], v[134:137], v[198:201], v[94:97]
	v_mfma_f32_16x16x32_bf16 v[86:89], v[142:145], v[198:201], v[86:89]
	v_mfma_f32_16x16x32_bf16 v[78:81], v[134:137], v[206:209], v[78:81]
	v_mfma_f32_16x16x32_bf16 v[70:73], v[142:145], v[206:209], v[70:73]
	s_setprio 0
	s_setprio 1
	v_mfma_f32_16x16x32_bf16 v[114:117], v[146:149], v[172:175], v[114:117]
	v_mfma_f32_16x16x32_bf16 v[126:129], v[164:167], v[172:175], v[126:129]
	v_mfma_f32_16x16x32_bf16 v[106:109], v[146:149], v[186:189], v[106:109]
	v_mfma_f32_16x16x32_bf16 v[98:101], v[164:167], v[186:189], v[98:101]
	v_mfma_f32_16x16x32_bf16 v[90:93], v[146:149], v[194:197], v[90:93]
	v_mfma_f32_16x16x32_bf16 v[82:85], v[164:167], v[194:197], v[82:85]
	v_mfma_f32_16x16x32_bf16 v[74:77], v[146:149], v[202:205], v[74:77]
	v_mfma_f32_16x16x32_bf16 v[66:69], v[164:167], v[202:205], v[66:69]
	v_mfma_f32_16x16x32_bf16 v[114:117], v[150:153], v[176:179], v[114:117]
	v_mfma_f32_16x16x32_bf16 v[126:129], v[168:171], v[176:179], v[126:129]
	v_mfma_f32_16x16x32_bf16 v[106:109], v[150:153], v[190:193], v[106:109]
	v_mfma_f32_16x16x32_bf16 v[98:101], v[168:171], v[190:193], v[98:101]
	v_mfma_f32_16x16x32_bf16 v[90:93], v[150:153], v[198:201], v[90:93]
	v_mfma_f32_16x16x32_bf16 v[82:85], v[168:171], v[198:201], v[82:85]
	s_setprio 2
	s_barrier
; #define PG8_STAGE(bufoff, gbase, voff) do { _Pragma("unroll") for (int _i = 0; _i < 2; ++_i) \
;         __builtin_amdgcn_global_load_lds((const unsigned*)((const char*)(gbase) + (voff)[_i]), (LAS unsigned*)(lds + (bufoff) + ldsw + _i * 8192), 16, 0, 0); } while (0)
; #define PG8_LDA(dst, b, h) do { _Pragma("unroll") for (int m = 0; m < 4; ++m) _Pragma("unroll") for (int k = 0; k < 2; ++k) dst[m][k] = *(const LAS bf16x8*)(lds + PG8_SA(b, h) + aoff + m * 2048 + k * 1024); } while (0)
; #define PG8_MMA(ai, bj, At, Bt) do { __builtin_amdgcn_s_setprio(1); _Pragma("unroll") for (int m = 0; m < 4; ++m) _Pragma("unroll") for (int n = 0; n < 2; ++n) _Pragma("unroll") for (int k = 0; k < 2; ++k) \
;         acc[ai][bj][m][n] = __builtin_amdgcn_mfma_f32_16x16x32_bf16(Bt[n][k], At[m][k], acc[ai][bj][m][n], 0, 0, 0); __builtin_amdgcn_s_setprio(0); } while (0)
; #define PG8_WAIT_V(n) asm volatile("s_waitcnt vmcnt(" #n ")" ::: "memory")
; #define PG8_WAIT_L(n) asm volatile("s_waitcnt lgkmcnt(" #n ")" ::: "memory")
; #define PG8_BAR __builtin_amdgcn_s_barrier()
; #define PG8_SCHED __builtin_amdgcn_sched_barrier(0)
; template <class Epi>
; __device__ __forceinline__ void gemm_phase(LAS unsigned char* lds, const Gemm g, const TileOrder& S, const Epi& E) {
;     ...
;             PG8_WAIT_V(8); PG8_WAIT_L(0); PG8_BAR; PG8_MMA(0, 0, At, B0); PG8_MMA(0, 1, At, B1); PG8_BAR; PG8_SCHED;
;             PG8_LDA(At, 1, 1); PG8_STAGE(PG8_SB(1, 0), b3, voffB); PG8_STAGE(PG8_SB(1, 1), b3 + hstepB, voffB); PG8_STAGE(PG8_SA(1, 0), a3, voffA);
;             PG8_WAIT_V(8); PG8_WAIT_L(0); PG8_BAR; PG8_MMA(1, 0, At, B0); PG8_MMA(1, 1, At, B1); PG8_BAR; PG8_SCHED;
;         }
;         if (wr == 0) PG8_BAR;
	v_mfma_f32_16x16x32_bf16 v[74:77], v[150:153], v[206:209], v[74:77]
	ds_read_b128 v[172:175], v185 offset:49152
	ds_read_b128 v[176:179], v185 offset:50176
	ds_read_b128 v[186:189], v185 offset:51200
	v_mfma_f32_16x16x32_bf16 v[66:69], v[168:171], v[206:209], v[66:69]
	s_setprio 0
	s_add_i32 s6, s6, s31
	v_lshl_add_u64 v[180:181], v[180:181], 0, s[34:35]
	s_mov_b32 m0, s6
	ds_read_b128 v[190:193], v185 offset:52224
	ds_read_b128 v[194:197], v185 offset:53248
	ds_read_b128 v[198:201], v185 offset:54272
	ds_read_b128 v[202:205], v185 offset:55296
	ds_read_b128 v[206:209], v185 offset:56320
	global_load_lds_dwordx4 v[180:181], off
	s_add_i32 m0, s6, 0x2000
	s_add_u32 s2, s2, 0x80080
	v_lshl_add_u64 v[180:181], v[210:211], 0, s[34:35]
	s_addc_u32 s3, s3, 0
	s_add_i32 s6, s12, s31
	global_load_lds_dwordx4 v[180:181], off
	s_mov_b32 m0, s6
	s_nop 0
	global_load_lds_dwordx4 v0, s[2:3]
	v_lshl_add_u64 v[180:181], s[2:3], 0, v[154:155]
	s_add_i32 m0, s6, 0x2000
	s_nop 0
	global_load_lds_dwordx4 v[180:181], off
	v_lshl_add_u64 v[180:181], v[212:213], 0, s[34:35]
	s_mov_b32 m0, s58
	s_nop 0
	global_load_lds_dwordx4 v[180:181], off
	v_lshl_add_u64 v[180:181], v[214:215], 0, s[34:35]
	s_mov_b32 m0, s59
	s_nop 0
	global_load_lds_dwordx4 v[180:181], off
	s_waitcnt vmcnt(8)
	s_waitcnt lgkmcnt(0)
	s_barrier
	s_setprio 1
	s_waitcnt lgkmcnt(0)
	v_mfma_f32_16x16x32_bf16 v[62:65], v[130:133], v[172:175], v[62:65]
	v_mfma_f32_16x16x32_bf16 v[54:57], v[138:141], v[172:175], v[54:57]
	v_mfma_f32_16x16x32_bf16 v[46:49], v[130:133], v[186:189], v[46:49]
	v_mfma_f32_16x16x32_bf16 v[38:41], v[138:141], v[186:189], v[38:41]
	v_mfma_f32_16x16x32_bf16 v[30:33], v[130:133], v[194:197], v[30:33]
	v_mfma_f32_16x16x32_bf16 v[22:25], v[138:141], v[194:197], v[22:25]
	v_mfma_f32_16x16x32_bf16 v[14:17], v[130:133], v[202:205], v[14:17]
	v_mfma_f32_16x16x32_bf16 v[6:9], v[138:141], v[202:205], v[6:9]
	v_mfma_f32_16x16x32_bf16 v[62:65], v[134:137], v[176:179], v[62:65]
	v_mfma_f32_16x16x32_bf16 v[54:57], v[142:145], v[176:179], v[54:57]
	v_mfma_f32_16x16x32_bf16 v[46:49], v[134:137], v[190:193], v[46:49]
	v_mfma_f32_16x16x32_bf16 v[38:41], v[142:145], v[190:193], v[38:41]
	v_mfma_f32_16x16x32_bf16 v[30:33], v[134:137], v[198:201], v[30:33]
	v_mfma_f32_16x16x32_bf16 v[22:25], v[142:145], v[198:201], v[22:25]
	v_mfma_f32_16x16x32_bf16 v[14:17], v[134:137], v[206:209], v[14:17]
	v_mfma_f32_16x16x32_bf16 v[6:9], v[142:145], v[206:209], v[6:9]
	s_setprio 0
	s_setprio 1
	v_mfma_f32_16x16x32_bf16 v[58:61], v[146:149], v[172:175], v[58:61]
	v_mfma_f32_16x16x32_bf16 v[50:53], v[164:167], v[172:175], v[50:53]
	v_mfma_f32_16x16x32_bf16 v[42:45], v[146:149], v[186:189], v[42:45]
	v_mfma_f32_16x16x32_bf16 v[34:37], v[164:167], v[186:189], v[34:37]
	v_mfma_f32_16x16x32_bf16 v[26:29], v[146:149], v[194:197], v[26:29]
	v_mfma_f32_16x16x32_bf16 v[18:21], v[164:167], v[194:197], v[18:21]
	v_mfma_f32_16x16x32_bf16 v[10:13], v[146:149], v[202:205], v[10:13]
	v_mfma_f32_16x16x32_bf16 v[2:5], v[164:167], v[202:205], v[2:5]
	v_mfma_f32_16x16x32_bf16 v[58:61], v[150:153], v[176:179], v[58:61]
	v_mfma_f32_16x16x32_bf16 v[50:53], v[168:171], v[176:179], v[50:53]
	v_mfma_f32_16x16x32_bf16 v[42:45], v[150:153], v[190:193], v[42:45]
	v_mfma_f32_16x16x32_bf16 v[34:37], v[168:171], v[190:193], v[34:37]
	v_mfma_f32_16x16x32_bf16 v[26:29], v[150:153], v[198:201], v[26:29]
	v_mfma_f32_16x16x32_bf16 v[18:21], v[168:171], v[198:201], v[18:21]
	s_setprio 2
	s_barrier
	v_mfma_f32_16x16x32_bf16 v[10:13], v[150:153], v[206:209], v[10:13]
	v_mfma_f32_16x16x32_bf16 v[2:5], v[168:171], v[206:209], v[2:5]
	s_setprio 0
	s_add_i32 s66, s66, 2
	s_add_u32 s4, s4, 0x100
	s_addc_u32 s5, s5, 0
	s_add_u32 s64, s64, 0x100
	s_addc_u32 s65, s65, 0
	s_cmp_gt_u32 s66, 29
	s_cbranch_scc0 .LBB0_668
	s_and_b64 vcc, exec, s[38:39]
	s_cbranch_vccz .LBB0_671
	s_barrier

; #define PG8_STAGE(bufoff, gbase, voff) do { _Pragma("unroll") for (int _i = 0; _i < 2; ++_i) \
;         __builtin_amdgcn_global_load_lds((const unsigned*)((const char*)(gbase) + (voff)[_i]), (LAS unsigned*)(lds + (bufoff) + ldsw + _i * 8192), 16, 0, 0); } while (0)
; #define PG8_LDA(dst, b, h) do { _Pragma("unroll") for (int m = 0; m < 4; ++m) _Pragma("unroll") for (int k = 0; k < 2; ++k) dst[m][k] = *(const LAS bf16x8*)(lds + PG8_SA(b, h) + aoff + m * 2048 + k * 1024); } while (0)
; #define PG8_LDB(dst, b, h) do { _Pragma("unroll") for (int n = 0; n < 2; ++n) _Pragma("unroll") for (int k = 0; k < 2; ++k) dst[n][k] = *(const LAS bf16x8*)(lds + PG8_SB(b, h) + boff + n * 2048 + k * 1024); } while (0)
; #define PG8_MMA(ai, bj, At, Bt) do { __builtin_amdgcn_s_setprio(1); _Pragma("unroll") for (int m = 0; m < 4; ++m) _Pragma("unroll") for (int n = 0; n < 2; ++n) _Pragma("unroll") for (int k = 0; k < 2; ++k) \
;         acc[ai][bj][m][n] = __builtin_amdgcn_mfma_f32_16x16x32_bf16(Bt[n][k], At[m][k], acc[ai][bj][m][n], 0, 0, 0); __builtin_amdgcn_s_setprio(0); } while (0)
; #define PG8_WAIT_V(n) asm volatile("s_waitcnt vmcnt(" #n ")" ::: "memory")
; #define PG8_WAIT_L(n) asm volatile("s_waitcnt lgkmcnt(" #n ")" ::: "memory")
; template <class Epi>
; __device__ __forceinline__ void gemm_phase(LAS unsigned char* lds, const Gemm g, const TileOrder& S, const Epi& E) {
;     ...
;         const bool has_next = S.next(ui + 1, nxt);
;         const char* nA = has_next ? (const char*)g.A + (size_t)nxt.pm * tstepA : cA; const char* nB = has_next ? (const char*)g.Bt + (size_t)nxt.pb * tstepB : cB;
;         for (int t = 0; t < nt; t += 2) {
;             const bool last = (t == nt - 2);
;             const char* a1 = cA + (size_t)(t + 1) * kstepA;
;             const char* a2 = last ? nA : cA + (size_t)(t + 2) * kstepA; const char* b2 = last ? nB : cB + (size_t)(t + 2) * kstep;
;             const char* a3 = a2 + kstepA; const char* b3 = b2 + kstep;
;             PG8_LDB(B0, 0, 0); PG8_LDB(B1, 0, 1); PG8_SCHED; PG8_LDA(At, 0, 0); PG8_STAGE(PG8_SA(1, 1), a1 + hstepA, voffA);
;             PG8_WAIT_V(8); PG8_WAIT_L(0); PG8_BAR; PG8_MMA(0, 0, At, B0); PG8_MMA(0, 1, At, B1); PG8_BAR; PG8_SCHED;
;             PG8_LDA(At, 0, 1); PG8_STAGE(PG8_SB(0, 0), b2, voffB); PG8_STAGE(PG8_SB(0, 1), b2 + hstepB, voffB); PG8_STAGE(PG8_SA(0, 0), a2, voffA);
.LBB0_757:
	s_mov_b32 s6, 0x10000
	v_add_u32_e32 v0, s6, v154
	s_mov_b32 s14, 0x14000
	ds_read_b128 v[142:145], v0
	ds_read_b128 v[146:149], v0 offset:1024
	ds_read_b128 v[156:159], v0 offset:2048
	ds_read_b128 v[160:163], v0 offset:3072
	v_add_u32_e32 v0, s14, v154
	ds_read_b128 v[164:167], v0
	ds_read_b128 v[168:171], v0 offset:1024
	ds_read_b128 v[172:175], v0 offset:2048
	ds_read_b128 v[176:179], v0 offset:3072
	ds_read_b128 v[180:183], v155
	ds_read_b128 v[184:187], v155 offset:1024
	ds_read_b128 v[188:191], v155 offset:2048
	ds_read_b128 v[192:195], v155 offset:3072
	ds_read_b128 v[196:199], v155 offset:4096
	ds_read_b128 v[200:203], v155 offset:5120
	ds_read_b128 v[204:207], v155 offset:6144
	ds_read_b128 v[208:211], v155 offset:7168
	s_add_u32 s2, s28, 0xfff80080
	s_addc_u32 s3, s29, -1
	s_cmp_eq_u32 s72, 28
	s_cselect_b32 s31, s47, s3
	s_cselect_b32 s30, s51, s2
	s_cselect_b32 s3, s49, s71
	s_cselect_b32 s2, s69, s70
	s_add_i32 m0, s59, 0xc000
	s_nop 0
	global_load_lds_dwordx4 v138, s[28:29]
	s_add_i32 m0, s59, 0xe000
	s_nop 0
	global_load_lds_dwordx4 v140, s[28:29]
	s_waitcnt vmcnt(8)
	s_waitcnt lgkmcnt(0)
	s_barrier
	s_setprio 1
	s_waitcnt lgkmcnt(0)
	v_mfma_f32_16x16x32_bf16 v[126:129], v[142:145], v[180:183], v[126:129]
	v_mfma_f32_16x16x32_bf16 v[122:125], v[156:159], v[180:183], v[122:125]
	v_mfma_f32_16x16x32_bf16 v[110:113], v[142:145], v[188:191], v[110:113]
	v_mfma_f32_16x16x32_bf16 v[106:109], v[156:159], v[188:191], v[106:109]
	v_mfma_f32_16x16x32_bf16 v[94:97], v[142:145], v[196:199], v[94:97]
	v_mfma_f32_16x16x32_bf16 v[90:93], v[156:159], v[196:199], v[90:93]
	v_mfma_f32_16x16x32_bf16 v[78:81], v[142:145], v[204:207], v[78:81]
	v_mfma_f32_16x16x32_bf16 v[74:77], v[156:159], v[204:207], v[74:77]
	v_mfma_f32_16x16x32_bf16 v[126:129], v[146:149], v[184:187], v[126:129]
	v_mfma_f32_16x16x32_bf16 v[122:125], v[160:163], v[184:187], v[122:125]
	v_mfma_f32_16x16x32_bf16 v[110:113], v[146:149], v[192:195], v[110:113]
	v_mfma_f32_16x16x32_bf16 v[106:109], v[160:163], v[192:195], v[106:109]
	v_mfma_f32_16x16x32_bf16 v[94:97], v[146:149], v[200:203], v[94:97]
	v_mfma_f32_16x16x32_bf16 v[90:93], v[160:163], v[200:203], v[90:93]
	v_mfma_f32_16x16x32_bf16 v[78:81], v[146:149], v[208:211], v[78:81]
	v_mfma_f32_16x16x32_bf16 v[74:77], v[160:163], v[208:211], v[74:77]
	s_setprio 0
	s_setprio 1
	v_mfma_f32_16x16x32_bf16 v[118:121], v[164:167], v[180:183], v[118:121]
	v_mfma_f32_16x16x32_bf16 v[114:117], v[172:175], v[180:183], v[114:117]
	v_mfma_f32_16x16x32_bf16 v[102:105], v[164:167], v[188:191], v[102:105]
	v_mfma_f32_16x16x32_bf16 v[98:101], v[172:175], v[188:191], v[98:101]
	v_mfma_f32_16x16x32_bf16 v[86:89], v[164:167], v[196:199], v[86:89]
	v_mfma_f32_16x16x32_bf16 v[82:85], v[172:175], v[196:199], v[82:85]
	v_mfma_f32_16x16x32_bf16 v[70:73], v[164:167], v[204:207], v[70:73]
	v_mfma_f32_16x16x32_bf16 v[66:69], v[172:175], v[204:207], v[66:69]
	v_mfma_f32_16x16x32_bf16 v[118:121], v[168:171], v[184:187], v[118:121]
	v_mfma_f32_16x16x32_bf16 v[114:117], v[176:179], v[184:187], v[114:117]
	v_mfma_f32_16x16x32_bf16 v[102:105], v[168:171], v[192:195], v[102:105]
	v_mfma_f32_16x16x32_bf16 v[98:101], v[176:179], v[192:195], v[98:101]
	v_mfma_f32_16x16x32_bf16 v[86:89], v[168:171], v[200:203], v[86:89]
	v_mfma_f32_16x16x32_bf16 v[82:85], v[176:179], v[200:203], v[82:85]
	s_setprio 2
	s_barrier
	v_mfma_f32_16x16x32_bf16 v[70:73], v[168:171], v[208:211], v[70:73]
	ds_read_b128 v[180:183], v155 offset:16384
	ds_read_b128 v[184:187], v155 offset:17408
	ds_read_b128 v[188:191], v155 offset:18432
	v_mfma_f32_16x16x32_bf16 v[66:69], v[176:179], v[208:211], v[66:69]
	s_setprio 0
	s_add_i32 s6, s6, s58
	v_lshl_add_u64 v[150:151], s[2:3], 0, v[134:135]
	s_mov_b32 m0, s6
	ds_read_b128 v[192:195], v155 offset:19456
	ds_read_b128 v[196:199], v155 offset:20480
	ds_read_b128 v[200:203], v155 offset:21504
	ds_read_b128 v[204:207], v155 offset:22528
	ds_read_b128 v[208:211], v155 offset:23552
	global_load_lds_dwordx4 v[150:151], off
	s_add_i32 m0, s6, 0x2000
	s_add_u32 s12, s2, 0x80000
	v_lshl_add_u64 v[212:213], s[2:3], 0, v[130:131]
	s_addc_u32 s13, s3, 0
	s_add_i32 s6, s14, s58
	global_load_lds_dwordx4 v[212:213], off
	s_mov_b32 m0, s6
	v_lshl_add_u64 v[216:217], s[30:31], 0, v[132:133]
	global_load_lds_dwordx4 v134, s[12:13]
	s_add_i32 m0, s6, 0x2000
	s_nop 0
	global_load_lds_dwordx4 v130, s[12:13]
	v_lshl_add_u64 v[214:215], s[30:31], 0, v[136:137]
	s_mov_b32 m0, s59
	s_nop 0
	global_load_lds_dwordx4 v[214:215], off
	s_mov_b32 m0, s60
	s_nop 0
	global_load_lds_dwordx4 v[216:217], off
	s_waitcnt vmcnt(8)
	s_waitcnt lgkmcnt(0)
	s_barrier
; #define PG8_STAGE(bufoff, gbase, voff) do { _Pragma("unroll") for (int _i = 0; _i < 2; ++_i) \
;         __builtin_amdgcn_global_load_lds((const unsigned*)((const char*)(gbase) + (voff)[_i]), (LAS unsigned*)(lds + (bufoff) + ldsw + _i * 8192), 16, 0, 0); } while (0)
; #define PG8_LDA(dst, b, h) do { _Pragma("unroll") for (int m = 0; m < 4; ++m) _Pragma("unroll") for (int k = 0; k < 2; ++k) dst[m][k] = *(const LAS bf16x8*)(lds + PG8_SA(b, h) + aoff + m * 2048 + k * 1024); } while (0)
; #define PG8_LDB(dst, b, h) do { _Pragma("unroll") for (int n = 0; n < 2; ++n) _Pragma("unroll") for (int k = 0; k < 2; ++k) dst[n][k] = *(const LAS bf16x8*)(lds + PG8_SB(b, h) + boff + n * 2048 + k * 1024); } while (0)
; #define PG8_MMA(ai, bj, At, Bt) do { __builtin_amdgcn_s_setprio(1); _Pragma("unroll") for (int m = 0; m < 4; ++m) _Pragma("unroll") for (int n = 0; n < 2; ++n) _Pragma("unroll") for (int k = 0; k < 2; ++k) \
;         acc[ai][bj][m][n] = __builtin_amdgcn_mfma_f32_16x16x32_bf16(Bt[n][k], At[m][k], acc[ai][bj][m][n], 0, 0, 0); __builtin_amdgcn_s_setprio(0); } while (0)
; #define PG8_WAIT_V(n) asm volatile("s_waitcnt vmcnt(" #n ")" ::: "memory")
; #define PG8_WAIT_L(n) asm volatile("s_waitcnt lgkmcnt(" #n ")" ::: "memory")
; #define PG8_BAR __builtin_amdgcn_s_barrier()
; #define PG8_SCHED __builtin_amdgcn_sched_barrier(0)
; template <class Epi>
; __device__ __forceinline__ void gemm_phase(LAS unsigned char* lds, const Gemm g, const TileOrder& S, const Epi& E) {
;     ...
;             PG8_WAIT_V(8); PG8_WAIT_L(0); PG8_BAR; PG8_MMA(1, 0, At, B0); PG8_MMA(1, 1, At, B1); PG8_BAR; PG8_SCHED;
;             PG8_LDB(B0, 1, 0); PG8_LDB(B1, 1, 1); PG8_SCHED; PG8_LDA(At, 1, 0); PG8_STAGE(PG8_SA(0, 1), a2 + hstepA, voffA);
;             PG8_WAIT_V(8); PG8_WAIT_L(0); PG8_BAR; PG8_MMA(0, 0, At, B0); PG8_MMA(0, 1, At, B1); PG8_BAR; PG8_SCHED;
	s_setprio 1
	s_waitcnt lgkmcnt(0)
	v_mfma_f32_16x16x32_bf16 v[62:65], v[142:145], v[180:183], v[62:65]
	v_mfma_f32_16x16x32_bf16 v[58:61], v[156:159], v[180:183], v[58:61]
	v_mfma_f32_16x16x32_bf16 v[46:49], v[142:145], v[188:191], v[46:49]
	v_mfma_f32_16x16x32_bf16 v[42:45], v[156:159], v[188:191], v[42:45]
	v_mfma_f32_16x16x32_bf16 v[30:33], v[142:145], v[196:199], v[30:33]
	v_mfma_f32_16x16x32_bf16 v[26:29], v[156:159], v[196:199], v[26:29]
	v_mfma_f32_16x16x32_bf16 v[14:17], v[142:145], v[204:207], v[14:17]
	v_mfma_f32_16x16x32_bf16 v[10:13], v[156:159], v[204:207], v[10:13]
	v_mfma_f32_16x16x32_bf16 v[62:65], v[146:149], v[184:187], v[62:65]
	v_mfma_f32_16x16x32_bf16 v[58:61], v[160:163], v[184:187], v[58:61]
	v_mfma_f32_16x16x32_bf16 v[46:49], v[146:149], v[192:195], v[46:49]
	v_mfma_f32_16x16x32_bf16 v[42:45], v[160:163], v[192:195], v[42:45]
	v_mfma_f32_16x16x32_bf16 v[30:33], v[146:149], v[200:203], v[30:33]
	v_mfma_f32_16x16x32_bf16 v[26:29], v[160:163], v[200:203], v[26:29]
	v_mfma_f32_16x16x32_bf16 v[14:17], v[146:149], v[208:211], v[14:17]
	v_mfma_f32_16x16x32_bf16 v[10:13], v[160:163], v[208:211], v[10:13]
	s_setprio 0
	s_setprio 1
	v_mfma_f32_16x16x32_bf16 v[54:57], v[164:167], v[180:183], v[54:57]
	v_mfma_f32_16x16x32_bf16 v[50:53], v[172:175], v[180:183], v[50:53]
	v_mfma_f32_16x16x32_bf16 v[38:41], v[164:167], v[188:191], v[38:41]
	v_mfma_f32_16x16x32_bf16 v[34:37], v[172:175], v[188:191], v[34:37]
	v_mfma_f32_16x16x32_bf16 v[22:25], v[164:167], v[196:199], v[22:25]
	v_mfma_f32_16x16x32_bf16 v[18:21], v[172:175], v[196:199], v[18:21]
	v_mfma_f32_16x16x32_bf16 v[6:9], v[164:167], v[204:207], v[6:9]
	v_mfma_f32_16x16x32_bf16 v[2:5], v[172:175], v[204:207], v[2:5]
	v_mfma_f32_16x16x32_bf16 v[54:57], v[168:171], v[184:187], v[54:57]
	v_mfma_f32_16x16x32_bf16 v[50:53], v[176:179], v[184:187], v[50:53]
	v_mfma_f32_16x16x32_bf16 v[38:41], v[168:171], v[192:195], v[38:41]
	v_mfma_f32_16x16x32_bf16 v[34:37], v[176:179], v[192:195], v[34:37]
	v_mfma_f32_16x16x32_bf16 v[22:25], v[168:171], v[200:203], v[22:25]
	v_mfma_f32_16x16x32_bf16 v[18:21], v[176:179], v[200:203], v[18:21]
	s_setprio 2
	s_barrier
	v_mfma_f32_16x16x32_bf16 v[6:9], v[168:171], v[208:211], v[6:9]
	s_mov_b32 s6, 0x18000
	v_add_u32_e32 v0, s6, v154
	s_mov_b32 s14, 0x1c000
	ds_read_b128 v[142:145], v0
	ds_read_b128 v[146:149], v0 offset:1024
	ds_read_b128 v[156:159], v0 offset:2048
	v_mfma_f32_16x16x32_bf16 v[2:5], v[176:179], v[208:211], v[2:5]
	s_setprio 0
	ds_read_b128 v[160:163], v0 offset:3072
	v_add_u32_e32 v0, s14, v154
	ds_read_b128 v[164:167], v0
	ds_read_b128 v[168:171], v0 offset:1024
	ds_read_b128 v[172:175], v0 offset:2048
	ds_read_b128 v[176:179], v0 offset:3072
	s_add_u32 s12, s30, 0x80000
	s_addc_u32 s13, s31, 0
	s_mov_b32 m0, s61
	ds_read_b128 v[180:183], v155 offset:32768
	ds_read_b128 v[184:187], v155 offset:33792
	ds_read_b128 v[188:191], v155 offset:34816
	ds_read_b128 v[192:195], v155 offset:35840
	ds_read_b128 v[196:199], v155 offset:36864
	ds_read_b128 v[200:203], v155 offset:37888
	ds_read_b128 v[204:207], v155 offset:38912
	ds_read_b128 v[208:211], v155 offset:39936
	global_load_lds_dwordx4 v136, s[12:13]
	s_mov_b32 m0, s62
	s_nop 0
	global_load_lds_dwordx4 v132, s[12:13]
	s_waitcnt vmcnt(8)
	s_waitcnt lgkmcnt(0)
	s_barrier
	s_setprio 1
	s_waitcnt lgkmcnt(0)
	v_mfma_f32_16x16x32_bf16 v[126:129], v[142:145], v[180:183], v[126:129]
	v_mfma_f32_16x16x32_bf16 v[122:125], v[156:159], v[180:183], v[122:125]
	v_mfma_f32_16x16x32_bf16 v[110:113], v[142:145], v[188:191], v[110:113]
	v_mfma_f32_16x16x32_bf16 v[106:109], v[156:159], v[188:191], v[106:109]
	v_mfma_f32_16x16x32_bf16 v[94:97], v[142:145], v[196:199], v[94:97]
	v_mfma_f32_16x16x32_bf16 v[90:93], v[156:159], v[196:199], v[90:93]
	v_mfma_f32_16x16x32_bf16 v[78:81], v[142:145], v[204:207], v[78:81]
	v_mfma_f32_16x16x32_bf16 v[74:77], v[156:159], v[204:207], v[74:77]
	v_mfma_f32_16x16x32_bf16 v[126:129], v[146:149], v[184:187], v[126:129]
	v_mfma_f32_16x16x32_bf16 v[122:125], v[160:163], v[184:187], v[122:125]
	v_mfma_f32_16x16x32_bf16 v[110:113], v[146:149], v[192:195], v[110:113]
	v_mfma_f32_16x16x32_bf16 v[106:109], v[160:163], v[192:195], v[106:109]
	v_mfma_f32_16x16x32_bf16 v[94:97], v[146:149], v[200:203], v[94:97]
	v_mfma_f32_16x16x32_bf16 v[90:93], v[160:163], v[200:203], v[90:93]
	v_mfma_f32_16x16x32_bf16 v[78:81], v[146:149], v[208:211], v[78:81]
	v_mfma_f32_16x16x32_bf16 v[74:77], v[160:163], v[208:211], v[74:77]
	s_setprio 0
	s_setprio 1
	v_mfma_f32_16x16x32_bf16 v[118:121], v[164:167], v[180:183], v[118:121]
	v_mfma_f32_16x16x32_bf16 v[114:117], v[172:175], v[180:183], v[114:117]
	v_mfma_f32_16x16x32_bf16 v[102:105], v[164:167], v[188:191], v[102:105]
	v_mfma_f32_16x16x32_bf16 v[98:101], v[172:175], v[188:191], v[98:101]
	v_mfma_f32_16x16x32_bf16 v[86:89], v[164:167], v[196:199], v[86:89]
	v_mfma_f32_16x16x32_bf16 v[82:85], v[172:175], v[196:199], v[82:85]
	v_mfma_f32_16x16x32_bf16 v[70:73], v[164:167], v[204:207], v[70:73]
	v_mfma_f32_16x16x32_bf16 v[66:69], v[172:175], v[204:207], v[66:69]
	v_mfma_f32_16x16x32_bf16 v[118:121], v[168:171], v[184:187], v[118:121]
	v_mfma_f32_16x16x32_bf16 v[114:117], v[176:179], v[184:187], v[114:117]
	v_mfma_f32_16x16x32_bf16 v[102:105], v[168:171], v[192:195], v[102:105]
	v_mfma_f32_16x16x32_bf16 v[98:101], v[176:179], v[192:195], v[98:101]
	v_mfma_f32_16x16x32_bf16 v[86:89], v[168:171], v[200:203], v[86:89]
	v_mfma_f32_16x16x32_bf16 v[82:85], v[176:179], v[200:203], v[82:85]
	s_setprio 2
	s_barrier
; #define PG8_STAGE(bufoff, gbase, voff) do { _Pragma("unroll") for (int _i = 0; _i < 2; ++_i) \
;         __builtin_amdgcn_global_load_lds((const unsigned*)((const char*)(gbase) + (voff)[_i]), (LAS unsigned*)(lds + (bufoff) + ldsw + _i * 8192), 16, 0, 0); } while (0)
; #define PG8_LDA(dst, b, h) do { _Pragma("unroll") for (int m = 0; m < 4; ++m) _Pragma("unroll") for (int k = 0; k < 2; ++k) dst[m][k] = *(const LAS bf16x8*)(lds + PG8_SA(b, h) + aoff + m * 2048 + k * 1024); } while (0)
; #define PG8_MMA(ai, bj, At, Bt) do { __builtin_amdgcn_s_setprio(1); _Pragma("unroll") for (int m = 0; m < 4; ++m) _Pragma("unroll") for (int n = 0; n < 2; ++n) _Pragma("unroll") for (int k = 0; k < 2; ++k) \
;         acc[ai][bj][m][n] = __builtin_amdgcn_mfma_f32_16x16x32_bf16(Bt[n][k], At[m][k], acc[ai][bj][m][n], 0, 0, 0); __builtin_amdgcn_s_setprio(0); } while (0)
; #define PG8_WAIT_V(n) asm volatile("s_waitcnt vmcnt(" #n ")" ::: "memory")
; #define PG8_WAIT_L(n) asm volatile("s_waitcnt lgkmcnt(" #n ")" ::: "memory")
; #define PG8_BAR __builtin_amdgcn_s_barrier()
; #define PG8_SCHED __builtin_amdgcn_sched_barrier(0)
; template <class Epi>
; __device__ __forceinline__ void gemm_phase(LAS unsigned char* lds, const Gemm g, const TileOrder& S, const Epi& E) {
;     ...
;             PG8_WAIT_V(8); PG8_WAIT_L(0); PG8_BAR; PG8_MMA(0, 0, At, B0); PG8_MMA(0, 1, At, B1); PG8_BAR; PG8_SCHED;
;             PG8_LDA(At, 1, 1); PG8_STAGE(PG8_SB(1, 0), b3, voffB); PG8_STAGE(PG8_SB(1, 1), b3 + hstepB, voffB); PG8_STAGE(PG8_SA(1, 0), a3, voffA);
;             PG8_WAIT_V(8); PG8_WAIT_L(0); PG8_BAR; PG8_MMA(1, 0, At, B0); PG8_MMA(1, 1, At, B1); PG8_BAR; PG8_SCHED;
;         }
;         if (wr == 0) PG8_BAR;
	v_mfma_f32_16x16x32_bf16 v[70:73], v[168:171], v[208:211], v[70:73]
	ds_read_b128 v[180:183], v155 offset:49152
	ds_read_b128 v[184:187], v155 offset:50176
	ds_read_b128 v[188:191], v155 offset:51200
	v_mfma_f32_16x16x32_bf16 v[66:69], v[176:179], v[208:211], v[66:69]
	s_setprio 0
	s_add_i32 s6, s6, s58
	v_lshl_add_u64 v[150:151], v[150:151], 0, s[34:35]
	s_mov_b32 m0, s6
	ds_read_b128 v[192:195], v155 offset:52224
	ds_read_b128 v[196:199], v155 offset:53248
	ds_read_b128 v[200:203], v155 offset:54272
	ds_read_b128 v[204:207], v155 offset:55296
	ds_read_b128 v[208:211], v155 offset:56320
	global_load_lds_dwordx4 v[150:151], off
	s_add_i32 m0, s6, 0x2000
	s_add_u32 s2, s2, 0x80080
	v_lshl_add_u64 v[150:151], v[212:213], 0, s[34:35]
	s_addc_u32 s3, s3, 0
	s_add_i32 s6, s14, s58
	global_load_lds_dwordx4 v[150:151], off
	s_mov_b32 m0, s6
	s_nop 0
	global_load_lds_dwordx4 v134, s[2:3]
	v_lshl_add_u64 v[150:151], s[2:3], 0, v[130:131]
	s_add_i32 m0, s6, 0x2000
	s_nop 0
	global_load_lds_dwordx4 v[150:151], off
	v_lshl_add_u64 v[150:151], v[214:215], 0, s[34:35]
	s_mov_b32 m0, s63
	s_nop 0
	global_load_lds_dwordx4 v[150:151], off
	v_lshl_add_u64 v[150:151], v[216:217], 0, s[34:35]
	s_mov_b32 m0, s64
	s_nop 0
	global_load_lds_dwordx4 v[150:151], off
	s_waitcnt vmcnt(8)
	s_waitcnt lgkmcnt(0)
	s_barrier
	s_setprio 1
	s_waitcnt lgkmcnt(0)
	v_mfma_f32_16x16x32_bf16 v[62:65], v[142:145], v[180:183], v[62:65]
	v_mfma_f32_16x16x32_bf16 v[58:61], v[156:159], v[180:183], v[58:61]
	v_mfma_f32_16x16x32_bf16 v[46:49], v[142:145], v[188:191], v[46:49]
	v_mfma_f32_16x16x32_bf16 v[42:45], v[156:159], v[188:191], v[42:45]
	v_mfma_f32_16x16x32_bf16 v[30:33], v[142:145], v[196:199], v[30:33]
	v_mfma_f32_16x16x32_bf16 v[26:29], v[156:159], v[196:199], v[26:29]
	v_mfma_f32_16x16x32_bf16 v[14:17], v[142:145], v[204:207], v[14:17]
	v_mfma_f32_16x16x32_bf16 v[10:13], v[156:159], v[204:207], v[10:13]
	v_mfma_f32_16x16x32_bf16 v[62:65], v[146:149], v[184:187], v[62:65]
	v_mfma_f32_16x16x32_bf16 v[58:61], v[160:163], v[184:187], v[58:61]
	v_mfma_f32_16x16x32_bf16 v[46:49], v[146:149], v[192:195], v[46:49]
	v_mfma_f32_16x16x32_bf16 v[42:45], v[160:163], v[192:195], v[42:45]
	v_mfma_f32_16x16x32_bf16 v[30:33], v[146:149], v[200:203], v[30:33]
	v_mfma_f32_16x16x32_bf16 v[26:29], v[160:163], v[200:203], v[26:29]
	v_mfma_f32_16x16x32_bf16 v[14:17], v[146:149], v[208:211], v[14:17]
	v_mfma_f32_16x16x32_bf16 v[10:13], v[160:163], v[208:211], v[10:13]
	s_setprio 0
	s_setprio 1
	v_mfma_f32_16x16x32_bf16 v[54:57], v[164:167], v[180:183], v[54:57]
	v_mfma_f32_16x16x32_bf16 v[50:53], v[172:175], v[180:183], v[50:53]
	v_mfma_f32_16x16x32_bf16 v[38:41], v[164:167], v[188:191], v[38:41]
	v_mfma_f32_16x16x32_bf16 v[34:37], v[172:175], v[188:191], v[34:37]
	v_mfma_f32_16x16x32_bf16 v[22:25], v[164:167], v[196:199], v[22:25]
	v_mfma_f32_16x16x32_bf16 v[18:21], v[172:175], v[196:199], v[18:21]
	v_mfma_f32_16x16x32_bf16 v[6:9], v[164:167], v[204:207], v[6:9]
	v_mfma_f32_16x16x32_bf16 v[2:5], v[172:175], v[204:207], v[2:5]
	v_mfma_f32_16x16x32_bf16 v[54:57], v[168:171], v[184:187], v[54:57]
	v_mfma_f32_16x16x32_bf16 v[50:53], v[176:179], v[184:187], v[50:53]
	v_mfma_f32_16x16x32_bf16 v[38:41], v[168:171], v[192:195], v[38:41]
	v_mfma_f32_16x16x32_bf16 v[34:37], v[176:179], v[192:195], v[34:37]
	v_mfma_f32_16x16x32_bf16 v[22:25], v[168:171], v[200:203], v[22:25]
	v_mfma_f32_16x16x32_bf16 v[18:21], v[176:179], v[200:203], v[18:21]
	s_setprio 2
	s_barrier
	v_mfma_f32_16x16x32_bf16 v[6:9], v[168:171], v[208:211], v[6:9]
	v_mfma_f32_16x16x32_bf16 v[2:5], v[176:179], v[208:211], v[2:5]
	s_setprio 0
	s_add_i32 s72, s72, 2
	s_add_u32 s28, s28, 0x100
	s_addc_u32 s29, s29, 0
	s_add_u32 s70, s70, 0x100
	s_addc_u32 s71, s71, 0
	s_cmp_gt_u32 s72, 29
	s_cbranch_scc0 .LBB0_757
	s_and_b64 vcc, exec, s[42:43]
	s_cbranch_vccz .LBB0_760
	s_barrier

; #define PG8_STAGE(bufoff, gbase, voff) do { _Pragma("unroll") for (int _i = 0; _i < 2; ++_i) \
;         __builtin_amdgcn_global_load_lds((const unsigned*)((const char*)(gbase) + (voff)[_i]), (LAS unsigned*)(lds + (bufoff) + ldsw + _i * 8192), 16, 0, 0); } while (0)
; #define PG8_LDA(dst, b, h) do { _Pragma("unroll") for (int m = 0; m < 4; ++m) _Pragma("unroll") for (int k = 0; k < 2; ++k) dst[m][k] = *(const LAS bf16x8*)(lds + PG8_SA(b, h) + aoff + m * 2048 + k * 1024); } while (0)
; #define PG8_LDB(dst, b, h) do { _Pragma("unroll") for (int n = 0; n < 2; ++n) _Pragma("unroll") for (int k = 0; k < 2; ++k) dst[n][k] = *(const LAS bf16x8*)(lds + PG8_SB(b, h) + boff + n * 2048 + k * 1024); } while (0)
; #define PG8_MMA(ai, bj, At, Bt) do { __builtin_amdgcn_s_setprio(1); _Pragma("unroll") for (int m = 0; m < 4; ++m) _Pragma("unroll") for (int n = 0; n < 2; ++n) _Pragma("unroll") for (int k = 0; k < 2; ++k) \
;         acc[ai][bj][m][n] = __builtin_amdgcn_mfma_f32_16x16x32_bf16(Bt[n][k], At[m][k], acc[ai][bj][m][n], 0, 0, 0); __builtin_amdgcn_s_setprio(0); } while (0)
; #define PG8_WAIT_V(n) asm volatile("s_waitcnt vmcnt(" #n ")" ::: "memory")
; #define PG8_WAIT_L(n) asm volatile("s_waitcnt lgkmcnt(" #n ")" ::: "memory")
; template <class Epi>
; __device__ __forceinline__ void gemm_phase(LAS unsigned char* lds, const Gemm g, const TileOrder& S, const Epi& E) {
;     ...
;         const bool has_next = S.next(ui + 1, nxt);
;         const char* nA = has_next ? (const char*)g.A + (size_t)nxt.pm * tstepA : cA; const char* nB = has_next ? (const char*)g.Bt + (size_t)nxt.pb * tstepB : cB;
;         for (int t = 0; t < nt; t += 2) {
;             const bool last = (t == nt - 2);
;             const char* a1 = cA + (size_t)(t + 1) * kstepA;
;             const char* a2 = last ? nA : cA + (size_t)(t + 2) * kstepA; const char* b2 = last ? nB : cB + (size_t)(t + 2) * kstep;
;             const char* a3 = a2 + kstepA; const char* b3 = b2 + kstep;
;             PG8_LDB(B0, 0, 0); PG8_LDB(B1, 0, 1); PG8_SCHED; PG8_LDA(At, 0, 0); PG8_STAGE(PG8_SA(1, 1), a1 + hstepA, voffA);
;             PG8_WAIT_V(8); PG8_WAIT_L(0); PG8_BAR; PG8_MMA(0, 0, At, B0); PG8_MMA(0, 1, At, B1); PG8_BAR; PG8_SCHED;
;             PG8_LDA(At, 0, 1); PG8_STAGE(PG8_SB(0, 0), b2, voffB); PG8_STAGE(PG8_SB(0, 1), b2 + hstepB, voffB); PG8_STAGE(PG8_SA(0, 0), a2, voffA);
.LBB0_835:
	s_mov_b32 s6, 0x10000
	s_mov_b32 s14, 0x14000
	v_add_u32_e32 v106, s6, v240
	v_add_u32_e32 v150, s14, v240
	ds_read_b128 v[74:77], v106
	ds_read_b128 v[86:89], v106 offset:1024
	ds_read_b128 v[98:101], v106 offset:2048
	ds_read_b128 v[106:109], v106 offset:3072
	ds_read_b128 v[122:125], v150
	ds_read_b128 v[126:129], v150 offset:1024
	ds_read_b128 v[142:145], v150 offset:2048
	ds_read_b128 v[150:153], v150 offset:3072
	ds_read_b128 v[154:157], v241
	ds_read_b128 v[166:169], v241 offset:1024
	ds_read_b128 v[170:173], v241 offset:2048
	ds_read_b128 v[174:177], v241 offset:3072
	ds_read_b128 v[178:181], v241 offset:4096
	ds_read_b128 v[182:185], v241 offset:5120
	ds_read_b128 v[186:189], v241 offset:6144
	ds_read_b128 v[200:203], v241 offset:7168
	s_add_u32 s2, s28, 0x4000
	s_addc_u32 s3, s29, 0
	s_cmpk_eq_i32 s72, 0x7c
	s_cselect_b32 s38, s43, s2
	s_cselect_b32 s39, s42, s3
	s_cselect_b32 s30, s51, s53
	s_cselect_b32 s31, s45, s71
	s_add_u32 s2, s38, 0x8000
	s_addc_u32 s3, s39, 0
	s_add_i32 m0, s60, 0xc000
	s_nop 0
	global_load_lds_dwordx4 v196, s[28:29]
	s_add_i32 m0, s60, 0xe000
	s_nop 0
	global_load_lds_dwordx4 v198, s[28:29]
	s_waitcnt vmcnt(8)
	s_waitcnt lgkmcnt(0)
	s_barrier
	s_setprio 1
	s_waitcnt lgkmcnt(0)
	v_mfma_f32_16x16x32_bf16 v[162:165], v[74:77], v[154:157], v[162:165]
	v_mfma_f32_16x16x32_bf16 v[158:161], v[98:101], v[154:157], v[158:161]
	v_mfma_f32_16x16x32_bf16 v[134:137], v[74:77], v[170:173], v[134:137]
	v_mfma_f32_16x16x32_bf16 v[130:133], v[98:101], v[170:173], v[130:133]
	v_mfma_f32_16x16x32_bf16 v[110:113], v[74:77], v[178:181], v[110:113]
	v_mfma_f32_16x16x32_bf16 v[102:105], v[98:101], v[178:181], v[102:105]
	v_mfma_f32_16x16x32_bf16 v[82:85], v[74:77], v[186:189], v[82:85]
	v_mfma_f32_16x16x32_bf16 v[78:81], v[98:101], v[186:189], v[78:81]
	v_mfma_f32_16x16x32_bf16 v[162:165], v[86:89], v[166:169], v[162:165]
	v_mfma_f32_16x16x32_bf16 v[158:161], v[106:109], v[166:169], v[158:161]
	v_mfma_f32_16x16x32_bf16 v[134:137], v[86:89], v[174:177], v[134:137]
	v_mfma_f32_16x16x32_bf16 v[130:133], v[106:109], v[174:177], v[130:133]
	v_mfma_f32_16x16x32_bf16 v[110:113], v[86:89], v[182:185], v[110:113]
	v_mfma_f32_16x16x32_bf16 v[102:105], v[106:109], v[182:185], v[102:105]
	v_mfma_f32_16x16x32_bf16 v[82:85], v[86:89], v[200:203], v[82:85]
	v_mfma_f32_16x16x32_bf16 v[78:81], v[106:109], v[200:203], v[78:81]
	s_setprio 0
	s_setprio 1
	v_mfma_f32_16x16x32_bf16 v[146:149], v[122:125], v[154:157], v[146:149]
	v_mfma_f32_16x16x32_bf16 v[138:141], v[142:145], v[154:157], v[138:141]
	v_mfma_f32_16x16x32_bf16 v[118:121], v[122:125], v[170:173], v[118:121]
	v_mfma_f32_16x16x32_bf16 v[114:117], v[142:145], v[170:173], v[114:117]
	v_mfma_f32_16x16x32_bf16 v[94:97], v[122:125], v[178:181], v[94:97]
	v_mfma_f32_16x16x32_bf16 v[90:93], v[142:145], v[178:181], v[90:93]
	v_mfma_f32_16x16x32_bf16 v[70:73], v[122:125], v[186:189], v[70:73]
	v_mfma_f32_16x16x32_bf16 v[66:69], v[142:145], v[186:189], v[66:69]
	v_mfma_f32_16x16x32_bf16 v[146:149], v[126:129], v[166:169], v[146:149]
	v_mfma_f32_16x16x32_bf16 v[138:141], v[150:153], v[166:169], v[138:141]
	v_mfma_f32_16x16x32_bf16 v[118:121], v[126:129], v[174:177], v[118:121]
	v_mfma_f32_16x16x32_bf16 v[114:117], v[150:153], v[174:177], v[114:117]
	v_mfma_f32_16x16x32_bf16 v[94:97], v[126:129], v[182:185], v[94:97]
	v_mfma_f32_16x16x32_bf16 v[90:93], v[150:153], v[182:185], v[90:93]
	s_setprio 2
	s_barrier
	v_mfma_f32_16x16x32_bf16 v[70:73], v[126:129], v[200:203], v[70:73]
	ds_read_b128 v[154:157], v241 offset:16384
	ds_read_b128 v[166:169], v241 offset:17408
	ds_read_b128 v[170:173], v241 offset:18432
	v_mfma_f32_16x16x32_bf16 v[66:69], v[150:153], v[200:203], v[66:69]
	s_setprio 0
	s_add_i32 s6, s6, s59
	v_lshl_add_u64 v[204:205], s[30:31], 0, v[0:1]
	s_mov_b32 m0, s6
	ds_read_b128 v[174:177], v241 offset:19456
	ds_read_b128 v[178:181], v241 offset:20480
	ds_read_b128 v[182:185], v241 offset:21504
	ds_read_b128 v[186:189], v241 offset:22528
	ds_read_b128 v[200:203], v241 offset:23552
	global_load_lds_dwordx4 v[204:205], off
	s_add_i32 m0, s6, 0x2000
	s_add_u32 s12, s30, 0x200000
	v_lshl_add_u64 v[206:207], s[30:31], 0, v[190:191]
	s_addc_u32 s13, s31, 0
	s_add_i32 s6, s14, s59
	global_load_lds_dwordx4 v[206:207], off
	s_mov_b32 m0, s6
	s_nop 0
	global_load_lds_dwordx4 v0, s[12:13]
	s_add_i32 m0, s6, 0x2000
	s_nop 0
	global_load_lds_dwordx4 v190, s[12:13]
	s_mov_b32 m0, s60
	s_nop 0
	global_load_lds_dwordx4 v194, s[38:39]
	s_mov_b32 m0, s61
	s_nop 0
	global_load_lds_dwordx4 v192, s[38:39]
	s_waitcnt vmcnt(8)
	s_waitcnt lgkmcnt(0)
	s_barrier
; #define PG8_STAGE(bufoff, gbase, voff) do { _Pragma("unroll") for (int _i = 0; _i < 2; ++_i) \
;         __builtin_amdgcn_global_load_lds((const unsigned*)((const char*)(gbase) + (voff)[_i]), (LAS unsigned*)(lds + (bufoff) + ldsw + _i * 8192), 16, 0, 0); } while (0)
; #define PG8_LDA(dst, b, h) do { _Pragma("unroll") for (int m = 0; m < 4; ++m) _Pragma("unroll") for (int k = 0; k < 2; ++k) dst[m][k] = *(const LAS bf16x8*)(lds + PG8_SA(b, h) + aoff + m * 2048 + k * 1024); } while (0)
; #define PG8_LDB(dst, b, h) do { _Pragma("unroll") for (int n = 0; n < 2; ++n) _Pragma("unroll") for (int k = 0; k < 2; ++k) dst[n][k] = *(const LAS bf16x8*)(lds + PG8_SB(b, h) + boff + n * 2048 + k * 1024); } while (0)
; #define PG8_MMA(ai, bj, At, Bt) do { __builtin_amdgcn_s_setprio(1); _Pragma("unroll") for (int m = 0; m < 4; ++m) _Pragma("unroll") for (int n = 0; n < 2; ++n) _Pragma("unroll") for (int k = 0; k < 2; ++k) \
;         acc[ai][bj][m][n] = __builtin_amdgcn_mfma_f32_16x16x32_bf16(Bt[n][k], At[m][k], acc[ai][bj][m][n], 0, 0, 0); __builtin_amdgcn_s_setprio(0); } while (0)
; #define PG8_WAIT_V(n) asm volatile("s_waitcnt vmcnt(" #n ")" ::: "memory")
; #define PG8_WAIT_L(n) asm volatile("s_waitcnt lgkmcnt(" #n ")" ::: "memory")
; #define PG8_BAR __builtin_amdgcn_s_barrier()
; #define PG8_SCHED __builtin_amdgcn_sched_barrier(0)
; template <class Epi>
; __device__ __forceinline__ void gemm_phase(LAS unsigned char* lds, const Gemm g, const TileOrder& S, const Epi& E) {
;     ...
;             PG8_WAIT_V(8); PG8_WAIT_L(0); PG8_BAR; PG8_MMA(1, 0, At, B0); PG8_MMA(1, 1, At, B1); PG8_BAR; PG8_SCHED;
;             PG8_LDB(B0, 1, 0); PG8_LDB(B1, 1, 1); PG8_SCHED; PG8_LDA(At, 1, 0); PG8_STAGE(PG8_SA(0, 1), a2 + hstepA, voffA);
;             PG8_WAIT_V(8); PG8_WAIT_L(0); PG8_BAR; PG8_MMA(0, 0, At, B0); PG8_MMA(0, 1, At, B1); PG8_BAR; PG8_SCHED;
	s_setprio 1
	s_waitcnt lgkmcnt(0)
	v_mfma_f32_16x16x32_bf16 v[62:65], v[74:77], v[154:157], v[62:65]
	v_mfma_f32_16x16x32_bf16 v[58:61], v[98:101], v[154:157], v[58:61]
	v_mfma_f32_16x16x32_bf16 v[46:49], v[74:77], v[170:173], v[46:49]
	v_mfma_f32_16x16x32_bf16 v[42:45], v[98:101], v[170:173], v[42:45]
	v_mfma_f32_16x16x32_bf16 v[30:33], v[74:77], v[178:181], v[30:33]
	v_mfma_f32_16x16x32_bf16 v[26:29], v[98:101], v[178:181], v[26:29]
	v_mfma_f32_16x16x32_bf16 v[14:17], v[74:77], v[186:189], v[14:17]
	v_mfma_f32_16x16x32_bf16 v[10:13], v[98:101], v[186:189], v[10:13]
	v_mfma_f32_16x16x32_bf16 v[62:65], v[86:89], v[166:169], v[62:65]
	v_mfma_f32_16x16x32_bf16 v[58:61], v[106:109], v[166:169], v[58:61]
	v_mfma_f32_16x16x32_bf16 v[46:49], v[86:89], v[174:177], v[46:49]
	v_mfma_f32_16x16x32_bf16 v[42:45], v[106:109], v[174:177], v[42:45]
	v_mfma_f32_16x16x32_bf16 v[30:33], v[86:89], v[182:185], v[30:33]
	v_mfma_f32_16x16x32_bf16 v[26:29], v[106:109], v[182:185], v[26:29]
	v_mfma_f32_16x16x32_bf16 v[14:17], v[86:89], v[200:203], v[14:17]
	v_mfma_f32_16x16x32_bf16 v[10:13], v[106:109], v[200:203], v[10:13]
	s_setprio 0
	s_setprio 1
	v_mfma_f32_16x16x32_bf16 v[54:57], v[122:125], v[154:157], v[54:57]
	v_mfma_f32_16x16x32_bf16 v[50:53], v[142:145], v[154:157], v[50:53]
	v_mfma_f32_16x16x32_bf16 v[38:41], v[122:125], v[170:173], v[38:41]
	v_mfma_f32_16x16x32_bf16 v[34:37], v[142:145], v[170:173], v[34:37]
	v_mfma_f32_16x16x32_bf16 v[22:25], v[122:125], v[178:181], v[22:25]
	v_mfma_f32_16x16x32_bf16 v[18:21], v[142:145], v[178:181], v[18:21]
	v_mfma_f32_16x16x32_bf16 v[6:9], v[122:125], v[186:189], v[6:9]
	v_mfma_f32_16x16x32_bf16 v[2:5], v[142:145], v[186:189], v[2:5]
	v_mfma_f32_16x16x32_bf16 v[54:57], v[126:129], v[166:169], v[54:57]
	v_mfma_f32_16x16x32_bf16 v[50:53], v[150:153], v[166:169], v[50:53]
	v_mfma_f32_16x16x32_bf16 v[38:41], v[126:129], v[174:177], v[38:41]
	v_mfma_f32_16x16x32_bf16 v[34:37], v[150:153], v[174:177], v[34:37]
	v_mfma_f32_16x16x32_bf16 v[22:25], v[126:129], v[182:185], v[22:25]
	v_mfma_f32_16x16x32_bf16 v[18:21], v[150:153], v[182:185], v[18:21]
	s_setprio 2
	s_barrier
	v_mfma_f32_16x16x32_bf16 v[6:9], v[126:129], v[200:203], v[6:9]
	s_mov_b32 s6, 0x18000
	s_mov_b32 s14, 0x1c000
	v_add_u32_e32 v106, s6, v240
	ds_read_b128 v[74:77], v106
	ds_read_b128 v[86:89], v106 offset:1024
	ds_read_b128 v[98:101], v106 offset:2048
	v_mfma_f32_16x16x32_bf16 v[2:5], v[150:153], v[200:203], v[2:5]
	s_setprio 0
	v_add_u32_e32 v150, s14, v240
	ds_read_b128 v[106:109], v106 offset:3072
	ds_read_b128 v[122:125], v150
	ds_read_b128 v[126:129], v150 offset:1024
	ds_read_b128 v[142:145], v150 offset:2048
	ds_read_b128 v[150:153], v150 offset:3072
	s_add_u32 s12, s38, 0x4000
	s_addc_u32 s13, s39, 0
	s_mov_b32 m0, s62
	ds_read_b128 v[154:157], v241 offset:32768
	ds_read_b128 v[166:169], v241 offset:33792
	ds_read_b128 v[170:173], v241 offset:34816
	ds_read_b128 v[174:177], v241 offset:35840
	ds_read_b128 v[178:181], v241 offset:36864
	ds_read_b128 v[182:185], v241 offset:37888
	ds_read_b128 v[186:189], v241 offset:38912
	ds_read_b128 v[200:203], v241 offset:39936
	global_load_lds_dwordx4 v194, s[12:13]
	s_mov_b32 m0, s63
	s_nop 0
	global_load_lds_dwordx4 v192, s[12:13]
	s_waitcnt vmcnt(8)
	s_waitcnt lgkmcnt(0)
	s_barrier
	s_setprio 1
	s_waitcnt lgkmcnt(0)
	v_mfma_f32_16x16x32_bf16 v[162:165], v[74:77], v[154:157], v[162:165]
	v_mfma_f32_16x16x32_bf16 v[158:161], v[98:101], v[154:157], v[158:161]
	v_mfma_f32_16x16x32_bf16 v[134:137], v[74:77], v[170:173], v[134:137]
	v_mfma_f32_16x16x32_bf16 v[130:133], v[98:101], v[170:173], v[130:133]
	v_mfma_f32_16x16x32_bf16 v[110:113], v[74:77], v[178:181], v[110:113]
	v_mfma_f32_16x16x32_bf16 v[102:105], v[98:101], v[178:181], v[102:105]
	v_mfma_f32_16x16x32_bf16 v[82:85], v[74:77], v[186:189], v[82:85]
	v_mfma_f32_16x16x32_bf16 v[78:81], v[98:101], v[186:189], v[78:81]
	v_mfma_f32_16x16x32_bf16 v[162:165], v[86:89], v[166:169], v[162:165]
	v_mfma_f32_16x16x32_bf16 v[158:161], v[106:109], v[166:169], v[158:161]
	v_mfma_f32_16x16x32_bf16 v[134:137], v[86:89], v[174:177], v[134:137]
	v_mfma_f32_16x16x32_bf16 v[130:133], v[106:109], v[174:177], v[130:133]
	v_mfma_f32_16x16x32_bf16 v[110:113], v[86:89], v[182:185], v[110:113]
	v_mfma_f32_16x16x32_bf16 v[102:105], v[106:109], v[182:185], v[102:105]
	v_mfma_f32_16x16x32_bf16 v[82:85], v[86:89], v[200:203], v[82:85]
	v_mfma_f32_16x16x32_bf16 v[78:81], v[106:109], v[200:203], v[78:81]
	s_setprio 0
	s_setprio 1
	v_mfma_f32_16x16x32_bf16 v[146:149], v[122:125], v[154:157], v[146:149]
	v_mfma_f32_16x16x32_bf16 v[138:141], v[142:145], v[154:157], v[138:141]
	v_mfma_f32_16x16x32_bf16 v[118:121], v[122:125], v[170:173], v[118:121]
	v_mfma_f32_16x16x32_bf16 v[114:117], v[142:145], v[170:173], v[114:117]
	v_mfma_f32_16x16x32_bf16 v[94:97], v[122:125], v[178:181], v[94:97]
	v_mfma_f32_16x16x32_bf16 v[90:93], v[142:145], v[178:181], v[90:93]
	v_mfma_f32_16x16x32_bf16 v[70:73], v[122:125], v[186:189], v[70:73]
	v_mfma_f32_16x16x32_bf16 v[66:69], v[142:145], v[186:189], v[66:69]
	v_mfma_f32_16x16x32_bf16 v[146:149], v[126:129], v[166:169], v[146:149]
	v_mfma_f32_16x16x32_bf16 v[138:141], v[150:153], v[166:169], v[138:141]
	v_mfma_f32_16x16x32_bf16 v[118:121], v[126:129], v[174:177], v[118:121]
	v_mfma_f32_16x16x32_bf16 v[114:117], v[150:153], v[174:177], v[114:117]
	v_mfma_f32_16x16x32_bf16 v[94:97], v[126:129], v[182:185], v[94:97]
	v_mfma_f32_16x16x32_bf16 v[90:93], v[150:153], v[182:185], v[90:93]
	s_setprio 2
	s_barrier
; #define PG8_STAGE(bufoff, gbase, voff) do { _Pragma("unroll") for (int _i = 0; _i < 2; ++_i) \
;         __builtin_amdgcn_global_load_lds((const unsigned*)((const char*)(gbase) + (voff)[_i]), (LAS unsigned*)(lds + (bufoff) + ldsw + _i * 8192), 16, 0, 0); } while (0)
; #define PG8_LDA(dst, b, h) do { _Pragma("unroll") for (int m = 0; m < 4; ++m) _Pragma("unroll") for (int k = 0; k < 2; ++k) dst[m][k] = *(const LAS bf16x8*)(lds + PG8_SA(b, h) + aoff + m * 2048 + k * 1024); } while (0)
; #define PG8_MMA(ai, bj, At, Bt) do { __builtin_amdgcn_s_setprio(1); _Pragma("unroll") for (int m = 0; m < 4; ++m) _Pragma("unroll") for (int n = 0; n < 2; ++n) _Pragma("unroll") for (int k = 0; k < 2; ++k) \
;         acc[ai][bj][m][n] = __builtin_amdgcn_mfma_f32_16x16x32_bf16(Bt[n][k], At[m][k], acc[ai][bj][m][n], 0, 0, 0); __builtin_amdgcn_s_setprio(0); } while (0)
; #define PG8_WAIT_V(n) asm volatile("s_waitcnt vmcnt(" #n ")" ::: "memory")
; #define PG8_WAIT_L(n) asm volatile("s_waitcnt lgkmcnt(" #n ")" ::: "memory")
; #define PG8_BAR __builtin_amdgcn_s_barrier()
; #define PG8_SCHED __builtin_amdgcn_sched_barrier(0)
; template <class Epi>
; __device__ __forceinline__ void gemm_phase(LAS unsigned char* lds, const Gemm g, const TileOrder& S, const Epi& E) {
;     ...
;             PG8_WAIT_V(8); PG8_WAIT_L(0); PG8_BAR; PG8_MMA(0, 0, At, B0); PG8_MMA(0, 1, At, B1); PG8_BAR; PG8_SCHED;
;             PG8_LDA(At, 1, 1); PG8_STAGE(PG8_SB(1, 0), b3, voffB); PG8_STAGE(PG8_SB(1, 1), b3 + hstepB, voffB); PG8_STAGE(PG8_SA(1, 0), a3, voffA);
;             PG8_WAIT_V(8); PG8_WAIT_L(0); PG8_BAR; PG8_MMA(1, 0, At, B0); PG8_MMA(1, 1, At, B1); PG8_BAR; PG8_SCHED;
;         }
;         if (wr == 0) PG8_BAR;
	v_mfma_f32_16x16x32_bf16 v[70:73], v[126:129], v[200:203], v[70:73]
	ds_read_b128 v[154:157], v241 offset:49152
	ds_read_b128 v[166:169], v241 offset:50176
	ds_read_b128 v[170:173], v241 offset:51200
	v_mfma_f32_16x16x32_bf16 v[66:69], v[150:153], v[200:203], v[66:69]
	s_setprio 0
	s_add_i32 s6, s6, s59
	v_lshl_add_u64 v[204:205], v[204:205], 0, s[34:35]
	s_mov_b32 m0, s6
	ds_read_b128 v[174:177], v241 offset:52224
	ds_read_b128 v[178:181], v241 offset:53248
	ds_read_b128 v[182:185], v241 offset:54272
	ds_read_b128 v[186:189], v241 offset:55296
	ds_read_b128 v[200:203], v241 offset:56320
	global_load_lds_dwordx4 v[204:205], off
	s_add_i32 m0, s6, 0x2000
	s_add_u32 s12, s30, 0x200080
	v_lshl_add_u64 v[204:205], v[206:207], 0, s[34:35]
	s_addc_u32 s13, s31, 0
	s_add_i32 s6, s14, s59
	global_load_lds_dwordx4 v[204:205], off
	s_mov_b32 m0, s6
	s_nop 0
	global_load_lds_dwordx4 v0, s[12:13]
	s_add_i32 m0, s6, 0x2000
	s_nop 0
	global_load_lds_dwordx4 v190, s[12:13]
	s_mov_b32 m0, s69
	s_nop 0
	global_load_lds_dwordx4 v194, s[2:3]
	s_mov_b32 m0, s70
	s_nop 0
	global_load_lds_dwordx4 v192, s[2:3]
	s_waitcnt vmcnt(8)
	s_waitcnt lgkmcnt(0)
	s_barrier
	s_setprio 1
	s_waitcnt lgkmcnt(0)
	v_mfma_f32_16x16x32_bf16 v[62:65], v[74:77], v[154:157], v[62:65]
	v_mfma_f32_16x16x32_bf16 v[58:61], v[98:101], v[154:157], v[58:61]
	v_mfma_f32_16x16x32_bf16 v[46:49], v[74:77], v[170:173], v[46:49]
	v_mfma_f32_16x16x32_bf16 v[42:45], v[98:101], v[170:173], v[42:45]
	v_mfma_f32_16x16x32_bf16 v[30:33], v[74:77], v[178:181], v[30:33]
	v_mfma_f32_16x16x32_bf16 v[26:29], v[98:101], v[178:181], v[26:29]
	v_mfma_f32_16x16x32_bf16 v[14:17], v[74:77], v[186:189], v[14:17]
	v_mfma_f32_16x16x32_bf16 v[10:13], v[98:101], v[186:189], v[10:13]
	v_mfma_f32_16x16x32_bf16 v[62:65], v[86:89], v[166:169], v[62:65]
	v_mfma_f32_16x16x32_bf16 v[58:61], v[106:109], v[166:169], v[58:61]
	v_mfma_f32_16x16x32_bf16 v[46:49], v[86:89], v[174:177], v[46:49]
	v_mfma_f32_16x16x32_bf16 v[42:45], v[106:109], v[174:177], v[42:45]
	v_mfma_f32_16x16x32_bf16 v[30:33], v[86:89], v[182:185], v[30:33]
	v_mfma_f32_16x16x32_bf16 v[26:29], v[106:109], v[182:185], v[26:29]
	v_mfma_f32_16x16x32_bf16 v[14:17], v[86:89], v[200:203], v[14:17]
	v_mfma_f32_16x16x32_bf16 v[10:13], v[106:109], v[200:203], v[10:13]
	s_setprio 0
	s_setprio 1
	v_mfma_f32_16x16x32_bf16 v[54:57], v[122:125], v[154:157], v[54:57]
	v_mfma_f32_16x16x32_bf16 v[50:53], v[142:145], v[154:157], v[50:53]
	v_mfma_f32_16x16x32_bf16 v[38:41], v[122:125], v[170:173], v[38:41]
	v_mfma_f32_16x16x32_bf16 v[34:37], v[142:145], v[170:173], v[34:37]
	v_mfma_f32_16x16x32_bf16 v[22:25], v[122:125], v[178:181], v[22:25]
	v_mfma_f32_16x16x32_bf16 v[18:21], v[142:145], v[178:181], v[18:21]
	v_mfma_f32_16x16x32_bf16 v[6:9], v[122:125], v[186:189], v[6:9]
	v_mfma_f32_16x16x32_bf16 v[2:5], v[142:145], v[186:189], v[2:5]
	v_mfma_f32_16x16x32_bf16 v[54:57], v[126:129], v[166:169], v[54:57]
	v_mfma_f32_16x16x32_bf16 v[50:53], v[150:153], v[166:169], v[50:53]
	v_mfma_f32_16x16x32_bf16 v[38:41], v[126:129], v[174:177], v[38:41]
	v_mfma_f32_16x16x32_bf16 v[34:37], v[150:153], v[174:177], v[34:37]
	v_mfma_f32_16x16x32_bf16 v[22:25], v[126:129], v[182:185], v[22:25]
	v_mfma_f32_16x16x32_bf16 v[18:21], v[150:153], v[182:185], v[18:21]
	s_setprio 2
	s_barrier
	v_mfma_f32_16x16x32_bf16 v[6:9], v[126:129], v[200:203], v[6:9]
	v_mfma_f32_16x16x32_bf16 v[2:5], v[150:153], v[200:203], v[2:5]
	s_setprio 0
	s_add_i32 s72, s72, 2
	s_add_u32 s53, s53, 0x100
	s_addc_u32 s71, s71, 0
	s_add_u32 s28, s28, 0x10000
	s_addc_u32 s29, s29, 0
	s_cmpk_gt_u32 s72, 0x7d
	s_cbranch_scc0 .LBB0_835
	s_and_b64 vcc, exec, s[46:47]
	s_cbranch_vccz .LBB0_838
	s_barrier
